# a6 + fused-LN GEMM K-loops: staging loads via scalar base (vcc) + VGPR offsets, bases from readfirstlane once per tile, invariant LDS sums hoisted
# speedup vs baseline: 1.0407x; 1.0090x over previous
; #define G_GLOAD(XR, WR, KT) { _Pragma("unroll") for (int i_ = 0; i_ < 4; ++i_) XR[i_] = *(const u32x4*)(Xt + ((size_t)(64 * i_) * ldx + (KT) * 64) * 2 + xoff); \
;     _Pragma("unroll") for (int i_ = 0; i_ < 4; ++i_) WR[i_] = *(const u32x4*)(Wtb + ((size_t)(64 * i_) * K + (KT) * 64) * 2 + woff); }
; #define G_LSTORE(XR, WR, STG) { char* xs_ = lds + (STG) * G_STAGE; char* ws_ = xs_ + G_XB; \
;     _Pragma("unroll") for (int i_ = 0; i_ < 4; ++i_) *(u32x4*)(xs_ + (lrow + 64 * i_) * LROW + lch * 16) = XR[i_]; \
;     _Pragma("unroll") for (int i_ = 0; i_ < 4; ++i_) *(u32x4*)(ws_ + (lrow + 64 * i_) * LROW + lch * 16) = WR[i_]; }
; template <class Epi>
; DI void gemm_phase(const bf16_t* __restrict__ X, const int ldx, const bf16_t* __restrict__ Wt, const int N, const int K, const Epi& epi, char* lds) {
;     ...
;     const int L = chunk * 32 + slot, band = L / (4 * nNt), rem = L % (4 * nNt);
;     const int mt_ = band * 4 + (rem & 3), nt_ = rem >> 2;
;     const char* Xt = (const char*)(X + (size_t)(mt_ * 256) * ldx);
;     const char* Wtb = (const char*)(Wt + (size_t)(nt_ * 256) * K);
;     const unsigned xoff = (unsigned)(lrow * ldx + lch * 8) * 2u, woff = (unsigned)(lrow * K + lch * 8) * 2u;
;     const bool has_next = !Epi::kFull && (chunk + 8 < nchunks);
;     const int Ln = (has_next ? chunk + 8 : chunk) * 32 + slot, band_n = Ln / (4 * nNt), rem_n = Ln % (4 * nNt);
;     const char* Xt_n = (const char*)(X + (size_t)((band_n * 4 + (rem_n & 3)) * 256) * ldx);
;     const char* Wtb_n = (const char*)(Wt + (size_t)((rem_n >> 2) * 256) * K);
;     f32x16 acc[2][2][2];
;     ...
;     asm volatile("" ::: "memory");
;     if (Epi::kFull || chunk == xcd) {
;       G_GLOAD(xr0, wr0, 0);
;       G_LSTORE(xr0, wr0, 0);
;       __syncthreads();
;       G_GLOAD(xr0, wr0, 1);
;     }
; #pragma unroll
;     for (int c = 0; c < 2; ++c)
; #pragma unroll
;       for (int a = 0; a < 2; ++a)
; #pragma unroll
;         for (int b = 0; b < 2; ++b)
; #pragma unroll
;           for (int i = 0; i < 16; ++i) acc[c][a][b][i] = 0.f;
.LBB0_268:
	s_lshl_b32 s2, s34, 5
	v_readlane_b32 s3, v254, 3
	s_add_i32 s2, s2, s3
	s_lshr_b32 s2, s2, 2
	s_and_b32 s2, s2, 0xffffffc
	s_or_b32 s2, s2, s90
	s_lshl_b32 s4, s2, 8
	s_mov_b32 s5, s97
	s_lshl_b64 s[20:21], s[4:5], 11
	s_add_u32 s20, s12, s20
	s_addc_u32 s21, s13, s21
	v_lshl_add_u64 v[178:179], s[20:21], 0, v[162:163]
	s_waitcnt vmcnt(2)
	v_add_co_u32_e32 v48, vcc, s91, v178
	s_mov_b64 s[22:23], 0x40000
	s_nop 0
	v_addc_co_u32_e32 v49, vcc, 0, v179, vcc
	v_add_co_u32_e32 v74, vcc, s1, v178
	global_load_dwordx4 v[24:27], v[178:179], off
	global_load_dwordx4 v[28:31], v[48:49], off
	v_addc_co_u32_e32 v75, vcc, 0, v179, vcc
	v_add_co_u32_e32 v76, vcc, s76, v178
	global_load_dwordx4 v[32:35], v[164:165], off
	global_load_dwordx4 v[36:39], v[198:199], off
	global_load_dwordx4 v[40:43], v[206:207], off
	global_load_dwordx4 v[44:47], v[170:171], off
	v_addc_co_u32_e32 v77, vcc, 0, v179, vcc
	global_load_dwordx4 v[66:69], v[74:75], off
	global_load_dwordx4 v[70:73], v[76:77], off
	v_mov_b32_e32 v2, 0
	v_lshl_add_u64 v[180:181], v[178:179], 0, s[22:23]
	s_mov_b64 s[22:23], 0x60000
	s_mov_b32 s21, 0
	s_movk_i32 s3, 0x100
	v_mov_b32_e32 v3, v2
	v_mov_b64_e32 v[4:5], v[2:3]
	v_mov_b64_e32 v[6:7], v[2:3]
	v_mov_b64_e32 v[8:9], v[2:3]
	v_mov_b64_e32 v[10:11], v[2:3]
	v_mov_b64_e32 v[12:13], v[2:3]
	v_mov_b64_e32 v[14:15], v[2:3]
	v_mov_b64_e32 v[16:17], v[2:3]
	s_waitcnt vmcnt(9)
	v_mov_b64_e32 v[50:51], v[2:3]
	v_mov_b64_e32 v[52:53], v[2:3]
	s_waitcnt vmcnt(8)
	v_mov_b64_e32 v[54:55], v[2:3]
	v_mov_b64_e32 v[56:57], v[2:3]
	v_mov_b64_e32 v[58:59], v[2:3]
	v_mov_b64_e32 v[60:61], v[2:3]
	v_mov_b64_e32 v[62:63], v[2:3]
	v_mov_b64_e32 v[64:65], v[2:3]
	v_mov_b64_e32 v[18:19], v[2:3]
	v_mov_b64_e32 v[20:21], v[2:3]
	v_mov_b32_e32 v22, v2
	v_lshl_add_u64 v[182:183], v[178:179], 0, s[22:23]
	v_mov_b32_e32 v23, v2
	v_mov_b64_e32 v[82:83], v[2:3]
	v_mov_b64_e32 v[84:85], v[2:3]
	v_mov_b64_e32 v[86:87], v[2:3]
	v_mov_b64_e32 v[88:89], v[2:3]
	v_mov_b64_e32 v[90:91], v[2:3]
	v_mov_b64_e32 v[92:93], v[2:3]
	v_mov_b64_e32 v[94:95], v[2:3]
	v_mov_b64_e32 v[96:97], v[2:3]
	v_mov_b64_e32 v[98:99], v[2:3]
	v_mov_b64_e32 v[100:101], v[2:3]
	v_mov_b64_e32 v[102:103], v[2:3]
	v_mov_b32_e32 v104, v2
	s_waitcnt vmcnt(5)
	ds_write_b128 v222, v[32:35] offset:36864
	s_waitcnt vmcnt(4)
	ds_write_b128 v222, v[36:39] offset:46080
	s_waitcnt vmcnt(3)
	ds_write_b128 v222, v[40:43] offset:55296
	s_waitcnt vmcnt(2)
	ds_write_b128 v222, v[44:47] offset:64512
	ds_write_b128 v222, v[24:27]
	ds_write_b128 v222, v[28:31] offset:9216
	s_waitcnt vmcnt(1)
	ds_write_b128 v222, v[66:69] offset:18432
	s_waitcnt vmcnt(0)
	ds_write_b128 v222, v[70:73] offset:27648
	s_waitcnt lgkmcnt(0)
	s_barrier
	global_load_dwordx4 v[130:133], v[174:175], off
	global_load_dwordx4 v[150:153], v[176:177], off
	global_load_dwordx4 v[158:161], v[172:173], off
	global_load_dwordx4 v[138:141], v[164:165], off offset:128
	global_load_dwordx4 v[146:149], v[76:77], off offset:128
	global_load_dwordx4 v[134:137], v[74:75], off offset:128
	global_load_dwordx4 v[154:157], v[48:49], off offset:128
	global_load_dwordx4 v[142:145], v[178:179], off offset:128
	v_mov_b64_e32 v[24:25], v[2:3]
	v_mov_b64_e32 v[26:27], v[2:3]
	v_mov_b64_e32 v[28:29], v[2:3]
	v_mov_b64_e32 v[30:31], v[2:3]
	v_mov_b64_e32 v[32:33], v[2:3]
	v_mov_b64_e32 v[34:35], v[2:3]
	v_mov_b64_e32 v[36:37], v[2:3]
	v_mov_b64_e32 v[38:39], v[2:3]
	v_mov_b64_e32 v[40:41], v[2:3]
	v_mov_b64_e32 v[42:43], v[2:3]
	v_mov_b64_e32 v[44:45], v[2:3]
	v_mov_b64_e32 v[46:47], v[2:3]
	v_mov_b64_e32 v[48:49], v[2:3]
	v_mov_b32_e32 v105, v2
	v_mov_b64_e32 v[106:107], v[2:3]
	v_mov_b64_e32 v[108:109], v[2:3]
	v_mov_b64_e32 v[110:111], v[2:3]
	v_mov_b64_e32 v[112:113], v[2:3]
	v_mov_b64_e32 v[66:67], v[2:3]
	v_mov_b64_e32 v[68:69], v[2:3]
	v_mov_b64_e32 v[70:71], v[2:3]
	v_mov_b64_e32 v[72:73], v[2:3]
	v_mov_b64_e32 v[74:75], v[2:3]
	v_mov_b64_e32 v[76:77], v[2:3]
	v_mov_b64_e32 v[78:79], v[2:3]
	v_mov_b64_e32 v[80:81], v[2:3]
	v_mov_b64_e32 v[114:115], v[2:3]
	v_mov_b64_e32 v[116:117], v[2:3]
	v_mov_b32_e32 v118, v2
	v_mov_b32_e32 v119, v2
	v_mov_b32_e32 v120, v2
	v_mov_b32_e32 v121, v2
	v_mov_b32_e32 v122, v2
	v_mov_b32_e32 v123, v2
	v_mov_b32_e32 v124, v2
	v_mov_b32_e32 v125, v2
	v_mov_b32_e32 v126, v2
	v_mov_b32_e32 v127, v2
	v_mov_b32_e32 v128, v2
	v_mov_b32_e32 v129, v2
	v_readfirstlane_b32 vcc_lo, v162
	v_readfirstlane_b32 s98, v178
	v_readfirstlane_b32 s99, v179
	v_readfirstlane_b32 s100, v164
	v_readfirstlane_b32 s101, v165
	s_nop 4
	s_sub_u32 s98, s98, vcc_lo
	s_subb_u32 s99, s99, 0
	s_sub_u32 s100, s100, vcc_lo
	s_subb_u32 s101, s101, 0
	v_add_u32_e32 v179, s91, v162
	v_add_u32_e32 v181, s1, v162
	v_add_u32_e32 v183, s76, v162
	v_add_u32_e32 v178, v191, v208
	v_add_u32_e32 v180, v191, v209
	v_add_u32_e32 v182, v210, v190
.LBB0_269:
	ds_read_b128 v[166:169], v178
	ds_read_b128 v[184:187], v178 offset:4608
	ds_read_b128 v[194:197], v180 offset:36864
	ds_read_b128 v[202:205], v180 offset:41472
	ds_read_b128 v[224:227], v180 offset:46080
	ds_read_b128 v[228:231], v180 offset:50688
	ds_read_b128 v[232:235], v212 offset:32
	ds_read_b128 v[236:239], v212 offset:4640
	s_add_i32 s5, s21, 2
	s_cmp_lt_u32 s21, 14
	s_cselect_b32 s96, s3, 0x780
	s_min_u32 s20, s21, 12
	s_lshl_b32 s20, s20, 7
	s_addk_i32 s3, 0x100
	s_cmp_gt_u32 s21, 13
	s_waitcnt lgkmcnt(5)
	v_mfma_f32_32x32x16_bf16 v[114:129], v[194:197], v[166:169], v[114:129]
	v_mfma_f32_32x32x16_bf16 v[66:81], v[194:197], v[184:187], v[66:81]
	s_waitcnt lgkmcnt(4)
	v_mfma_f32_32x32x16_bf16 v[98:113], v[202:205], v[166:169], v[98:113]
	v_mfma_f32_32x32x16_bf16 v[34:49], v[202:205], v[184:187], v[34:49]
	s_waitcnt lgkmcnt(3)
	v_mfma_f32_32x32x16_bf16 v[82:97], v[224:227], v[166:169], v[82:97]
	v_mfma_f32_32x32x16_bf16 v[18:33], v[224:227], v[184:187], v[18:33]
	s_waitcnt lgkmcnt(2)
	v_mfma_f32_32x32x16_bf16 v[50:65], v[228:231], v[166:169], v[50:65]
	ds_read_b128 v[166:169], v213 offset:36896
	ds_read_b128 v[194:197], v213 offset:41504
	v_mfma_f32_32x32x16_bf16 v[2:17], v[228:231], v[184:187], v[2:17]
	s_waitcnt vmcnt(1)
	ds_write_b128 v214, v[154:157] offset:9216
	s_waitcnt vmcnt(0)
	ds_write_b128 v214, v[142:145]
	s_add_u32 vcc_lo, s98, s96
	s_addc_u32 vcc_hi, s99, 0
	global_load_dwordx4 v[142:145], v162, vcc
	global_load_dwordx4 v[154:157], v179, vcc
	ds_write_b128 v214, v[134:137] offset:18432
	ds_write_b128 v214, v[146:149] offset:27648
	global_load_dwordx4 v[134:137], v181, vcc
	global_load_dwordx4 v[146:149], v183, vcc
	ds_read_b128 v[184:187], v213 offset:46112
	ds_read_b128 v[202:205], v213 offset:50720
	ds_read_b128 v[224:227], v212 offset:64
	ds_read_b128 v[228:231], v212 offset:4672
	s_waitcnt lgkmcnt(9)
	v_mfma_f32_32x32x16_bf16 v[114:129], v[166:169], v[232:235], v[114:129]
	v_mfma_f32_32x32x16_bf16 v[66:81], v[166:169], v[236:239], v[66:81]
	s_waitcnt lgkmcnt(8)
	v_mfma_f32_32x32x16_bf16 v[98:113], v[194:197], v[232:235], v[98:113]
	v_mfma_f32_32x32x16_bf16 v[34:49], v[194:197], v[236:239], v[34:49]
	s_waitcnt lgkmcnt(3)
	v_mfma_f32_32x32x16_bf16 v[82:97], v[184:187], v[232:235], v[82:97]
	v_mfma_f32_32x32x16_bf16 v[18:33], v[184:187], v[236:239], v[18:33]
	ds_read_b128 v[166:169], v213 offset:36928
	ds_read_b128 v[184:187], v213 offset:41536
	s_waitcnt lgkmcnt(4)
	v_mfma_f32_32x32x16_bf16 v[50:65], v[202:205], v[232:235], v[50:65]
	v_mfma_f32_32x32x16_bf16 v[2:17], v[202:205], v[236:239], v[2:17]
	ds_write_b128 v215, v[150:153] offset:9216
	ds_write_b128 v215, v[138:141]
	s_add_u32 vcc_lo, s100, s96
	s_addc_u32 vcc_hi, s101, 0
	global_load_dwordx4 v[138:141], v162, vcc
	global_load_dwordx4 v[150:153], v179, vcc
	ds_read_b128 v[194:197], v213 offset:46144
	ds_read_b128 v[202:205], v213 offset:50752
	ds_read_b128 v[232:235], v212 offset:96
	ds_read_b128 v[236:239], v212 offset:4704
	s_waitcnt lgkmcnt(7)
	v_mfma_f32_32x32x16_bf16 v[114:129], v[166:169], v[224:227], v[114:129]
	v_mfma_f32_32x32x16_bf16 v[66:81], v[166:169], v[228:231], v[66:81]
	s_waitcnt lgkmcnt(6)
	v_mfma_f32_32x32x16_bf16 v[98:113], v[184:187], v[224:227], v[98:113]
	v_mfma_f32_32x32x16_bf16 v[34:49], v[184:187], v[228:231], v[34:49]
	s_waitcnt lgkmcnt(3)
	v_mfma_f32_32x32x16_bf16 v[82:97], v[194:197], v[224:227], v[82:97]
	ds_read_b128 v[166:169], v213 offset:36960
	ds_read_b128 v[184:187], v213 offset:41568
	v_mfma_f32_32x32x16_bf16 v[18:33], v[194:197], v[228:231], v[18:33]
	s_waitcnt lgkmcnt(4)
	v_mfma_f32_32x32x16_bf16 v[50:65], v[202:205], v[224:227], v[50:65]
	v_mfma_f32_32x32x16_bf16 v[2:17], v[202:205], v[228:231], v[2:17]
	ds_write_b128 v215, v[130:133] offset:18432
	ds_write_b128 v215, v[158:161] offset:27648
	global_load_dwordx4 v[130:133], v181, vcc
	global_load_dwordx4 v[158:161], v183, vcc
	ds_read_b128 v[194:197], v213 offset:46176
	ds_read_b128 v[202:205], v213 offset:50784
	s_waitcnt lgkmcnt(5)
	v_mfma_f32_32x32x16_bf16 v[114:129], v[166:169], v[232:235], v[114:129]
	v_mfma_f32_32x32x16_bf16 v[66:81], v[166:169], v[236:239], v[66:81]
	s_waitcnt lgkmcnt(4)
	v_mfma_f32_32x32x16_bf16 v[98:113], v[184:187], v[232:235], v[98:113]
	v_mfma_f32_32x32x16_bf16 v[34:49], v[184:187], v[236:239], v[34:49]
	s_waitcnt lgkmcnt(1)
	v_mfma_f32_32x32x16_bf16 v[82:97], v[194:197], v[232:235], v[82:97]
	v_mfma_f32_32x32x16_bf16 v[18:33], v[194:197], v[236:239], v[18:33]
	s_waitcnt lgkmcnt(0)
	v_mfma_f32_32x32x16_bf16 v[50:65], v[202:205], v[232:235], v[50:65]
	v_mfma_f32_32x32x16_bf16 v[2:17], v[202:205], v[236:239], v[2:17]
	s_barrier
	ds_read_b128 v[166:169], v216
	ds_read_b128 v[184:187], v216 offset:4608
	ds_read_b128 v[194:197], v217
	ds_read_b128 v[202:205], v217 offset:4608
	ds_read_b128 v[224:227], v217 offset:9216
	ds_read_b128 v[228:231], v217 offset:13824
	ds_read_b128 v[232:235], v182 offset:32
	ds_read_b128 v[236:239], v218 offset:32
	s_waitcnt lgkmcnt(5)
	v_mfma_f32_32x32x16_bf16 v[114:129], v[194:197], v[166:169], v[114:129]
	v_mfma_f32_32x32x16_bf16 v[66:81], v[194:197], v[184:187], v[66:81]
	s_waitcnt lgkmcnt(4)
	v_mfma_f32_32x32x16_bf16 v[98:113], v[202:205], v[166:169], v[98:113]
	v_mfma_f32_32x32x16_bf16 v[34:49], v[202:205], v[184:187], v[34:49]
	s_waitcnt lgkmcnt(3)
	v_mfma_f32_32x32x16_bf16 v[82:97], v[224:227], v[166:169], v[82:97]
	v_add_u32_e32 v223, v211, v190
	v_mfma_f32_32x32x16_bf16 v[18:33], v[224:227], v[184:187], v[18:33]
	s_waitcnt lgkmcnt(2)
	v_mfma_f32_32x32x16_bf16 v[50:65], v[228:231], v[166:169], v[50:65]
	ds_read_b128 v[166:169], v223 offset:32
	ds_read_b128 v[194:197], v219 offset:32
	v_mfma_f32_32x32x16_bf16 v[2:17], v[228:231], v[184:187], v[2:17]
	s_mov_b32 s21, s97
	s_waitcnt vmcnt(6)
	ds_write_b128 v222, v[154:157] offset:9216
	ds_write_b128 v222, v[142:145]
	s_add_u32 vcc_lo, s98, s20
	s_addc_u32 vcc_hi, s99, 0
	global_load_dwordx4 v[142:145], v162, vcc offset:384
	global_load_dwordx4 v[154:157], v179, vcc offset:384
	s_waitcnt vmcnt(7)
	ds_write_b128 v222, v[134:137] offset:18432
	s_waitcnt vmcnt(6)
	ds_write_b128 v222, v[146:149] offset:27648
	global_load_dwordx4 v[134:137], v181, vcc offset:384
	global_load_dwordx4 v[146:149], v183, vcc offset:384
	ds_read_b128 v[184:187], v220 offset:32
	ds_read_b128 v[202:205], v221 offset:32
	ds_read_b128 v[224:227], v182 offset:64
	ds_read_b128 v[228:231], v218 offset:64
	s_waitcnt lgkmcnt(9)
	v_mfma_f32_32x32x16_bf16 v[114:129], v[166:169], v[232:235], v[114:129]
	v_mfma_f32_32x32x16_bf16 v[66:81], v[166:169], v[236:239], v[66:81]
	s_waitcnt lgkmcnt(8)
	v_mfma_f32_32x32x16_bf16 v[98:113], v[194:197], v[232:235], v[98:113]
	v_mfma_f32_32x32x16_bf16 v[34:49], v[194:197], v[236:239], v[34:49]
	s_waitcnt lgkmcnt(3)
	v_mfma_f32_32x32x16_bf16 v[82:97], v[184:187], v[232:235], v[82:97]
	v_mfma_f32_32x32x16_bf16 v[18:33], v[184:187], v[236:239], v[18:33]
	ds_read_b128 v[166:169], v223 offset:64
	ds_read_b128 v[184:187], v219 offset:64
	s_waitcnt lgkmcnt(4)
	v_mfma_f32_32x32x16_bf16 v[50:65], v[202:205], v[232:235], v[50:65]
	v_mfma_f32_32x32x16_bf16 v[2:17], v[202:205], v[236:239], v[2:17]
	s_waitcnt vmcnt(6)
	ds_write_b128 v222, v[150:153] offset:46080
	ds_write_b128 v222, v[138:141] offset:36864
	s_add_u32 vcc_lo, s100, s20
	s_addc_u32 vcc_hi, s101, 0
	global_load_dwordx4 v[138:141], v162, vcc offset:384
	global_load_dwordx4 v[150:153], v179, vcc offset:384
	ds_read_b128 v[194:197], v220 offset:64
	ds_read_b128 v[202:205], v221 offset:64
	ds_read_b128 v[232:235], v182 offset:96
	ds_read_b128 v[236:239], v218 offset:96
	s_waitcnt lgkmcnt(7)
	v_mfma_f32_32x32x16_bf16 v[114:129], v[166:169], v[224:227], v[114:129]
	v_mfma_f32_32x32x16_bf16 v[66:81], v[166:169], v[228:231], v[66:81]
	s_waitcnt lgkmcnt(6)
	v_mfma_f32_32x32x16_bf16 v[98:113], v[184:187], v[224:227], v[98:113]
	v_mfma_f32_32x32x16_bf16 v[34:49], v[184:187], v[228:231], v[34:49]
	s_waitcnt lgkmcnt(3)
	v_mfma_f32_32x32x16_bf16 v[82:97], v[194:197], v[224:227], v[82:97]
	ds_read_b128 v[166:169], v223 offset:96
	ds_read_b128 v[184:187], v219 offset:96
	v_mfma_f32_32x32x16_bf16 v[18:33], v[194:197], v[228:231], v[18:33]
	s_waitcnt lgkmcnt(4)
	v_mfma_f32_32x32x16_bf16 v[50:65], v[202:205], v[224:227], v[50:65]
	v_mfma_f32_32x32x16_bf16 v[2:17], v[202:205], v[228:231], v[2:17]
	s_waitcnt vmcnt(7)
	ds_write_b128 v222, v[130:133] offset:55296
	s_waitcnt vmcnt(6)
	ds_write_b128 v222, v[158:161] offset:64512
	global_load_dwordx4 v[130:133], v181, vcc offset:384
	global_load_dwordx4 v[158:161], v183, vcc offset:384
	ds_read_b128 v[194:197], v220 offset:96
	ds_read_b128 v[202:205], v221 offset:96
	s_waitcnt lgkmcnt(5)
	v_mfma_f32_32x32x16_bf16 v[114:129], v[166:169], v[232:235], v[114:129]
	v_mfma_f32_32x32x16_bf16 v[66:81], v[166:169], v[236:239], v[66:81]
	s_waitcnt lgkmcnt(4)
	v_mfma_f32_32x32x16_bf16 v[98:113], v[184:187], v[232:235], v[98:113]
	v_mfma_f32_32x32x16_bf16 v[34:49], v[184:187], v[236:239], v[34:49]
	s_waitcnt lgkmcnt(1)
	v_mfma_f32_32x32x16_bf16 v[82:97], v[194:197], v[232:235], v[82:97]
	v_mfma_f32_32x32x16_bf16 v[18:33], v[194:197], v[236:239], v[18:33]
	s_waitcnt lgkmcnt(0)
	v_mfma_f32_32x32x16_bf16 v[50:65], v[202:205], v[232:235], v[50:65]
	v_mfma_f32_32x32x16_bf16 v[2:17], v[202:205], v[236:239], v[2:17]
	s_mov_b32 s21, s5
	s_cmp_gt_u32 s21, 15
	s_barrier
	s_cbranch_scc0 .LBB0_269
; #define RL_LOAD(XV, G) { constexpr int mt__ = (G) >> 2, half__ = ((G) >> 1) & 1, nt__ = (G) & 1; \
;     _Pragma("unroll") for (int gq = 0; gq < 4; ++gq) XV[gq] = *(const f32x4*)(xin + rbase + (size_t)mt__ * 32 * 1024 + half__ * 64 + nt__ * 32 + 4 * gq); }
; #define RL_FOLD(XV, G, SM, SQ) { constexpr int mt__ = (G) >> 2, half__ = ((G) >> 1) & 1, nt__ = (G) & 1; \
;     _Pragma("unroll") for (int gq = 0; gq < 4; ++gq) _Pragma("unroll") for (int jj = 0; jj < 4; ++jj) { \
;       const float y = ALPHA * XV[gq][jj] + acc[half__][nt__][mt__][4 * gq + jj]; acc[half__][nt__][mt__][4 * gq + jj] = y; SM += y; SQ += y * y; } }
; #define SB __builtin_amdgcn_sched_barrier(0)
;   DI void full(const int mt_, const int nt_, f32x16 (&acc)[2][2][2], const int tw, const int fw, const int r, const int hh, char* lds, const int tid) const {
;     float* part = (float*)(lds + G_STAGE);
;     const size_t rbase = (size_t)(mt_ * 256 + tw * 64 + r) * 1024 + nt_ * 256 + fw * 128 + 16 * hh;
;     f32x4 xa[4], xc[4], xe[4];
;     ...
;     float sm0 = 0.f, sq0 = 0.f, sm1 = 0.f, sq1 = 0.f;
;     RL_LOAD(xa, 0); RL_LOAD(xc, 1); RL_LOAD(xe, 2); SB;
;     RL_FOLD(xa, 0, sm0, sq0); SB; RL_LOAD(xa, 3); SB;
;     RL_FOLD(xc, 1, sm0, sq0); SB; RL_LOAD(xc, 4); SB;
;     RL_FOLD(xe, 2, sm0, sq0); SB; RL_LOAD(xe, 5); SB;
;     RL_FOLD(xa, 3, sm0, sq0); SB; RL_LOAD(xa, 6); SB;
	v_mov_b32_e32 v184, v192
	s_waitcnt vmcnt(1)
	v_ashrrev_i32_e32 v130, 1, v184
	v_and_b32_e32 v223, 0xdf, v184
	v_and_b32_e32 v182, 0xffffff80, v130
	v_or_b32_e32 v0, s4, v223
	v_ashrrev_i32_e32 v183, 31, v182
	v_bfe_u32 v224, v184, 5, 1
	v_lshl_add_u64 v[130:131], v[182:183], 2, s[18:19]
	v_lshlrev_b64 v[132:133], 12, v[0:1]
	v_lshl_add_u64 v[130:131], v[130:131], 0, v[132:133]
	v_lshlrev_b32_e32 v132, 6, v224
	v_mov_b32_e32 v133, v1
	v_lshl_add_u64 v[186:187], v[130:131], 0, v[132:133]
	global_load_dwordx4 v[130:133], v[186:187], off offset:48
	global_load_dwordx4 v[134:137], v[186:187], off offset:32
	global_load_dwordx4 v[138:141], v[186:187], off offset:16
	global_load_dwordx4 v[142:145], v[186:187], off
	global_load_dwordx4 v[194:197], v[186:187], off offset:176
	global_load_dwordx4 v[202:205], v[186:187], off offset:160
	global_load_dwordx4 v[226:229], v[186:187], off offset:144
	global_load_dwordx4 v[146:149], v[186:187], off offset:128
	global_load_dwordx4 v[230:233], v[186:187], off offset:304
	global_load_dwordx4 v[234:237], v[186:187], off offset:288
	global_load_dwordx4 v[238:241], v[186:187], off offset:272
	global_load_dwordx4 v[242:245], v[186:187], off offset:256
	s_waitcnt vmcnt(8)
	v_pk_fma_f32 v[178:179], v[142:143], s[0:1], v[114:115] op_sel_hi:[1,0,1]
	v_pk_fma_f32 v[180:181], v[144:145], s[0:1], v[116:117] op_sel_hi:[1,0,1]
	v_add_f32_e32 v114, 0, v178
	v_add_f32_e32 v142, v179, v114
	v_mul_f32_e32 v114, v179, v179
	v_pk_fma_f32 v[114:115], v[178:179], v[178:179], v[114:115] op_sel_hi:[1,1,0]
	v_add_f32_e32 v116, v180, v142
	v_pk_fma_f32 v[114:115], v[180:181], v[180:181], v[114:115]
	v_add_f32_e32 v117, v181, v116
	v_mul_f32_e32 v116, v181, v181
	v_pk_fma_f32 v[158:159], v[138:139], s[0:1], v[118:119] op_sel_hi:[1,0,1]
	v_pk_add_f32 v[114:115], v[116:117], v[114:115] op_sel_hi:[0,1]
	v_add_f32_e32 v116, v158, v117
	v_pk_fma_f32 v[114:115], v[158:159], v[158:159], v[114:115]
	v_add_f32_e32 v117, v159, v116
	v_mul_f32_e32 v116, v159, v159
	v_pk_fma_f32 v[160:161], v[140:141], s[0:1], v[120:121] op_sel_hi:[1,0,1]
	v_pk_add_f32 v[114:115], v[116:117], v[114:115] op_sel_hi:[0,1]
	v_add_f32_e32 v116, v160, v117
	v_pk_fma_f32 v[114:115], v[160:161], v[160:161], v[114:115]
	v_add_f32_e32 v117, v161, v116
	v_mul_f32_e32 v116, v161, v161
	v_pk_fma_f32 v[154:155], v[134:135], s[0:1], v[122:123] op_sel_hi:[1,0,1]
	v_pk_add_f32 v[114:115], v[116:117], v[114:115] op_sel_hi:[0,1]
	v_add_f32_e32 v116, v154, v117
	v_pk_fma_f32 v[114:115], v[154:155], v[154:155], v[114:115]
	v_add_f32_e32 v117, v155, v116
	v_mul_f32_e32 v116, v155, v155
	v_pk_fma_f32 v[156:157], v[136:137], s[0:1], v[124:125] op_sel_hi:[1,0,1]
	v_pk_add_f32 v[114:115], v[116:117], v[114:115] op_sel_hi:[0,1]
	v_add_f32_e32 v116, v156, v117
	v_pk_fma_f32 v[114:115], v[156:157], v[156:157], v[114:115]
	v_add_f32_e32 v124, v157, v116
	v_mul_f32_e32 v116, v157, v157
	v_pk_add_f32 v[114:115], v[116:117], v[114:115] op_sel_hi:[0,1]
	v_pk_fma_f32 v[152:153], v[130:131], s[0:1], v[126:127] op_sel_hi:[1,0,1]
	v_pk_fma_f32 v[150:151], v[132:133], s[0:1], v[128:129] op_sel_hi:[1,0,1]
	v_pk_fma_f32 v[114:115], v[152:153], v[152:153], v[114:115]
	v_mul_f32_e32 v116, v153, v153
	v_pk_add_f32 v[114:115], v[116:117], v[114:115] op_sel_hi:[0,1]
	v_pk_fma_f32 v[114:115], v[150:151], v[150:151], v[114:115]
	v_mul_f32_e32 v116, v151, v151
	v_pk_add_f32 v[118:119], v[116:117], v[114:115] op_sel_hi:[0,1]
	global_load_dwordx4 v[114:117], v[186:187], off offset:432
	global_load_dwordx4 v[246:249], v[186:187], off offset:416
	global_load_dwordx4 v[250:253], v[186:187], off offset:400
	global_load_dwordx4 v[120:123], v[186:187], off offset:384
	v_add_f32_e32 v124, v152, v124
	v_add_f32_e32 v124, v153, v124
	v_add_f32_e32 v124, v150, v124
	v_add_f32_e32 v124, v151, v124
	s_waitcnt vmcnt(8)
	v_pk_fma_f32 v[144:145], v[146:147], s[0:1], v[98:99] op_sel_hi:[1,0,1]
	v_pk_fma_f32 v[148:149], v[148:149], s[0:1], v[100:101] op_sel_hi:[1,0,1]
	v_add_f32_e32 v124, v144, v124
	v_pk_fma_f32 v[98:99], v[144:145], v[144:145], v[118:119]
	v_add_f32_e32 v119, v145, v124
	v_mul_f32_e32 v118, v145, v145
	v_pk_add_f32 v[98:99], v[118:119], v[98:99] op_sel_hi:[0,1]
	v_add_f32_e32 v100, v148, v119
	v_pk_fma_f32 v[98:99], v[148:149], v[148:149], v[98:99]
	v_add_f32_e32 v101, v149, v100
	v_mul_f32_e32 v100, v149, v149
	v_pk_fma_f32 v[138:139], v[226:227], s[0:1], v[102:103] op_sel_hi:[1,0,1]
	v_pk_add_f32 v[98:99], v[100:101], v[98:99] op_sel_hi:[0,1]
	v_add_f32_e32 v100, v138, v101
	v_pk_fma_f32 v[98:99], v[138:139], v[138:139], v[98:99]
	v_add_f32_e32 v101, v139, v100
	v_mul_f32_e32 v100, v139, v139
	v_pk_fma_f32 v[146:147], v[228:229], s[0:1], v[104:105] op_sel_hi:[1,0,1]
	v_pk_add_f32 v[98:99], v[100:101], v[98:99] op_sel_hi:[0,1]
	v_add_f32_e32 v100, v146, v101
	v_pk_fma_f32 v[98:99], v[146:147], v[146:147], v[98:99]
	v_add_f32_e32 v101, v147, v100
	v_mul_f32_e32 v100, v147, v147
	v_pk_fma_f32 v[130:131], v[202:203], s[0:1], v[106:107] op_sel_hi:[1,0,1]
	v_pk_add_f32 v[98:99], v[100:101], v[98:99] op_sel_hi:[0,1]
	v_add_f32_e32 v100, v130, v101
	v_pk_fma_f32 v[98:99], v[130:131], v[130:131], v[98:99]
	v_add_f32_e32 v101, v131, v100
	v_mul_f32_e32 v100, v131, v131
	v_pk_fma_f32 v[140:141], v[204:205], s[0:1], v[108:109] op_sel_hi:[1,0,1]
	v_pk_add_f32 v[98:99], v[100:101], v[98:99] op_sel_hi:[0,1]
	v_add_f32_e32 v100, v140, v101
	v_pk_fma_f32 v[98:99], v[140:141], v[140:141], v[98:99]
	v_add_f32_e32 v106, v141, v100
	v_mul_f32_e32 v100, v141, v141
	v_pk_add_f32 v[102:103], v[100:101], v[98:99] op_sel_hi:[0,1]
	v_pk_fma_f32 v[124:125], v[194:195], s[0:1], v[110:111] op_sel_hi:[1,0,1]
	v_pk_fma_f32 v[134:135], v[196:197], s[0:1], v[112:113] op_sel_hi:[1,0,1]
	v_add_co_u32_e32 v188, vcc, s91, v186
	s_mov_b64 s[20:21], 0x20000
	s_nop 0
	v_addc_co_u32_e32 v189, vcc, 0, v187, vcc
	v_lshl_add_u64 v[104:105], v[186:187], 0, s[20:21]
	global_load_dwordx4 v[194:197], v[188:189], off
	global_load_dwordx4 v[98:101], v[104:105], off offset:48
	global_load_dwordx4 v[202:205], v[104:105], off offset:32
	global_load_dwordx4 v[226:229], v[104:105], off offset:16
	v_add_f32_e32 v104, v124, v106
	v_pk_fma_f32 v[102:103], v[124:125], v[124:125], v[102:103]
	v_add_f32_e32 v105, v125, v104
	v_mul_f32_e32 v104, v125, v125
	v_pk_add_f32 v[102:103], v[104:105], v[102:103] op_sel_hi:[0,1]
	v_add_f32_e32 v104, v134, v105
	v_pk_fma_f32 v[102:103], v[134:135], v[134:135], v[102:103]
	v_add_f32_e32 v105, v135, v104
	v_mul_f32_e32 v104, v135, v135
	v_pk_add_f32 v[102:103], v[104:105], v[102:103] op_sel_hi:[0,1]
	s_waitcnt vmcnt(8)
; #define RL_LOAD(XV, G) { constexpr int mt__ = (G) >> 2, half__ = ((G) >> 1) & 1, nt__ = (G) & 1; \
;     _Pragma("unroll") for (int gq = 0; gq < 4; ++gq) XV[gq] = *(const f32x4*)(xin + rbase + (size_t)mt__ * 32 * 1024 + half__ * 64 + nt__ * 32 + 4 * gq); }
; #define RL_FOLD(XV, G, SM, SQ) { constexpr int mt__ = (G) >> 2, half__ = ((G) >> 1) & 1, nt__ = (G) & 1; \
;     _Pragma("unroll") for (int gq = 0; gq < 4; ++gq) _Pragma("unroll") for (int jj = 0; jj < 4; ++jj) { \
;       const float y = ALPHA * XV[gq][jj] + acc[half__][nt__][mt__][4 * gq + jj]; acc[half__][nt__][mt__][4 * gq + jj] = y; SM += y; SQ += y * y; } }
; #define SB __builtin_amdgcn_sched_barrier(0)
;   DI void full(const int mt_, const int nt_, f32x16 (&acc)[2][2][2], const int tw, const int fw, const int r, const int hh, char* lds, const int tid) const {
;     ...
;     RL_LOAD(xa, 0); RL_LOAD(xc, 1); RL_LOAD(xe, 2); SB;
;     RL_FOLD(xa, 0, sm0, sq0); SB; RL_LOAD(xa, 3); SB;
;     RL_FOLD(xc, 1, sm0, sq0); SB; RL_LOAD(xc, 4); SB;
;     RL_FOLD(xe, 2, sm0, sq0); SB; RL_LOAD(xe, 5); SB;
;     RL_FOLD(xa, 3, sm0, sq0); SB; RL_LOAD(xa, 6); SB;
;     RL_FOLD(xc, 4, sm1, sq1); SB; RL_LOAD(xc, 7); SB;
;     RL_FOLD(xe, 5, sm1, sq1); SB;
;     RL_FOLD(xa, 6, sm1, sq1); SB;
;     RL_FOLD(xc, 7, sm1, sq1);
	v_pk_fma_f32 v[132:133], v[242:243], s[0:1], v[82:83] op_sel_hi:[1,0,1]
	v_pk_fma_f32 v[142:143], v[244:245], s[0:1], v[84:85] op_sel_hi:[1,0,1]
	v_add_f32_e32 v104, v132, v105
	v_pk_fma_f32 v[82:83], v[132:133], v[132:133], v[102:103]
	v_add_f32_e32 v103, v133, v104
	v_mul_f32_e32 v102, v133, v133
	v_pk_add_f32 v[82:83], v[102:103], v[82:83] op_sel_hi:[0,1]
	v_add_f32_e32 v84, v142, v103
	v_pk_fma_f32 v[82:83], v[142:143], v[142:143], v[82:83]
	v_add_f32_e32 v85, v143, v84
	v_mul_f32_e32 v84, v143, v143
	v_pk_fma_f32 v[126:127], v[238:239], s[0:1], v[86:87] op_sel_hi:[1,0,1]
	v_pk_add_f32 v[82:83], v[84:85], v[82:83] op_sel_hi:[0,1]
	v_add_f32_e32 v84, v126, v85
	v_pk_fma_f32 v[82:83], v[126:127], v[126:127], v[82:83]
	v_add_f32_e32 v85, v127, v84
	v_mul_f32_e32 v84, v127, v127
	v_pk_fma_f32 v[136:137], v[240:241], s[0:1], v[88:89] op_sel_hi:[1,0,1]
	v_pk_add_f32 v[82:83], v[84:85], v[82:83] op_sel_hi:[0,1]
	v_add_f32_e32 v84, v136, v85
	v_pk_fma_f32 v[82:83], v[136:137], v[136:137], v[82:83]
	v_add_f32_e32 v85, v137, v84
	v_mul_f32_e32 v84, v137, v137
	v_pk_fma_f32 v[112:113], v[234:235], s[0:1], v[90:91] op_sel_hi:[1,0,1]
	v_pk_add_f32 v[82:83], v[84:85], v[82:83] op_sel_hi:[0,1]
	v_add_f32_e32 v84, v112, v85
	v_pk_fma_f32 v[82:83], v[112:113], v[112:113], v[82:83]
	v_add_f32_e32 v85, v113, v84
	v_mul_f32_e32 v84, v113, v113
	v_pk_fma_f32 v[128:129], v[236:237], s[0:1], v[92:93] op_sel_hi:[1,0,1]
	v_pk_add_f32 v[82:83], v[84:85], v[82:83] op_sel_hi:[0,1]
	v_add_f32_e32 v84, v128, v85
	v_pk_fma_f32 v[82:83], v[128:129], v[128:129], v[82:83]
	v_add_f32_e32 v90, v129, v84
	v_mul_f32_e32 v84, v129, v129
	v_pk_add_f32 v[86:87], v[84:85], v[82:83] op_sel_hi:[0,1]
	v_pk_fma_f32 v[106:107], v[230:231], s[0:1], v[94:95] op_sel_hi:[1,0,1]
	v_pk_fma_f32 v[118:119], v[232:233], s[0:1], v[96:97] op_sel_hi:[1,0,1]
	s_mov_b64 s[20:21], 0x20080
	v_lshl_add_u64 v[88:89], v[186:187], 0, s[20:21]
	global_load_dwordx4 v[82:85], v[88:89], off offset:48
	global_load_dwordx4 v[230:233], v[88:89], off offset:32
	global_load_dwordx4 v[234:237], v[188:189], off offset:128
	global_load_dwordx4 v[238:241], v[88:89], off offset:16
	v_add_f32_e32 v88, v106, v90
	v_pk_fma_f32 v[86:87], v[106:107], v[106:107], v[86:87]
	v_add_f32_e32 v89, v107, v88
	v_mul_f32_e32 v88, v107, v107
	v_pk_add_f32 v[86:87], v[88:89], v[86:87] op_sel_hi:[0,1]
	v_add_f32_e32 v88, v118, v89
	v_pk_fma_f32 v[86:87], v[118:119], v[118:119], v[86:87]
	v_add_f32_e32 v89, v119, v88
	v_mul_f32_e32 v88, v119, v119
	v_pk_add_f32 v[86:87], v[88:89], v[86:87] op_sel_hi:[0,1]
	s_waitcnt vmcnt(8)
	v_pk_fma_f32 v[104:105], v[120:121], s[0:1], v[50:51] op_sel_hi:[1,0,1]
	v_pk_fma_f32 v[122:123], v[122:123], s[0:1], v[52:53] op_sel_hi:[1,0,1]
	v_add_f32_e32 v88, v104, v89
	v_pk_fma_f32 v[50:51], v[104:105], v[104:105], v[86:87]
	v_add_f32_e32 v87, v105, v88
	v_mul_f32_e32 v86, v105, v105
	v_add_f32_e32 v52, v122, v87
	v_pk_add_f32 v[50:51], v[86:87], v[50:51] op_sel_hi:[0,1]
	v_add_f32_e32 v52, v123, v52
	v_pk_fma_f32 v[102:103], v[250:251], s[0:1], v[54:55] op_sel_hi:[1,0,1]
	v_pk_fma_f32 v[50:51], v[122:123], v[122:123], v[50:51]
	v_add_f32_e32 v55, v102, v52
	v_mul_f32_e32 v54, v123, v123
	v_mov_b32_e32 v52, v102
	v_mov_b32_e32 v53, v123
	v_pk_add_f32 v[50:51], v[54:55], v[50:51] op_sel_hi:[0,1]
	v_pk_fma_f32 v[50:51], v[52:53], v[52:53], v[50:51]
	v_add_f32_e32 v52, v103, v55
	v_pk_fma_f32 v[120:121], v[252:253], s[0:1], v[56:57] op_sel_hi:[1,0,1]
	v_mul_f32_e32 v54, v103, v103
	v_add_f32_e32 v55, v120, v52
	v_mov_b32_e32 v52, v120
	v_mov_b32_e32 v53, v103
	v_pk_add_f32 v[50:51], v[54:55], v[50:51] op_sel_hi:[0,1]
	v_pk_fma_f32 v[50:51], v[52:53], v[52:53], v[50:51]
	v_add_f32_e32 v52, v121, v55
	v_pk_fma_f32 v[94:95], v[246:247], s[0:1], v[58:59] op_sel_hi:[1,0,1]
	v_mul_f32_e32 v54, v121, v121
	v_add_f32_e32 v55, v94, v52
	v_mov_b32_e32 v52, v94
	v_mov_b32_e32 v53, v121
	v_pk_add_f32 v[50:51], v[54:55], v[50:51] op_sel_hi:[0,1]
	v_pk_fma_f32 v[50:51], v[52:53], v[52:53], v[50:51]
	v_add_f32_e32 v52, v95, v55
	v_pk_fma_f32 v[108:109], v[248:249], s[0:1], v[60:61] op_sel_hi:[1,0,1]
	v_mul_f32_e32 v54, v95, v95
	v_add_f32_e32 v55, v108, v52
	v_mov_b32_e32 v52, v108
	v_mov_b32_e32 v53, v95
	v_pk_add_f32 v[50:51], v[54:55], v[50:51] op_sel_hi:[0,1]
	v_pk_fma_f32 v[50:51], v[52:53], v[52:53], v[50:51]
	v_pk_fma_f32 v[96:97], v[114:115], s[0:1], v[62:63] op_sel_hi:[1,0,1]
	v_mul_f32_e32 v54, v109, v109
	v_pk_fma_f32 v[110:111], v[116:117], s[0:1], v[64:65] op_sel_hi:[1,0,1]
	v_add_f32_e32 v58, v109, v55
	v_pk_add_f32 v[50:51], v[54:55], v[50:51] op_sel_hi:[0,1]
	v_mov_b32_e32 v54, v110
	v_mov_b32_e32 v55, v97
	v_mov_b32_e32 v52, v96
	v_mov_b32_e32 v53, v109
	v_pk_mul_f32 v[114:115], v[110:111], v[110:111]
	s_mov_b64 s[20:21], 0x20100
	v_lshl_add_u64 v[56:57], v[186:187], 0, s[20:21]
	global_load_dwordx4 v[242:245], v[56:57], off offset:48
	global_load_dwordx4 v[246:249], v[56:57], off offset:32
	global_load_dwordx4 v[250:253], v[188:189], off offset:256
	global_load_dwordx4 v[166:169], v[56:57], off offset:16
	v_add_f32_e32 v56, v96, v58
	v_add_f32_e32 v56, v97, v56
	v_add_f32_e32 v114, v110, v56
	s_waitcnt vmcnt(11)
	v_pk_fma_f32 v[90:91], v[194:195], s[0:1], v[66:67] op_sel_hi:[1,0,1]
	v_pk_fma_f32 v[92:93], v[196:197], s[0:1], v[68:69] op_sel_hi:[1,0,1]
	v_add_f32_e32 v56, 0, v90
	v_add_f32_e32 v58, v91, v56
	v_mul_f32_e32 v56, v91, v91
	v_pk_fma_f32 v[56:57], v[90:91], v[90:91], v[56:57] op_sel_hi:[1,1,0]
	v_add_f32_e32 v58, v92, v58
	v_pk_fma_f32 v[56:57], v[92:93], v[92:93], v[56:57]
	v_add_f32_e32 v59, v93, v58
	v_mul_f32_e32 v58, v93, v93
	s_waitcnt vmcnt(8)
; #define RL_LOAD(XV, G) { constexpr int mt__ = (G) >> 2, half__ = ((G) >> 1) & 1, nt__ = (G) & 1; \
;     _Pragma("unroll") for (int gq = 0; gq < 4; ++gq) XV[gq] = *(const f32x4*)(xin + rbase + (size_t)mt__ * 32 * 1024 + half__ * 64 + nt__ * 32 + 4 * gq); }
; #define RL_FOLD(XV, G, SM, SQ) { constexpr int mt__ = (G) >> 2, half__ = ((G) >> 1) & 1, nt__ = (G) & 1; \
;     _Pragma("unroll") for (int gq = 0; gq < 4; ++gq) _Pragma("unroll") for (int jj = 0; jj < 4; ++jj) { \
;       const float y = ALPHA * XV[gq][jj] + acc[half__][nt__][mt__][4 * gq + jj]; acc[half__][nt__][mt__][4 * gq + jj] = y; SM += y; SQ += y * y; } }
; #define SB __builtin_amdgcn_sched_barrier(0)
;   DI void full(const int mt_, const int nt_, f32x16 (&acc)[2][2][2], const int tw, const int fw, const int r, const int hh, char* lds, const int tid) const {
;     ...
;     RL_FOLD(xc, 1, sm0, sq0); SB; RL_LOAD(xc, 4); SB;
;     RL_FOLD(xe, 2, sm0, sq0); SB; RL_LOAD(xe, 5); SB;
;     RL_FOLD(xa, 3, sm0, sq0); SB; RL_LOAD(xa, 6); SB;
;     RL_FOLD(xc, 4, sm1, sq1); SB; RL_LOAD(xc, 7); SB;
;     RL_FOLD(xe, 5, sm1, sq1); SB;
;     RL_FOLD(xa, 6, sm1, sq1); SB;
;     RL_FOLD(xc, 7, sm1, sq1);
	v_pk_fma_f32 v[86:87], v[226:227], s[0:1], v[70:71] op_sel_hi:[1,0,1]
	v_pk_add_f32 v[56:57], v[58:59], v[56:57] op_sel_hi:[0,1]
	v_add_f32_e32 v58, v86, v59
	v_pk_fma_f32 v[56:57], v[86:87], v[86:87], v[56:57]
	v_add_f32_e32 v59, v87, v58
	v_mul_f32_e32 v58, v87, v87
	v_pk_fma_f32 v[88:89], v[228:229], s[0:1], v[72:73] op_sel_hi:[1,0,1]
	v_pk_add_f32 v[56:57], v[58:59], v[56:57] op_sel_hi:[0,1]
	v_add_f32_e32 v58, v88, v59
	v_pk_fma_f32 v[56:57], v[88:89], v[88:89], v[56:57]
	v_add_f32_e32 v59, v89, v58
	v_mul_f32_e32 v58, v89, v89
	v_pk_fma_f32 v[70:71], v[202:203], s[0:1], v[74:75] op_sel_hi:[1,0,1]
	v_pk_add_f32 v[56:57], v[58:59], v[56:57] op_sel_hi:[0,1]
	v_add_f32_e32 v58, v70, v59
	v_pk_fma_f32 v[56:57], v[70:71], v[70:71], v[56:57]
	v_add_f32_e32 v59, v71, v58
	v_mul_f32_e32 v58, v71, v71
	v_pk_fma_f32 v[72:73], v[204:205], s[0:1], v[76:77] op_sel_hi:[1,0,1]
	v_pk_add_f32 v[56:57], v[58:59], v[56:57] op_sel_hi:[0,1]
	v_add_f32_e32 v58, v72, v59
	v_pk_fma_f32 v[56:57], v[72:73], v[72:73], v[56:57]
	v_add_f32_e32 v59, v73, v58
	v_mul_f32_e32 v58, v73, v73
	v_pk_fma_f32 v[50:51], v[52:53], v[52:53], v[50:51]
	v_mul_f32_e32 v52, v97, v97
	v_pk_add_f32 v[56:57], v[58:59], v[56:57] op_sel_hi:[0,1]
	v_pk_fma_f32 v[68:69], v[98:99], s[0:1], v[78:79] op_sel_hi:[1,0,1]
	v_pk_fma_f32 v[66:67], v[100:101], s[0:1], v[80:81] op_sel_hi:[1,0,1]
	v_pk_add_f32 v[50:51], v[52:53], v[50:51] op_sel_hi:[0,1]
	v_pk_fma_f32 v[74:75], v[54:55], v[54:55], v[50:51]
	s_mov_b64 s[20:21], 0x20180
	v_lshl_add_u64 v[54:55], v[186:187], 0, s[20:21]
	global_load_dwordx4 v[50:53], v[54:55], off offset:48
	global_load_dwordx4 v[76:79], v[54:55], off offset:32
	global_load_dwordx4 v[98:101], v[188:189], off offset:384
	s_nop 0
	global_load_dwordx4 v[186:189], v[54:55], off offset:16
	v_add_f32_e32 v58, v68, v59
	v_pk_fma_f32 v[54:55], v[68:69], v[68:69], v[56:57]
	v_add_f32_e32 v57, v69, v58
	v_mul_f32_e32 v56, v69, v69
	v_pk_add_f32 v[54:55], v[56:57], v[54:55] op_sel_hi:[0,1]
	v_add_f32_e32 v56, v66, v57
	v_pk_fma_f32 v[54:55], v[66:67], v[66:67], v[54:55]
	v_add_f32_e32 v57, v67, v56
	v_mul_f32_e32 v56, v67, v67
	v_pk_add_f32 v[54:55], v[56:57], v[54:55] op_sel_hi:[0,1]
	s_waitcnt vmcnt(9)
	v_pk_fma_f32 v[60:61], v[234:235], s[0:1], v[34:35] op_sel_hi:[1,0,1]
	v_pk_fma_f32 v[64:65], v[236:237], s[0:1], v[36:37] op_sel_hi:[1,0,1]
	v_add_f32_e32 v56, v60, v57
	v_pk_fma_f32 v[34:35], v[60:61], v[60:61], v[54:55]
	v_add_f32_e32 v55, v61, v56
	v_mul_f32_e32 v54, v61, v61
	v_pk_add_f32 v[34:35], v[54:55], v[34:35] op_sel_hi:[0,1]
	v_add_f32_e32 v36, v64, v55
	v_pk_fma_f32 v[34:35], v[64:65], v[64:65], v[34:35]
	v_add_f32_e32 v37, v65, v36
	v_mul_f32_e32 v36, v65, v65
	s_waitcnt vmcnt(8)
	v_pk_fma_f32 v[56:57], v[238:239], s[0:1], v[38:39] op_sel_hi:[1,0,1]
	v_pk_add_f32 v[34:35], v[36:37], v[34:35] op_sel_hi:[0,1]
	v_add_f32_e32 v36, v56, v37
	v_pk_fma_f32 v[34:35], v[56:57], v[56:57], v[34:35]
	v_add_f32_e32 v37, v57, v36
	v_mul_f32_e32 v36, v57, v57
	v_pk_fma_f32 v[62:63], v[240:241], s[0:1], v[40:41] op_sel_hi:[1,0,1]
	v_pk_add_f32 v[34:35], v[36:37], v[34:35] op_sel_hi:[0,1]
	v_add_f32_e32 v36, v62, v37
	v_pk_fma_f32 v[34:35], v[62:63], v[62:63], v[34:35]
	v_add_f32_e32 v37, v63, v36
	v_mul_f32_e32 v36, v63, v63
	v_pk_fma_f32 v[54:55], v[230:231], s[0:1], v[42:43] op_sel_hi:[1,0,1]
	v_pk_add_f32 v[34:35], v[36:37], v[34:35] op_sel_hi:[0,1]
	v_add_f32_e32 v36, v54, v37
	v_pk_fma_f32 v[34:35], v[54:55], v[54:55], v[34:35]
	v_add_f32_e32 v37, v55, v36
	v_mul_f32_e32 v36, v55, v55
	v_pk_fma_f32 v[58:59], v[232:233], s[0:1], v[44:45] op_sel_hi:[1,0,1]
	v_pk_add_f32 v[34:35], v[36:37], v[34:35] op_sel_hi:[0,1]
	v_add_f32_e32 v36, v58, v37
	v_pk_fma_f32 v[34:35], v[58:59], v[58:59], v[34:35]
	v_add_f32_e32 v37, v59, v36
	v_mul_f32_e32 v36, v59, v59
	v_pk_fma_f32 v[44:45], v[82:83], s[0:1], v[46:47] op_sel_hi:[1,0,1]
	v_pk_add_f32 v[34:35], v[36:37], v[34:35] op_sel_hi:[0,1]
	v_add_f32_e32 v36, v44, v37
	v_pk_fma_f32 v[34:35], v[44:45], v[44:45], v[34:35]
	v_add_f32_e32 v37, v45, v36
	v_mul_f32_e32 v36, v45, v45
	v_pk_fma_f32 v[46:47], v[84:85], s[0:1], v[48:49] op_sel_hi:[1,0,1]
	v_pk_add_f32 v[34:35], v[36:37], v[34:35] op_sel_hi:[0,1]
	v_add_f32_e32 v36, v46, v37
	v_pk_fma_f32 v[34:35], v[46:47], v[46:47], v[34:35]
	v_add_f32_e32 v37, v47, v36
	v_mul_f32_e32 v36, v47, v47
	v_pk_add_f32 v[34:35], v[36:37], v[34:35] op_sel_hi:[0,1]
	s_waitcnt vmcnt(5)
	v_pk_fma_f32 v[38:39], v[250:251], s[0:1], v[18:19] op_sel_hi:[1,0,1]
	v_pk_fma_f32 v[42:43], v[252:253], s[0:1], v[20:21] op_sel_hi:[1,0,1]
	v_add_f32_e32 v36, v38, v37
	v_pk_fma_f32 v[18:19], v[38:39], v[38:39], v[34:35]
	v_add_f32_e32 v35, v39, v36
	v_mul_f32_e32 v34, v39, v39
	v_pk_add_f32 v[18:19], v[34:35], v[18:19] op_sel_hi:[0,1]
	v_add_f32_e32 v20, v42, v35
	v_pk_fma_f32 v[18:19], v[42:43], v[42:43], v[18:19]
	v_add_f32_e32 v21, v43, v20
	v_mul_f32_e32 v20, v43, v43
	s_waitcnt vmcnt(4)
; #define RL_FOLD(XV, G, SM, SQ) { constexpr int mt__ = (G) >> 2, half__ = ((G) >> 1) & 1, nt__ = (G) & 1; \
;     _Pragma("unroll") for (int gq = 0; gq < 4; ++gq) _Pragma("unroll") for (int jj = 0; jj < 4; ++jj) { \
;       const float y = ALPHA * XV[gq][jj] + acc[half__][nt__][mt__][4 * gq + jj]; acc[half__][nt__][mt__][4 * gq + jj] = y; SM += y; SQ += y * y; } }
;   DI void full(const int mt_, const int nt_, f32x16 (&acc)[2][2][2], const int tw, const int fw, const int r, const int hh, char* lds, const int tid) const {
;     ...
;     RL_FOLD(xc, 7, sm1, sq1);
;     ...
;     sm0 += __shfl_xor(sm0, 32, 64); sq0 += __shfl_xor(sq0, 32, 64); sm1 += __shfl_xor(sm1, 32, 64); sq1 += __shfl_xor(sq1, 32, 64);
;     if (hh == 0) {
;       float* pp = part + ((fw * 256) + tw * 64 + r) * 2; pp[0] = sm0; pp[1] = sq0;
;       pp[64] = sm1; pp[65] = sq1;
	v_pk_fma_f32 v[34:35], v[166:167], s[0:1], v[22:23] op_sel_hi:[1,0,1]
	v_pk_add_f32 v[18:19], v[20:21], v[18:19] op_sel_hi:[0,1]
	v_add_f32_e32 v20, v34, v21
	v_pk_fma_f32 v[18:19], v[34:35], v[34:35], v[18:19]
	v_add_f32_e32 v21, v35, v20
	v_mul_f32_e32 v20, v35, v35
	v_pk_fma_f32 v[40:41], v[168:169], s[0:1], v[24:25] op_sel_hi:[1,0,1]
	v_pk_add_f32 v[18:19], v[20:21], v[18:19] op_sel_hi:[0,1]
	v_add_f32_e32 v20, v40, v21
	v_pk_fma_f32 v[18:19], v[40:41], v[40:41], v[18:19]
	v_add_f32_e32 v21, v41, v20
	v_mul_f32_e32 v20, v41, v41
	v_pk_fma_f32 v[26:27], v[246:247], s[0:1], v[26:27] op_sel_hi:[1,0,1]
	v_pk_add_f32 v[18:19], v[20:21], v[18:19] op_sel_hi:[0,1]
	v_add_f32_e32 v20, v26, v21
	v_pk_fma_f32 v[18:19], v[26:27], v[26:27], v[18:19]
	v_add_f32_e32 v21, v27, v20
	v_mul_f32_e32 v20, v27, v27
	v_pk_fma_f32 v[36:37], v[248:249], s[0:1], v[28:29] op_sel_hi:[1,0,1]
	v_pk_add_f32 v[18:19], v[20:21], v[18:19] op_sel_hi:[0,1]
	v_add_f32_e32 v20, v36, v21
	v_pk_fma_f32 v[18:19], v[36:37], v[36:37], v[18:19]
	v_add_f32_e32 v21, v37, v20
	v_mul_f32_e32 v20, v37, v37
	v_pk_fma_f32 v[24:25], v[242:243], s[0:1], v[30:31] op_sel_hi:[1,0,1]
	v_pk_add_f32 v[18:19], v[20:21], v[18:19] op_sel_hi:[0,1]
	v_add_f32_e32 v20, v24, v21
	v_pk_fma_f32 v[18:19], v[24:25], v[24:25], v[18:19]
	v_add_f32_e32 v21, v25, v20
	v_mul_f32_e32 v20, v25, v25
	v_pk_fma_f32 v[28:29], v[244:245], s[0:1], v[32:33] op_sel_hi:[1,0,1]
	v_pk_add_f32 v[18:19], v[20:21], v[18:19] op_sel_hi:[0,1]
	v_add_f32_e32 v20, v28, v21
	v_pk_fma_f32 v[18:19], v[28:29], v[28:29], v[18:19]
	v_add_f32_e32 v22, v29, v20
	v_mul_f32_e32 v20, v29, v29
	v_pk_add_f32 v[20:21], v[20:21], v[18:19] op_sel_hi:[0,1]
	s_waitcnt vmcnt(1)
	v_pk_fma_f32 v[18:19], v[98:99], s[0:1], v[2:3] op_sel_hi:[1,0,1]
	s_waitcnt vmcnt(0)
	v_pk_fma_f32 v[6:7], v[186:187], s[0:1], v[6:7] op_sel_hi:[1,0,1]
	v_add_f32_e32 v22, v18, v22
	v_pk_fma_f32 v[2:3], v[18:19], v[18:19], v[20:21]
	v_add_f32_e32 v21, v19, v22
	v_pk_fma_f32 v[22:23], v[100:101], s[0:1], v[4:5] op_sel_hi:[1,0,1]
	v_mul_f32_e32 v20, v19, v19
	v_add_f32_e32 v4, v22, v21
	v_pk_add_f32 v[2:3], v[20:21], v[2:3] op_sel_hi:[0,1]
	v_add_f32_e32 v4, v23, v4
	v_pk_fma_f32 v[2:3], v[22:23], v[22:23], v[2:3]
	v_add_f32_e32 v21, v6, v4
	v_mul_f32_e32 v20, v23, v23
	v_mov_b32_e32 v4, v6
	v_mov_b32_e32 v5, v23
	v_pk_add_f32 v[2:3], v[20:21], v[2:3] op_sel_hi:[0,1]
	v_pk_fma_f32 v[2:3], v[4:5], v[4:5], v[2:3]
	v_add_f32_e32 v4, v7, v21
	v_pk_fma_f32 v[20:21], v[188:189], s[0:1], v[8:9] op_sel_hi:[1,0,1]
	v_mul_f32_e32 v8, v7, v7
	v_add_f32_e32 v9, v20, v4
	v_mov_b32_e32 v4, v20
	v_mov_b32_e32 v5, v7
	v_pk_add_f32 v[2:3], v[8:9], v[2:3] op_sel_hi:[0,1]
	v_pk_fma_f32 v[4:5], v[4:5], v[4:5], v[2:3]
	v_add_f32_e32 v8, v21, v9
	v_pk_fma_f32 v[2:3], v[76:77], s[0:1], v[10:11] op_sel_hi:[1,0,1]
	v_mul_f32_e32 v10, v21, v21
	v_add_f32_e32 v11, v2, v8
	v_mov_b32_e32 v8, v2
	v_mov_b32_e32 v9, v21
	v_pk_add_f32 v[4:5], v[10:11], v[4:5] op_sel_hi:[0,1]
	v_pk_fma_f32 v[4:5], v[8:9], v[8:9], v[4:5]
	v_add_f32_e32 v10, v3, v11
	v_pk_fma_f32 v[8:9], v[78:79], s[0:1], v[12:13] op_sel_hi:[1,0,1]
	v_mul_f32_e32 v12, v3, v3
	v_add_f32_e32 v13, v8, v10
	v_mov_b32_e32 v10, v8
	v_mov_b32_e32 v11, v3
	v_pk_add_f32 v[4:5], v[12:13], v[4:5] op_sel_hi:[0,1]
	v_pk_fma_f32 v[10:11], v[10:11], v[10:11], v[4:5]
	v_add_f32_e32 v12, v9, v13
	v_pk_fma_f32 v[4:5], v[50:51], s[0:1], v[14:15] op_sel_hi:[1,0,1]
	v_mul_f32_e32 v14, v9, v9
	v_add_f32_e32 v15, v4, v12
	v_mov_b32_e32 v12, v4
	v_mov_b32_e32 v13, v9
	v_pk_add_f32 v[10:11], v[14:15], v[10:11] op_sel_hi:[0,1]
	v_pk_fma_f32 v[12:13], v[12:13], v[12:13], v[10:11]
	v_pk_fma_f32 v[10:11], v[52:53], s[0:1], v[16:17] op_sel_hi:[1,0,1]
	v_mul_f32_e32 v30, v5, v5
	v_mov_b32_e32 v16, v10
	v_mov_b32_e32 v17, v5
	v_pk_add_f32 v[12:13], v[30:31], v[12:13] op_sel_hi:[0,1]
	v_pk_fma_f32 v[12:13], v[16:17], v[16:17], v[12:13]
	v_pk_mul_f32 v[16:17], v[10:11], v[10:11]
	v_add_f32_e32 v14, v5, v15
	v_mov_b32_e32 v15, v17
	v_and_b32_e32 v17, 64, v201
	v_xor_b32_e32 v16, 32, v201
	v_add_u32_e32 v17, 64, v17
	v_add_f32_e32 v14, v10, v14
	v_pk_mov_b32 v[12:13], v[10:11], v[12:13] op_sel:[1,0]
	v_cmp_lt_i32_e32 vcc, v16, v17
	v_pk_add_f32 v[12:13], v[12:13], v[14:15]
	v_pk_mov_b32 v[14:15], v[110:111], v[74:75] op_sel:[1,0]
	v_cndmask_b32_e32 v16, v201, v16, vcc
	v_pk_add_f32 v[14:15], v[14:15], v[114:115]
	v_lshlrev_b32_e32 v31, 2, v16
	ds_bpermute_b32 v16, v31, v14
	ds_bpermute_b32 v17, v31, v15
	ds_bpermute_b32 v30, v31, v12
	ds_bpermute_b32 v31, v31, v13
	v_cmp_eq_u32_e32 vcc, 0, v224
	s_and_saveexec_b64 s[20:21], vcc
	s_cbranch_execz .LBB0_272
	v_lshlrev_b32_e32 v32, 3, v184
	v_and_b32_e32 v32, 0xfffffef8, v32
	v_add_u32_e32 v32, 0, v32
	v_add_u32_e32 v32, 0x12000, v32
	s_waitcnt lgkmcnt(2)
	v_pk_add_f32 v[14:15], v[14:15], v[16:17]
	s_waitcnt lgkmcnt(0)
	v_pk_add_f32 v[12:13], v[12:13], v[30:31]
	ds_write2_b64 v32, v[14:15], v[12:13] offset1:32

; #define G_GLOAD(XR, WR, KT) { _Pragma("unroll") for (int i_ = 0; i_ < 4; ++i_) XR[i_] = *(const u32x4*)(Xt + ((size_t)(64 * i_) * ldx + (KT) * 64) * 2 + xoff); \
;     _Pragma("unroll") for (int i_ = 0; i_ < 4; ++i_) WR[i_] = *(const u32x4*)(Wtb + ((size_t)(64 * i_) * K + (KT) * 64) * 2 + woff); }
; #define G_LSTORE(XR, WR, STG) { char* xs_ = lds + (STG) * G_STAGE; char* ws_ = xs_ + G_XB; \
;     _Pragma("unroll") for (int i_ = 0; i_ < 4; ++i_) *(u32x4*)(xs_ + (lrow + 64 * i_) * LROW + lch * 16) = XR[i_]; \
;     _Pragma("unroll") for (int i_ = 0; i_ < 4; ++i_) *(u32x4*)(ws_ + (lrow + 64 * i_) * LROW + lch * 16) = WR[i_]; }
; template <class Epi>
; DI void gemm_phase(const bf16_t* __restrict__ X, const int ldx, const bf16_t* __restrict__ Wt, const int N, const int K, const Epi& epi, char* lds) {
;     ...
;     const int L = chunk * 32 + slot, band = L / (4 * nNt), rem = L % (4 * nNt);
;     const int mt_ = band * 4 + (rem & 3), nt_ = rem >> 2;
;     const char* Xt = (const char*)(X + (size_t)(mt_ * 256) * ldx);
;     const char* Wtb = (const char*)(Wt + (size_t)(nt_ * 256) * K);
;     const unsigned xoff = (unsigned)(lrow * ldx + lch * 8) * 2u, woff = (unsigned)(lrow * K + lch * 8) * 2u;
;     const bool has_next = !Epi::kFull && (chunk + 8 < nchunks);
;     const int Ln = (has_next ? chunk + 8 : chunk) * 32 + slot, band_n = Ln / (4 * nNt), rem_n = Ln % (4 * nNt);
;     const char* Xt_n = (const char*)(X + (size_t)((band_n * 4 + (rem_n & 3)) * 256) * ldx);
;     const char* Wtb_n = (const char*)(Wt + (size_t)((rem_n >> 2) * 256) * K);
;     f32x16 acc[2][2][2];
;     ...
;     asm volatile("" ::: "memory");
;     if (Epi::kFull || chunk == xcd) {
;       G_GLOAD(xr0, wr0, 0);
;       G_LSTORE(xr0, wr0, 0);
;       __syncthreads();
;       G_GLOAD(xr0, wr0, 1);
;     }
; #pragma unroll
;     for (int c = 0; c < 2; ++c)
; #pragma unroll
;       for (int a = 0; a < 2; ++a)
; #pragma unroll
;         for (int b = 0; b < 2; ++b)
; #pragma unroll
;           for (int i = 0; i < 16; ++i) acc[c][a][b][i] = 0.f;
.LBB0_700:
	s_lshl_b32 s2, s34, 5
	v_readlane_b32 s3, v254, 3
	s_add_i32 s2, s2, s3
	s_lshr_b32 s2, s2, 2
	s_and_b32 s2, s2, 0xffffffc
	s_or_b32 s2, s2, s90
	s_lshl_b32 s4, s2, 8
	s_mov_b32 s5, s97
	s_lshl_b64 s[18:19], s[4:5], 11
	s_add_u32 s18, s6, s18
	s_addc_u32 s19, s7, s19
	v_lshl_add_u64 v[178:179], s[18:19], 0, v[162:163]
	s_waitcnt vmcnt(2)
	v_add_co_u32_e32 v48, vcc, s91, v178
	s_mov_b64 s[20:21], 0x40000
	s_nop 0
	v_addc_co_u32_e32 v49, vcc, 0, v179, vcc
	v_add_co_u32_e32 v74, vcc, s1, v178
	global_load_dwordx4 v[24:27], v[178:179], off
	global_load_dwordx4 v[28:31], v[48:49], off
	v_addc_co_u32_e32 v75, vcc, 0, v179, vcc
	v_add_co_u32_e32 v76, vcc, s76, v178
	global_load_dwordx4 v[32:35], v[164:165], off
	global_load_dwordx4 v[36:39], v[198:199], off
	global_load_dwordx4 v[40:43], v[206:207], off
	global_load_dwordx4 v[44:47], v[170:171], off
	v_addc_co_u32_e32 v77, vcc, 0, v179, vcc
	global_load_dwordx4 v[66:69], v[74:75], off
	global_load_dwordx4 v[70:73], v[76:77], off
	v_mov_b32_e32 v2, 0
	v_lshl_add_u64 v[180:181], v[178:179], 0, s[20:21]
	s_mov_b64 s[20:21], 0x60000
	s_mov_b32 s19, 0
	s_movk_i32 s3, 0x100
	v_mov_b32_e32 v3, v2
	v_mov_b64_e32 v[4:5], v[2:3]
	v_mov_b64_e32 v[6:7], v[2:3]
	v_mov_b64_e32 v[8:9], v[2:3]
	v_mov_b64_e32 v[10:11], v[2:3]
	v_mov_b64_e32 v[12:13], v[2:3]
	v_mov_b64_e32 v[14:15], v[2:3]
	v_mov_b64_e32 v[16:17], v[2:3]
	s_waitcnt vmcnt(9)
	v_mov_b64_e32 v[50:51], v[2:3]
	v_mov_b64_e32 v[52:53], v[2:3]
	s_waitcnt vmcnt(8)
	v_mov_b64_e32 v[54:55], v[2:3]
	v_mov_b64_e32 v[56:57], v[2:3]
	v_mov_b64_e32 v[58:59], v[2:3]
	v_mov_b64_e32 v[60:61], v[2:3]
	v_mov_b64_e32 v[62:63], v[2:3]
	v_mov_b64_e32 v[64:65], v[2:3]
	v_mov_b64_e32 v[18:19], v[2:3]
	v_mov_b64_e32 v[20:21], v[2:3]
	v_mov_b32_e32 v22, v2
	v_lshl_add_u64 v[182:183], v[178:179], 0, s[20:21]
	v_mov_b32_e32 v23, v2
	v_mov_b64_e32 v[82:83], v[2:3]
	v_mov_b64_e32 v[84:85], v[2:3]
	v_mov_b64_e32 v[86:87], v[2:3]
	v_mov_b64_e32 v[88:89], v[2:3]
	v_mov_b64_e32 v[90:91], v[2:3]
	v_mov_b64_e32 v[92:93], v[2:3]
	v_mov_b64_e32 v[94:95], v[2:3]
	v_mov_b64_e32 v[96:97], v[2:3]
	v_mov_b64_e32 v[98:99], v[2:3]
	v_mov_b64_e32 v[100:101], v[2:3]
	v_mov_b64_e32 v[102:103], v[2:3]
	v_mov_b32_e32 v104, v2
	s_waitcnt vmcnt(5)
	ds_write_b128 v222, v[32:35] offset:36864
	s_waitcnt vmcnt(4)
	ds_write_b128 v222, v[36:39] offset:46080
	s_waitcnt vmcnt(3)
	ds_write_b128 v222, v[40:43] offset:55296
	s_waitcnt vmcnt(2)
	ds_write_b128 v222, v[44:47] offset:64512
	ds_write_b128 v222, v[24:27]
	ds_write_b128 v222, v[28:31] offset:9216
	s_waitcnt vmcnt(1)
	ds_write_b128 v222, v[66:69] offset:18432
	s_waitcnt vmcnt(0)
	ds_write_b128 v222, v[70:73] offset:27648
	s_waitcnt lgkmcnt(0)
	s_barrier
	global_load_dwordx4 v[130:133], v[174:175], off
	global_load_dwordx4 v[150:153], v[176:177], off
	global_load_dwordx4 v[158:161], v[172:173], off
	global_load_dwordx4 v[138:141], v[164:165], off offset:128
	global_load_dwordx4 v[146:149], v[76:77], off offset:128
	global_load_dwordx4 v[134:137], v[74:75], off offset:128
	global_load_dwordx4 v[154:157], v[48:49], off offset:128
	global_load_dwordx4 v[142:145], v[178:179], off offset:128
	v_mov_b64_e32 v[24:25], v[2:3]
	v_mov_b64_e32 v[26:27], v[2:3]
	v_mov_b64_e32 v[28:29], v[2:3]
	v_mov_b64_e32 v[30:31], v[2:3]
	v_mov_b64_e32 v[32:33], v[2:3]
	v_mov_b64_e32 v[34:35], v[2:3]
	v_mov_b64_e32 v[36:37], v[2:3]
	v_mov_b64_e32 v[38:39], v[2:3]
	v_mov_b64_e32 v[40:41], v[2:3]
	v_mov_b64_e32 v[42:43], v[2:3]
	v_mov_b64_e32 v[44:45], v[2:3]
	v_mov_b64_e32 v[46:47], v[2:3]
	v_mov_b64_e32 v[48:49], v[2:3]
	v_mov_b32_e32 v105, v2
	v_mov_b64_e32 v[106:107], v[2:3]
	v_mov_b64_e32 v[108:109], v[2:3]
	v_mov_b64_e32 v[110:111], v[2:3]
	v_mov_b64_e32 v[112:113], v[2:3]
	v_mov_b64_e32 v[66:67], v[2:3]
	v_mov_b64_e32 v[68:69], v[2:3]
	v_mov_b64_e32 v[70:71], v[2:3]
	v_mov_b64_e32 v[72:73], v[2:3]
	v_mov_b64_e32 v[74:75], v[2:3]
	v_mov_b64_e32 v[76:77], v[2:3]
	v_mov_b64_e32 v[78:79], v[2:3]
	v_mov_b64_e32 v[80:81], v[2:3]
	v_mov_b64_e32 v[114:115], v[2:3]
	v_mov_b64_e32 v[116:117], v[2:3]
	v_mov_b32_e32 v118, v2
	v_mov_b32_e32 v119, v2
	v_mov_b32_e32 v120, v2
	v_mov_b32_e32 v121, v2
	v_mov_b32_e32 v122, v2
	v_mov_b32_e32 v123, v2
	v_mov_b32_e32 v124, v2
	v_mov_b32_e32 v125, v2
	v_mov_b32_e32 v126, v2
	v_mov_b32_e32 v127, v2
	v_mov_b32_e32 v128, v2
	v_mov_b32_e32 v129, v2
	v_readfirstlane_b32 vcc_lo, v162
	v_readfirstlane_b32 s98, v178
	v_readfirstlane_b32 s99, v179
	v_readfirstlane_b32 s100, v164
	v_readfirstlane_b32 s101, v165
	s_nop 4
	s_sub_u32 s98, s98, vcc_lo
	s_subb_u32 s99, s99, 0
	s_sub_u32 s100, s100, vcc_lo
	s_subb_u32 s101, s101, 0
	v_add_u32_e32 v179, s91, v162
	v_add_u32_e32 v181, s1, v162
	v_add_u32_e32 v183, s76, v162
	v_add_u32_e32 v178, v191, v208
	v_add_u32_e32 v180, v191, v209
	v_add_u32_e32 v182, v210, v190
.LBB0_701:
	ds_read_b128 v[166:169], v178
	ds_read_b128 v[184:187], v178 offset:4608
	ds_read_b128 v[194:197], v180 offset:36864
	ds_read_b128 v[202:205], v180 offset:41472
	ds_read_b128 v[224:227], v180 offset:46080
	ds_read_b128 v[228:231], v180 offset:50688
	ds_read_b128 v[232:235], v212 offset:32
	ds_read_b128 v[236:239], v212 offset:4640
	s_add_i32 s5, s19, 2
	s_cmp_lt_u32 s19, 14
	s_cselect_b32 s96, s3, 0x780
	s_min_u32 s18, s19, 12
	s_lshl_b32 s18, s18, 7
	s_addk_i32 s3, 0x100
	s_cmp_gt_u32 s19, 13
	s_waitcnt lgkmcnt(5)
	v_mfma_f32_32x32x16_bf16 v[114:129], v[194:197], v[166:169], v[114:129]
	v_mfma_f32_32x32x16_bf16 v[66:81], v[194:197], v[184:187], v[66:81]
	s_waitcnt lgkmcnt(4)
	v_mfma_f32_32x32x16_bf16 v[98:113], v[202:205], v[166:169], v[98:113]
	v_mfma_f32_32x32x16_bf16 v[34:49], v[202:205], v[184:187], v[34:49]
	s_waitcnt lgkmcnt(3)
	v_mfma_f32_32x32x16_bf16 v[82:97], v[224:227], v[166:169], v[82:97]
	v_mfma_f32_32x32x16_bf16 v[18:33], v[224:227], v[184:187], v[18:33]
	s_waitcnt lgkmcnt(2)
	v_mfma_f32_32x32x16_bf16 v[50:65], v[228:231], v[166:169], v[50:65]
	ds_read_b128 v[166:169], v213 offset:36896
	ds_read_b128 v[194:197], v213 offset:41504
	v_mfma_f32_32x32x16_bf16 v[2:17], v[228:231], v[184:187], v[2:17]
	s_waitcnt vmcnt(1)
	ds_write_b128 v214, v[154:157] offset:9216
	s_waitcnt vmcnt(0)
	ds_write_b128 v214, v[142:145]
	s_add_u32 vcc_lo, s98, s96
	s_addc_u32 vcc_hi, s99, 0
	global_load_dwordx4 v[142:145], v162, vcc
	global_load_dwordx4 v[154:157], v179, vcc
	ds_write_b128 v214, v[134:137] offset:18432
	ds_write_b128 v214, v[146:149] offset:27648
	global_load_dwordx4 v[134:137], v181, vcc
	global_load_dwordx4 v[146:149], v183, vcc
	ds_read_b128 v[184:187], v213 offset:46112
	ds_read_b128 v[202:205], v213 offset:50720
	ds_read_b128 v[224:227], v212 offset:64
	ds_read_b128 v[228:231], v212 offset:4672
	s_waitcnt lgkmcnt(9)
	v_mfma_f32_32x32x16_bf16 v[114:129], v[166:169], v[232:235], v[114:129]
	v_mfma_f32_32x32x16_bf16 v[66:81], v[166:169], v[236:239], v[66:81]
	s_waitcnt lgkmcnt(8)
	v_mfma_f32_32x32x16_bf16 v[98:113], v[194:197], v[232:235], v[98:113]
	v_mfma_f32_32x32x16_bf16 v[34:49], v[194:197], v[236:239], v[34:49]
	s_waitcnt lgkmcnt(3)
	v_mfma_f32_32x32x16_bf16 v[82:97], v[184:187], v[232:235], v[82:97]
	v_mfma_f32_32x32x16_bf16 v[18:33], v[184:187], v[236:239], v[18:33]
	ds_read_b128 v[166:169], v213 offset:36928
	ds_read_b128 v[184:187], v213 offset:41536
	s_waitcnt lgkmcnt(4)
	v_mfma_f32_32x32x16_bf16 v[50:65], v[202:205], v[232:235], v[50:65]
	v_mfma_f32_32x32x16_bf16 v[2:17], v[202:205], v[236:239], v[2:17]
	ds_write_b128 v215, v[150:153] offset:9216
	ds_write_b128 v215, v[138:141]
	s_add_u32 vcc_lo, s100, s96
	s_addc_u32 vcc_hi, s101, 0
	global_load_dwordx4 v[138:141], v162, vcc
	global_load_dwordx4 v[150:153], v179, vcc
	ds_read_b128 v[194:197], v213 offset:46144
	ds_read_b128 v[202:205], v213 offset:50752
	ds_read_b128 v[232:235], v212 offset:96
	ds_read_b128 v[236:239], v212 offset:4704
	s_waitcnt lgkmcnt(7)
	v_mfma_f32_32x32x16_bf16 v[114:129], v[166:169], v[224:227], v[114:129]
	v_mfma_f32_32x32x16_bf16 v[66:81], v[166:169], v[228:231], v[66:81]
	s_waitcnt lgkmcnt(6)
	v_mfma_f32_32x32x16_bf16 v[98:113], v[184:187], v[224:227], v[98:113]
	v_mfma_f32_32x32x16_bf16 v[34:49], v[184:187], v[228:231], v[34:49]
	s_waitcnt lgkmcnt(3)
	v_mfma_f32_32x32x16_bf16 v[82:97], v[194:197], v[224:227], v[82:97]
	ds_read_b128 v[166:169], v213 offset:36960
	ds_read_b128 v[184:187], v213 offset:41568
	v_mfma_f32_32x32x16_bf16 v[18:33], v[194:197], v[228:231], v[18:33]
	s_waitcnt lgkmcnt(4)
	v_mfma_f32_32x32x16_bf16 v[50:65], v[202:205], v[224:227], v[50:65]
	v_mfma_f32_32x32x16_bf16 v[2:17], v[202:205], v[228:231], v[2:17]
	ds_write_b128 v215, v[130:133] offset:18432
	ds_write_b128 v215, v[158:161] offset:27648
	global_load_dwordx4 v[130:133], v181, vcc
	global_load_dwordx4 v[158:161], v183, vcc
	ds_read_b128 v[194:197], v213 offset:46176
	ds_read_b128 v[202:205], v213 offset:50784
	s_waitcnt lgkmcnt(5)
	v_mfma_f32_32x32x16_bf16 v[114:129], v[166:169], v[232:235], v[114:129]
	v_mfma_f32_32x32x16_bf16 v[66:81], v[166:169], v[236:239], v[66:81]
	s_waitcnt lgkmcnt(4)
	v_mfma_f32_32x32x16_bf16 v[98:113], v[184:187], v[232:235], v[98:113]
	v_mfma_f32_32x32x16_bf16 v[34:49], v[184:187], v[236:239], v[34:49]
	s_waitcnt lgkmcnt(1)
	v_mfma_f32_32x32x16_bf16 v[82:97], v[194:197], v[232:235], v[82:97]
	v_mfma_f32_32x32x16_bf16 v[18:33], v[194:197], v[236:239], v[18:33]
	s_waitcnt lgkmcnt(0)
	v_mfma_f32_32x32x16_bf16 v[50:65], v[202:205], v[232:235], v[50:65]
	v_mfma_f32_32x32x16_bf16 v[2:17], v[202:205], v[236:239], v[2:17]
	s_barrier
	ds_read_b128 v[166:169], v216
	ds_read_b128 v[184:187], v216 offset:4608
	ds_read_b128 v[194:197], v217
	ds_read_b128 v[202:205], v217 offset:4608
	ds_read_b128 v[224:227], v217 offset:9216
	ds_read_b128 v[228:231], v217 offset:13824
	ds_read_b128 v[232:235], v182 offset:32
	ds_read_b128 v[236:239], v218 offset:32
	s_waitcnt lgkmcnt(5)
	v_mfma_f32_32x32x16_bf16 v[114:129], v[194:197], v[166:169], v[114:129]
	v_mfma_f32_32x32x16_bf16 v[66:81], v[194:197], v[184:187], v[66:81]
	s_waitcnt lgkmcnt(4)
	v_mfma_f32_32x32x16_bf16 v[98:113], v[202:205], v[166:169], v[98:113]
	v_mfma_f32_32x32x16_bf16 v[34:49], v[202:205], v[184:187], v[34:49]
	s_waitcnt lgkmcnt(3)
	v_mfma_f32_32x32x16_bf16 v[82:97], v[224:227], v[166:169], v[82:97]
	v_add_u32_e32 v223, v211, v190
	v_mfma_f32_32x32x16_bf16 v[18:33], v[224:227], v[184:187], v[18:33]
	s_waitcnt lgkmcnt(2)
	v_mfma_f32_32x32x16_bf16 v[50:65], v[228:231], v[166:169], v[50:65]
	ds_read_b128 v[166:169], v223 offset:32
	ds_read_b128 v[194:197], v219 offset:32
	v_mfma_f32_32x32x16_bf16 v[2:17], v[228:231], v[184:187], v[2:17]
	s_mov_b32 s19, s97
	s_waitcnt vmcnt(6)
	ds_write_b128 v222, v[154:157] offset:9216
	ds_write_b128 v222, v[142:145]
	s_add_u32 vcc_lo, s98, s18
	s_addc_u32 vcc_hi, s99, 0
	global_load_dwordx4 v[142:145], v162, vcc offset:384
	global_load_dwordx4 v[154:157], v179, vcc offset:384
	s_waitcnt vmcnt(7)
	ds_write_b128 v222, v[134:137] offset:18432
	s_waitcnt vmcnt(6)
	ds_write_b128 v222, v[146:149] offset:27648
	global_load_dwordx4 v[134:137], v181, vcc offset:384
	global_load_dwordx4 v[146:149], v183, vcc offset:384
	ds_read_b128 v[184:187], v220 offset:32
	ds_read_b128 v[202:205], v221 offset:32
	ds_read_b128 v[224:227], v182 offset:64
	ds_read_b128 v[228:231], v218 offset:64
	s_waitcnt lgkmcnt(9)
	v_mfma_f32_32x32x16_bf16 v[114:129], v[166:169], v[232:235], v[114:129]
	v_mfma_f32_32x32x16_bf16 v[66:81], v[166:169], v[236:239], v[66:81]
	s_waitcnt lgkmcnt(8)
	v_mfma_f32_32x32x16_bf16 v[98:113], v[194:197], v[232:235], v[98:113]
	v_mfma_f32_32x32x16_bf16 v[34:49], v[194:197], v[236:239], v[34:49]
	s_waitcnt lgkmcnt(3)
	v_mfma_f32_32x32x16_bf16 v[82:97], v[184:187], v[232:235], v[82:97]
	v_mfma_f32_32x32x16_bf16 v[18:33], v[184:187], v[236:239], v[18:33]
	ds_read_b128 v[166:169], v223 offset:64
	ds_read_b128 v[184:187], v219 offset:64
	s_waitcnt lgkmcnt(4)
	v_mfma_f32_32x32x16_bf16 v[50:65], v[202:205], v[232:235], v[50:65]
	v_mfma_f32_32x32x16_bf16 v[2:17], v[202:205], v[236:239], v[2:17]
	s_waitcnt vmcnt(6)
	ds_write_b128 v222, v[150:153] offset:46080
	ds_write_b128 v222, v[138:141] offset:36864
	s_add_u32 vcc_lo, s100, s18
	s_addc_u32 vcc_hi, s101, 0
	global_load_dwordx4 v[138:141], v162, vcc offset:384
	global_load_dwordx4 v[150:153], v179, vcc offset:384
	ds_read_b128 v[194:197], v220 offset:64
	ds_read_b128 v[202:205], v221 offset:64
	ds_read_b128 v[232:235], v182 offset:96
	ds_read_b128 v[236:239], v218 offset:96
	s_waitcnt lgkmcnt(7)
	v_mfma_f32_32x32x16_bf16 v[114:129], v[166:169], v[224:227], v[114:129]
	v_mfma_f32_32x32x16_bf16 v[66:81], v[166:169], v[228:231], v[66:81]
	s_waitcnt lgkmcnt(6)
	v_mfma_f32_32x32x16_bf16 v[98:113], v[184:187], v[224:227], v[98:113]
	v_mfma_f32_32x32x16_bf16 v[34:49], v[184:187], v[228:231], v[34:49]
	s_waitcnt lgkmcnt(3)
	v_mfma_f32_32x32x16_bf16 v[82:97], v[194:197], v[224:227], v[82:97]
	ds_read_b128 v[166:169], v223 offset:96
	ds_read_b128 v[184:187], v219 offset:96
	v_mfma_f32_32x32x16_bf16 v[18:33], v[194:197], v[228:231], v[18:33]
	s_waitcnt lgkmcnt(4)
	v_mfma_f32_32x32x16_bf16 v[50:65], v[202:205], v[224:227], v[50:65]
	v_mfma_f32_32x32x16_bf16 v[2:17], v[202:205], v[228:231], v[2:17]
	s_waitcnt vmcnt(7)
	ds_write_b128 v222, v[130:133] offset:55296
	s_waitcnt vmcnt(6)
	ds_write_b128 v222, v[158:161] offset:64512
	global_load_dwordx4 v[130:133], v181, vcc offset:384
	global_load_dwordx4 v[158:161], v183, vcc offset:384
	ds_read_b128 v[194:197], v220 offset:96
	ds_read_b128 v[202:205], v221 offset:96
	s_waitcnt lgkmcnt(5)
	v_mfma_f32_32x32x16_bf16 v[114:129], v[166:169], v[232:235], v[114:129]
	v_mfma_f32_32x32x16_bf16 v[66:81], v[166:169], v[236:239], v[66:81]
	s_waitcnt lgkmcnt(4)
	v_mfma_f32_32x32x16_bf16 v[98:113], v[184:187], v[232:235], v[98:113]
	v_mfma_f32_32x32x16_bf16 v[34:49], v[184:187], v[236:239], v[34:49]
	s_waitcnt lgkmcnt(1)
	v_mfma_f32_32x32x16_bf16 v[82:97], v[194:197], v[232:235], v[82:97]
	v_mfma_f32_32x32x16_bf16 v[18:33], v[194:197], v[236:239], v[18:33]
	s_waitcnt lgkmcnt(0)
	v_mfma_f32_32x32x16_bf16 v[50:65], v[202:205], v[232:235], v[50:65]
	v_mfma_f32_32x32x16_bf16 v[2:17], v[202:205], v[236:239], v[2:17]
	s_mov_b32 s19, s5
	s_cmp_gt_u32 s19, 15
	s_barrier
	s_cbranch_scc0 .LBB0_701
; #define RL_LOAD(XV, G) { constexpr int mt__ = (G) >> 2, half__ = ((G) >> 1) & 1, nt__ = (G) & 1; \
;     _Pragma("unroll") for (int gq = 0; gq < 4; ++gq) XV[gq] = *(const f32x4*)(xin + rbase + (size_t)mt__ * 32 * 1024 + half__ * 64 + nt__ * 32 + 4 * gq); }
; #define RL_FOLD(XV, G, SM, SQ) { constexpr int mt__ = (G) >> 2, half__ = ((G) >> 1) & 1, nt__ = (G) & 1; \
;     _Pragma("unroll") for (int gq = 0; gq < 4; ++gq) _Pragma("unroll") for (int jj = 0; jj < 4; ++jj) { \
;       const float y = ALPHA * XV[gq][jj] + acc[half__][nt__][mt__][4 * gq + jj]; acc[half__][nt__][mt__][4 * gq + jj] = y; SM += y; SQ += y * y; } }
; #define SB __builtin_amdgcn_sched_barrier(0)
;   DI void full(const int mt_, const int nt_, f32x16 (&acc)[2][2][2], const int tw, const int fw, const int r, const int hh, char* lds, const int tid) const {
;     float* part = (float*)(lds + G_STAGE);
;     const size_t rbase = (size_t)(mt_ * 256 + tw * 64 + r) * 1024 + nt_ * 256 + fw * 128 + 16 * hh;
;     f32x4 xa[4], xc[4], xe[4];
;     ...
;     float sm0 = 0.f, sq0 = 0.f, sm1 = 0.f, sq1 = 0.f;
;     RL_LOAD(xa, 0); RL_LOAD(xc, 1); RL_LOAD(xe, 2); SB;
;     RL_FOLD(xa, 0, sm0, sq0); SB; RL_LOAD(xa, 3); SB;
;     RL_FOLD(xc, 1, sm0, sq0); SB; RL_LOAD(xc, 4); SB;
;     RL_FOLD(xe, 2, sm0, sq0); SB; RL_LOAD(xe, 5); SB;
;     RL_FOLD(xa, 3, sm0, sq0); SB; RL_LOAD(xa, 6); SB;
	v_mov_b32_e32 v184, v192
	s_waitcnt vmcnt(1)
	v_ashrrev_i32_e32 v130, 1, v184
	v_and_b32_e32 v223, 0xdf, v184
	v_and_b32_e32 v182, 0xffffff80, v130
	v_or_b32_e32 v0, s4, v223
	v_ashrrev_i32_e32 v183, 31, v182
	v_bfe_u32 v224, v184, 5, 1
	v_lshl_add_u64 v[130:131], v[182:183], 2, s[16:17]
	v_lshlrev_b64 v[132:133], 12, v[0:1]
	v_lshl_add_u64 v[130:131], v[130:131], 0, v[132:133]
	v_lshlrev_b32_e32 v132, 6, v224
	v_mov_b32_e32 v133, v1
	v_lshl_add_u64 v[186:187], v[130:131], 0, v[132:133]
	global_load_dwordx4 v[130:133], v[186:187], off offset:48
	global_load_dwordx4 v[134:137], v[186:187], off offset:32
	global_load_dwordx4 v[138:141], v[186:187], off offset:16
	global_load_dwordx4 v[142:145], v[186:187], off
	global_load_dwordx4 v[226:229], v[186:187], off offset:176
	global_load_dwordx4 v[230:233], v[186:187], off offset:160
	global_load_dwordx4 v[234:237], v[186:187], off offset:144
	global_load_dwordx4 v[146:149], v[186:187], off offset:128
	global_load_dwordx4 v[238:241], v[186:187], off offset:304
	global_load_dwordx4 v[242:245], v[186:187], off offset:288
	global_load_dwordx4 v[246:249], v[186:187], off offset:272
	global_load_dwordx4 v[250:253], v[186:187], off offset:256
	s_waitcnt vmcnt(8)
	v_pk_fma_f32 v[178:179], v[142:143], s[0:1], v[114:115] op_sel_hi:[1,0,1]
	v_pk_fma_f32 v[180:181], v[144:145], s[0:1], v[116:117] op_sel_hi:[1,0,1]
	v_add_f32_e32 v114, 0, v178
	v_add_f32_e32 v142, v179, v114
	v_mul_f32_e32 v114, v179, v179
	v_pk_fma_f32 v[114:115], v[178:179], v[178:179], v[114:115] op_sel_hi:[1,1,0]
	v_add_f32_e32 v116, v180, v142
	v_pk_fma_f32 v[114:115], v[180:181], v[180:181], v[114:115]
	v_add_f32_e32 v117, v181, v116
	v_mul_f32_e32 v116, v181, v181
	v_pk_fma_f32 v[158:159], v[138:139], s[0:1], v[118:119] op_sel_hi:[1,0,1]
	v_pk_add_f32 v[114:115], v[116:117], v[114:115] op_sel_hi:[0,1]
	v_add_f32_e32 v116, v158, v117
	v_pk_fma_f32 v[114:115], v[158:159], v[158:159], v[114:115]
	v_add_f32_e32 v117, v159, v116
	v_mul_f32_e32 v116, v159, v159
	v_pk_fma_f32 v[160:161], v[140:141], s[0:1], v[120:121] op_sel_hi:[1,0,1]
	v_pk_add_f32 v[114:115], v[116:117], v[114:115] op_sel_hi:[0,1]
	v_add_f32_e32 v116, v160, v117
	v_pk_fma_f32 v[114:115], v[160:161], v[160:161], v[114:115]
	v_add_f32_e32 v117, v161, v116
	v_mul_f32_e32 v116, v161, v161
	v_pk_fma_f32 v[154:155], v[134:135], s[0:1], v[122:123] op_sel_hi:[1,0,1]
	v_pk_add_f32 v[114:115], v[116:117], v[114:115] op_sel_hi:[0,1]
	v_add_f32_e32 v116, v154, v117
	v_pk_fma_f32 v[114:115], v[154:155], v[154:155], v[114:115]
	v_add_f32_e32 v117, v155, v116
	v_mul_f32_e32 v116, v155, v155
	v_pk_fma_f32 v[156:157], v[136:137], s[0:1], v[124:125] op_sel_hi:[1,0,1]
	v_pk_add_f32 v[114:115], v[116:117], v[114:115] op_sel_hi:[0,1]
	v_add_f32_e32 v116, v156, v117
	v_pk_fma_f32 v[114:115], v[156:157], v[156:157], v[114:115]
	v_add_f32_e32 v124, v157, v116
	v_mul_f32_e32 v116, v157, v157
	v_pk_add_f32 v[114:115], v[116:117], v[114:115] op_sel_hi:[0,1]
	v_pk_fma_f32 v[152:153], v[130:131], s[0:1], v[126:127] op_sel_hi:[1,0,1]
	v_pk_fma_f32 v[150:151], v[132:133], s[0:1], v[128:129] op_sel_hi:[1,0,1]
	v_pk_fma_f32 v[114:115], v[152:153], v[152:153], v[114:115]
	v_mul_f32_e32 v116, v153, v153
	v_pk_add_f32 v[114:115], v[116:117], v[114:115] op_sel_hi:[0,1]
	v_pk_fma_f32 v[114:115], v[150:151], v[150:151], v[114:115]
	v_mul_f32_e32 v116, v151, v151
	v_pk_add_f32 v[118:119], v[116:117], v[114:115] op_sel_hi:[0,1]
	global_load_dwordx4 v[114:117], v[186:187], off offset:432
	global_load_dwordx4 v[202:205], v[186:187], off offset:416
	global_load_dwordx4 v[194:197], v[186:187], off offset:400
	global_load_dwordx4 v[120:123], v[186:187], off offset:384
	v_add_f32_e32 v124, v152, v124
	v_add_f32_e32 v124, v153, v124
	v_add_f32_e32 v124, v150, v124
	v_add_f32_e32 v124, v151, v124
	s_waitcnt vmcnt(8)
	v_pk_fma_f32 v[144:145], v[146:147], s[0:1], v[98:99] op_sel_hi:[1,0,1]
	v_pk_fma_f32 v[148:149], v[148:149], s[0:1], v[100:101] op_sel_hi:[1,0,1]
	v_add_f32_e32 v124, v144, v124
	v_pk_fma_f32 v[98:99], v[144:145], v[144:145], v[118:119]
	v_add_f32_e32 v119, v145, v124
	v_mul_f32_e32 v118, v145, v145
	v_pk_add_f32 v[98:99], v[118:119], v[98:99] op_sel_hi:[0,1]
	v_add_f32_e32 v100, v148, v119
	v_pk_fma_f32 v[98:99], v[148:149], v[148:149], v[98:99]
	v_add_f32_e32 v101, v149, v100
	v_mul_f32_e32 v100, v149, v149
	v_pk_fma_f32 v[138:139], v[234:235], s[0:1], v[102:103] op_sel_hi:[1,0,1]
	v_pk_add_f32 v[98:99], v[100:101], v[98:99] op_sel_hi:[0,1]
	v_add_f32_e32 v100, v138, v101
	v_pk_fma_f32 v[98:99], v[138:139], v[138:139], v[98:99]
	v_add_f32_e32 v101, v139, v100
	v_mul_f32_e32 v100, v139, v139
	v_pk_fma_f32 v[146:147], v[236:237], s[0:1], v[104:105] op_sel_hi:[1,0,1]
	v_pk_add_f32 v[98:99], v[100:101], v[98:99] op_sel_hi:[0,1]
	v_add_f32_e32 v100, v146, v101
	v_pk_fma_f32 v[98:99], v[146:147], v[146:147], v[98:99]
	v_add_f32_e32 v101, v147, v100
	v_mul_f32_e32 v100, v147, v147
	v_pk_fma_f32 v[130:131], v[230:231], s[0:1], v[106:107] op_sel_hi:[1,0,1]
	v_pk_add_f32 v[98:99], v[100:101], v[98:99] op_sel_hi:[0,1]
	v_add_f32_e32 v100, v130, v101
	v_pk_fma_f32 v[98:99], v[130:131], v[130:131], v[98:99]
	v_add_f32_e32 v101, v131, v100
	v_mul_f32_e32 v100, v131, v131
	v_pk_fma_f32 v[140:141], v[232:233], s[0:1], v[108:109] op_sel_hi:[1,0,1]
	v_pk_add_f32 v[98:99], v[100:101], v[98:99] op_sel_hi:[0,1]
	v_add_f32_e32 v100, v140, v101
	v_pk_fma_f32 v[98:99], v[140:141], v[140:141], v[98:99]
	v_add_f32_e32 v106, v141, v100
	v_mul_f32_e32 v100, v141, v141
	v_pk_add_f32 v[102:103], v[100:101], v[98:99] op_sel_hi:[0,1]
	v_pk_fma_f32 v[124:125], v[226:227], s[0:1], v[110:111] op_sel_hi:[1,0,1]
	v_pk_fma_f32 v[134:135], v[228:229], s[0:1], v[112:113] op_sel_hi:[1,0,1]
	v_add_co_u32_e32 v188, vcc, s91, v186
	s_mov_b64 s[18:19], 0x20000
	s_nop 0
	v_addc_co_u32_e32 v189, vcc, 0, v187, vcc
	v_lshl_add_u64 v[104:105], v[186:187], 0, s[18:19]
	global_load_dwordx4 v[226:229], v[188:189], off
	global_load_dwordx4 v[98:101], v[104:105], off offset:48
	global_load_dwordx4 v[230:233], v[104:105], off offset:32
	global_load_dwordx4 v[234:237], v[104:105], off offset:16
	v_add_f32_e32 v104, v124, v106
	v_pk_fma_f32 v[102:103], v[124:125], v[124:125], v[102:103]
	v_add_f32_e32 v105, v125, v104
	v_mul_f32_e32 v104, v125, v125
	v_pk_add_f32 v[102:103], v[104:105], v[102:103] op_sel_hi:[0,1]
	v_add_f32_e32 v104, v134, v105
	v_pk_fma_f32 v[102:103], v[134:135], v[134:135], v[102:103]
	v_add_f32_e32 v105, v135, v104
	v_mul_f32_e32 v104, v135, v135
	v_pk_add_f32 v[102:103], v[104:105], v[102:103] op_sel_hi:[0,1]
	s_waitcnt vmcnt(8)
; #define RL_LOAD(XV, G) { constexpr int mt__ = (G) >> 2, half__ = ((G) >> 1) & 1, nt__ = (G) & 1; \
;     _Pragma("unroll") for (int gq = 0; gq < 4; ++gq) XV[gq] = *(const f32x4*)(xin + rbase + (size_t)mt__ * 32 * 1024 + half__ * 64 + nt__ * 32 + 4 * gq); }
; #define RL_FOLD(XV, G, SM, SQ) { constexpr int mt__ = (G) >> 2, half__ = ((G) >> 1) & 1, nt__ = (G) & 1; \
;     _Pragma("unroll") for (int gq = 0; gq < 4; ++gq) _Pragma("unroll") for (int jj = 0; jj < 4; ++jj) { \
;       const float y = ALPHA * XV[gq][jj] + acc[half__][nt__][mt__][4 * gq + jj]; acc[half__][nt__][mt__][4 * gq + jj] = y; SM += y; SQ += y * y; } }
; #define SB __builtin_amdgcn_sched_barrier(0)
;   DI void full(const int mt_, const int nt_, f32x16 (&acc)[2][2][2], const int tw, const int fw, const int r, const int hh, char* lds, const int tid) const {
;     ...
;     RL_LOAD(xa, 0); RL_LOAD(xc, 1); RL_LOAD(xe, 2); SB;
;     RL_FOLD(xa, 0, sm0, sq0); SB; RL_LOAD(xa, 3); SB;
;     RL_FOLD(xc, 1, sm0, sq0); SB; RL_LOAD(xc, 4); SB;
;     RL_FOLD(xe, 2, sm0, sq0); SB; RL_LOAD(xe, 5); SB;
;     RL_FOLD(xa, 3, sm0, sq0); SB; RL_LOAD(xa, 6); SB;
;     RL_FOLD(xc, 4, sm1, sq1); SB; RL_LOAD(xc, 7); SB;
;     RL_FOLD(xe, 5, sm1, sq1); SB;
;     RL_FOLD(xa, 6, sm1, sq1); SB;
;     RL_FOLD(xc, 7, sm1, sq1);
	v_pk_fma_f32 v[132:133], v[250:251], s[0:1], v[82:83] op_sel_hi:[1,0,1]
	v_pk_fma_f32 v[142:143], v[252:253], s[0:1], v[84:85] op_sel_hi:[1,0,1]
	v_add_f32_e32 v104, v132, v105
	v_pk_fma_f32 v[82:83], v[132:133], v[132:133], v[102:103]
	v_add_f32_e32 v103, v133, v104
	v_mul_f32_e32 v102, v133, v133
	v_pk_add_f32 v[82:83], v[102:103], v[82:83] op_sel_hi:[0,1]
	v_add_f32_e32 v84, v142, v103
	v_pk_fma_f32 v[82:83], v[142:143], v[142:143], v[82:83]
	v_add_f32_e32 v85, v143, v84
	v_mul_f32_e32 v84, v143, v143
	v_pk_fma_f32 v[126:127], v[246:247], s[0:1], v[86:87] op_sel_hi:[1,0,1]
	v_pk_add_f32 v[82:83], v[84:85], v[82:83] op_sel_hi:[0,1]
	v_add_f32_e32 v84, v126, v85
	v_pk_fma_f32 v[82:83], v[126:127], v[126:127], v[82:83]
	v_add_f32_e32 v85, v127, v84
	v_mul_f32_e32 v84, v127, v127
	v_pk_fma_f32 v[136:137], v[248:249], s[0:1], v[88:89] op_sel_hi:[1,0,1]
	v_pk_add_f32 v[82:83], v[84:85], v[82:83] op_sel_hi:[0,1]
	v_add_f32_e32 v84, v136, v85
	v_pk_fma_f32 v[82:83], v[136:137], v[136:137], v[82:83]
	v_add_f32_e32 v85, v137, v84
	v_mul_f32_e32 v84, v137, v137
	v_pk_fma_f32 v[112:113], v[242:243], s[0:1], v[90:91] op_sel_hi:[1,0,1]
	v_pk_add_f32 v[82:83], v[84:85], v[82:83] op_sel_hi:[0,1]
	v_add_f32_e32 v84, v112, v85
	v_pk_fma_f32 v[82:83], v[112:113], v[112:113], v[82:83]
	v_add_f32_e32 v85, v113, v84
	v_mul_f32_e32 v84, v113, v113
	v_pk_fma_f32 v[128:129], v[244:245], s[0:1], v[92:93] op_sel_hi:[1,0,1]
	v_pk_add_f32 v[82:83], v[84:85], v[82:83] op_sel_hi:[0,1]
	v_add_f32_e32 v84, v128, v85
	v_pk_fma_f32 v[82:83], v[128:129], v[128:129], v[82:83]
	v_add_f32_e32 v90, v129, v84
	v_mul_f32_e32 v84, v129, v129
	v_pk_add_f32 v[86:87], v[84:85], v[82:83] op_sel_hi:[0,1]
	v_pk_fma_f32 v[106:107], v[238:239], s[0:1], v[94:95] op_sel_hi:[1,0,1]
	v_pk_fma_f32 v[118:119], v[240:241], s[0:1], v[96:97] op_sel_hi:[1,0,1]
	s_mov_b64 s[18:19], 0x20080
	v_lshl_add_u64 v[88:89], v[186:187], 0, s[18:19]
	global_load_dwordx4 v[82:85], v[88:89], off offset:48
	global_load_dwordx4 v[238:241], v[88:89], off offset:32
	global_load_dwordx4 v[242:245], v[188:189], off offset:128
	global_load_dwordx4 v[246:249], v[88:89], off offset:16
	v_add_f32_e32 v88, v106, v90
	v_pk_fma_f32 v[86:87], v[106:107], v[106:107], v[86:87]
	v_add_f32_e32 v89, v107, v88
	v_mul_f32_e32 v88, v107, v107
	v_pk_add_f32 v[86:87], v[88:89], v[86:87] op_sel_hi:[0,1]
	v_add_f32_e32 v88, v118, v89
	v_pk_fma_f32 v[86:87], v[118:119], v[118:119], v[86:87]
	v_add_f32_e32 v89, v119, v88
	v_mul_f32_e32 v88, v119, v119
	v_pk_add_f32 v[86:87], v[88:89], v[86:87] op_sel_hi:[0,1]
	s_waitcnt vmcnt(8)
	v_pk_fma_f32 v[104:105], v[120:121], s[0:1], v[50:51] op_sel_hi:[1,0,1]
	v_pk_fma_f32 v[122:123], v[122:123], s[0:1], v[52:53] op_sel_hi:[1,0,1]
	v_add_f32_e32 v88, v104, v89
	v_pk_fma_f32 v[50:51], v[104:105], v[104:105], v[86:87]
	v_add_f32_e32 v87, v105, v88
	v_mul_f32_e32 v86, v105, v105
	v_add_f32_e32 v52, v122, v87
	v_pk_add_f32 v[50:51], v[86:87], v[50:51] op_sel_hi:[0,1]
	v_add_f32_e32 v52, v123, v52
	v_pk_fma_f32 v[102:103], v[194:195], s[0:1], v[54:55] op_sel_hi:[1,0,1]
	v_pk_fma_f32 v[50:51], v[122:123], v[122:123], v[50:51]
	v_add_f32_e32 v55, v102, v52
	v_mul_f32_e32 v54, v123, v123
	v_mov_b32_e32 v52, v102
	v_mov_b32_e32 v53, v123
	v_pk_add_f32 v[50:51], v[54:55], v[50:51] op_sel_hi:[0,1]
	v_pk_fma_f32 v[50:51], v[52:53], v[52:53], v[50:51]
	v_add_f32_e32 v52, v103, v55
	v_pk_fma_f32 v[120:121], v[196:197], s[0:1], v[56:57] op_sel_hi:[1,0,1]
	v_mul_f32_e32 v54, v103, v103
	v_add_f32_e32 v55, v120, v52
	v_mov_b32_e32 v52, v120
	v_mov_b32_e32 v53, v103
	v_pk_add_f32 v[50:51], v[54:55], v[50:51] op_sel_hi:[0,1]
	v_pk_fma_f32 v[50:51], v[52:53], v[52:53], v[50:51]
	v_add_f32_e32 v52, v121, v55
	v_pk_fma_f32 v[94:95], v[202:203], s[0:1], v[58:59] op_sel_hi:[1,0,1]
	v_mul_f32_e32 v54, v121, v121
	v_add_f32_e32 v55, v94, v52
	v_mov_b32_e32 v52, v94
	v_mov_b32_e32 v53, v121
	v_pk_add_f32 v[50:51], v[54:55], v[50:51] op_sel_hi:[0,1]
	v_pk_fma_f32 v[50:51], v[52:53], v[52:53], v[50:51]
	v_add_f32_e32 v52, v95, v55
	v_pk_fma_f32 v[108:109], v[204:205], s[0:1], v[60:61] op_sel_hi:[1,0,1]
	v_mul_f32_e32 v54, v95, v95
	v_add_f32_e32 v55, v108, v52
	v_mov_b32_e32 v52, v108
	v_mov_b32_e32 v53, v95
	v_pk_add_f32 v[50:51], v[54:55], v[50:51] op_sel_hi:[0,1]
	v_pk_fma_f32 v[50:51], v[52:53], v[52:53], v[50:51]
	v_pk_fma_f32 v[96:97], v[114:115], s[0:1], v[62:63] op_sel_hi:[1,0,1]
	v_mul_f32_e32 v54, v109, v109
	v_pk_fma_f32 v[110:111], v[116:117], s[0:1], v[64:65] op_sel_hi:[1,0,1]
	v_add_f32_e32 v58, v109, v55
	v_pk_add_f32 v[50:51], v[54:55], v[50:51] op_sel_hi:[0,1]
	v_mov_b32_e32 v54, v110
	v_mov_b32_e32 v55, v97
	v_mov_b32_e32 v52, v96
	v_mov_b32_e32 v53, v109
	v_pk_mul_f32 v[114:115], v[110:111], v[110:111]
	s_mov_b64 s[18:19], 0x20100
	v_lshl_add_u64 v[56:57], v[186:187], 0, s[18:19]
	global_load_dwordx4 v[194:197], v[56:57], off offset:48
	global_load_dwordx4 v[202:205], v[56:57], off offset:32
	global_load_dwordx4 v[250:253], v[188:189], off offset:256
	global_load_dwordx4 v[166:169], v[56:57], off offset:16
	v_add_f32_e32 v56, v96, v58
	v_add_f32_e32 v56, v97, v56
	v_add_f32_e32 v114, v110, v56
	s_waitcnt vmcnt(11)
	v_pk_fma_f32 v[90:91], v[226:227], s[0:1], v[66:67] op_sel_hi:[1,0,1]
	v_pk_fma_f32 v[92:93], v[228:229], s[0:1], v[68:69] op_sel_hi:[1,0,1]
	v_add_f32_e32 v56, 0, v90
	v_add_f32_e32 v58, v91, v56
	v_mul_f32_e32 v56, v91, v91
	v_pk_fma_f32 v[56:57], v[90:91], v[90:91], v[56:57] op_sel_hi:[1,1,0]
	v_add_f32_e32 v58, v92, v58
	v_pk_fma_f32 v[56:57], v[92:93], v[92:93], v[56:57]
	v_add_f32_e32 v59, v93, v58
	v_mul_f32_e32 v58, v93, v93
	s_waitcnt vmcnt(8)
; #define RL_LOAD(XV, G) { constexpr int mt__ = (G) >> 2, half__ = ((G) >> 1) & 1, nt__ = (G) & 1; \
;     _Pragma("unroll") for (int gq = 0; gq < 4; ++gq) XV[gq] = *(const f32x4*)(xin + rbase + (size_t)mt__ * 32 * 1024 + half__ * 64 + nt__ * 32 + 4 * gq); }
; #define RL_FOLD(XV, G, SM, SQ) { constexpr int mt__ = (G) >> 2, half__ = ((G) >> 1) & 1, nt__ = (G) & 1; \
;     _Pragma("unroll") for (int gq = 0; gq < 4; ++gq) _Pragma("unroll") for (int jj = 0; jj < 4; ++jj) { \
;       const float y = ALPHA * XV[gq][jj] + acc[half__][nt__][mt__][4 * gq + jj]; acc[half__][nt__][mt__][4 * gq + jj] = y; SM += y; SQ += y * y; } }
; #define SB __builtin_amdgcn_sched_barrier(0)
;   DI void full(const int mt_, const int nt_, f32x16 (&acc)[2][2][2], const int tw, const int fw, const int r, const int hh, char* lds, const int tid) const {
;     ...
;     RL_FOLD(xc, 1, sm0, sq0); SB; RL_LOAD(xc, 4); SB;
;     RL_FOLD(xe, 2, sm0, sq0); SB; RL_LOAD(xe, 5); SB;
;     RL_FOLD(xa, 3, sm0, sq0); SB; RL_LOAD(xa, 6); SB;
;     RL_FOLD(xc, 4, sm1, sq1); SB; RL_LOAD(xc, 7); SB;
;     RL_FOLD(xe, 5, sm1, sq1); SB;
;     RL_FOLD(xa, 6, sm1, sq1); SB;
;     RL_FOLD(xc, 7, sm1, sq1);
	v_pk_fma_f32 v[86:87], v[234:235], s[0:1], v[70:71] op_sel_hi:[1,0,1]
	v_pk_add_f32 v[56:57], v[58:59], v[56:57] op_sel_hi:[0,1]
	v_add_f32_e32 v58, v86, v59
	v_pk_fma_f32 v[56:57], v[86:87], v[86:87], v[56:57]
	v_add_f32_e32 v59, v87, v58
	v_mul_f32_e32 v58, v87, v87
	v_pk_fma_f32 v[88:89], v[236:237], s[0:1], v[72:73] op_sel_hi:[1,0,1]
	v_pk_add_f32 v[56:57], v[58:59], v[56:57] op_sel_hi:[0,1]
	v_add_f32_e32 v58, v88, v59
	v_pk_fma_f32 v[56:57], v[88:89], v[88:89], v[56:57]
	v_add_f32_e32 v59, v89, v58
	v_mul_f32_e32 v58, v89, v89
	v_pk_fma_f32 v[70:71], v[230:231], s[0:1], v[74:75] op_sel_hi:[1,0,1]
	v_pk_add_f32 v[56:57], v[58:59], v[56:57] op_sel_hi:[0,1]
	v_add_f32_e32 v58, v70, v59
	v_pk_fma_f32 v[56:57], v[70:71], v[70:71], v[56:57]
	v_add_f32_e32 v59, v71, v58
	v_mul_f32_e32 v58, v71, v71
	v_pk_fma_f32 v[72:73], v[232:233], s[0:1], v[76:77] op_sel_hi:[1,0,1]
	v_pk_add_f32 v[56:57], v[58:59], v[56:57] op_sel_hi:[0,1]
	v_add_f32_e32 v58, v72, v59
	v_pk_fma_f32 v[56:57], v[72:73], v[72:73], v[56:57]
	v_add_f32_e32 v59, v73, v58
	v_mul_f32_e32 v58, v73, v73
	v_pk_fma_f32 v[50:51], v[52:53], v[52:53], v[50:51]
	v_mul_f32_e32 v52, v97, v97
	v_pk_add_f32 v[56:57], v[58:59], v[56:57] op_sel_hi:[0,1]
	v_pk_fma_f32 v[68:69], v[98:99], s[0:1], v[78:79] op_sel_hi:[1,0,1]
	v_pk_fma_f32 v[66:67], v[100:101], s[0:1], v[80:81] op_sel_hi:[1,0,1]
	v_pk_add_f32 v[50:51], v[52:53], v[50:51] op_sel_hi:[0,1]
	v_pk_fma_f32 v[74:75], v[54:55], v[54:55], v[50:51]
	s_mov_b64 s[18:19], 0x20180
	v_lshl_add_u64 v[54:55], v[186:187], 0, s[18:19]
	global_load_dwordx4 v[50:53], v[54:55], off offset:48
	global_load_dwordx4 v[76:79], v[54:55], off offset:32
	global_load_dwordx4 v[98:101], v[188:189], off offset:384
	s_nop 0
	global_load_dwordx4 v[186:189], v[54:55], off offset:16
	v_add_f32_e32 v58, v68, v59
	v_pk_fma_f32 v[54:55], v[68:69], v[68:69], v[56:57]
	v_add_f32_e32 v57, v69, v58
	v_mul_f32_e32 v56, v69, v69
	v_pk_add_f32 v[54:55], v[56:57], v[54:55] op_sel_hi:[0,1]
	v_add_f32_e32 v56, v66, v57
	v_pk_fma_f32 v[54:55], v[66:67], v[66:67], v[54:55]
	v_add_f32_e32 v57, v67, v56
	v_mul_f32_e32 v56, v67, v67
	v_pk_add_f32 v[54:55], v[56:57], v[54:55] op_sel_hi:[0,1]
	s_waitcnt vmcnt(9)
	v_pk_fma_f32 v[60:61], v[242:243], s[0:1], v[34:35] op_sel_hi:[1,0,1]
	v_pk_fma_f32 v[64:65], v[244:245], s[0:1], v[36:37] op_sel_hi:[1,0,1]
	v_add_f32_e32 v56, v60, v57
	v_pk_fma_f32 v[34:35], v[60:61], v[60:61], v[54:55]
	v_add_f32_e32 v55, v61, v56
	v_mul_f32_e32 v54, v61, v61
	v_pk_add_f32 v[34:35], v[54:55], v[34:35] op_sel_hi:[0,1]
	v_add_f32_e32 v36, v64, v55
	v_pk_fma_f32 v[34:35], v[64:65], v[64:65], v[34:35]
	v_add_f32_e32 v37, v65, v36
	v_mul_f32_e32 v36, v65, v65
	s_waitcnt vmcnt(8)
	v_pk_fma_f32 v[56:57], v[246:247], s[0:1], v[38:39] op_sel_hi:[1,0,1]
	v_pk_add_f32 v[34:35], v[36:37], v[34:35] op_sel_hi:[0,1]
	v_add_f32_e32 v36, v56, v37
	v_pk_fma_f32 v[34:35], v[56:57], v[56:57], v[34:35]
	v_add_f32_e32 v37, v57, v36
	v_mul_f32_e32 v36, v57, v57
	v_pk_fma_f32 v[62:63], v[248:249], s[0:1], v[40:41] op_sel_hi:[1,0,1]
	v_pk_add_f32 v[34:35], v[36:37], v[34:35] op_sel_hi:[0,1]
	v_add_f32_e32 v36, v62, v37
	v_pk_fma_f32 v[34:35], v[62:63], v[62:63], v[34:35]
	v_add_f32_e32 v37, v63, v36
	v_mul_f32_e32 v36, v63, v63
	v_pk_fma_f32 v[54:55], v[238:239], s[0:1], v[42:43] op_sel_hi:[1,0,1]
	v_pk_add_f32 v[34:35], v[36:37], v[34:35] op_sel_hi:[0,1]
	v_add_f32_e32 v36, v54, v37
	v_pk_fma_f32 v[34:35], v[54:55], v[54:55], v[34:35]
	v_add_f32_e32 v37, v55, v36
	v_mul_f32_e32 v36, v55, v55
	v_pk_fma_f32 v[58:59], v[240:241], s[0:1], v[44:45] op_sel_hi:[1,0,1]
	v_pk_add_f32 v[34:35], v[36:37], v[34:35] op_sel_hi:[0,1]
	v_add_f32_e32 v36, v58, v37
	v_pk_fma_f32 v[34:35], v[58:59], v[58:59], v[34:35]
	v_add_f32_e32 v37, v59, v36
	v_mul_f32_e32 v36, v59, v59
	v_pk_fma_f32 v[44:45], v[82:83], s[0:1], v[46:47] op_sel_hi:[1,0,1]
	v_pk_add_f32 v[34:35], v[36:37], v[34:35] op_sel_hi:[0,1]
	v_add_f32_e32 v36, v44, v37
	v_pk_fma_f32 v[34:35], v[44:45], v[44:45], v[34:35]
	v_add_f32_e32 v37, v45, v36
	v_mul_f32_e32 v36, v45, v45
	v_pk_fma_f32 v[46:47], v[84:85], s[0:1], v[48:49] op_sel_hi:[1,0,1]
	v_pk_add_f32 v[34:35], v[36:37], v[34:35] op_sel_hi:[0,1]
	v_add_f32_e32 v36, v46, v37
	v_pk_fma_f32 v[34:35], v[46:47], v[46:47], v[34:35]
	v_add_f32_e32 v37, v47, v36
	v_mul_f32_e32 v36, v47, v47
	v_pk_add_f32 v[34:35], v[36:37], v[34:35] op_sel_hi:[0,1]
	s_waitcnt vmcnt(5)
	v_pk_fma_f32 v[38:39], v[250:251], s[0:1], v[18:19] op_sel_hi:[1,0,1]
	v_pk_fma_f32 v[42:43], v[252:253], s[0:1], v[20:21] op_sel_hi:[1,0,1]
	v_add_f32_e32 v36, v38, v37
	v_pk_fma_f32 v[18:19], v[38:39], v[38:39], v[34:35]
	v_add_f32_e32 v35, v39, v36
	v_mul_f32_e32 v34, v39, v39
	v_pk_add_f32 v[18:19], v[34:35], v[18:19] op_sel_hi:[0,1]
	v_add_f32_e32 v20, v42, v35
	v_pk_fma_f32 v[18:19], v[42:43], v[42:43], v[18:19]
	v_add_f32_e32 v21, v43, v20
	v_mul_f32_e32 v20, v43, v43
	s_waitcnt vmcnt(4)
; #define RL_FOLD(XV, G, SM, SQ) { constexpr int mt__ = (G) >> 2, half__ = ((G) >> 1) & 1, nt__ = (G) & 1; \
;     _Pragma("unroll") for (int gq = 0; gq < 4; ++gq) _Pragma("unroll") for (int jj = 0; jj < 4; ++jj) { \
;       const float y = ALPHA * XV[gq][jj] + acc[half__][nt__][mt__][4 * gq + jj]; acc[half__][nt__][mt__][4 * gq + jj] = y; SM += y; SQ += y * y; } }
;   DI void full(const int mt_, const int nt_, f32x16 (&acc)[2][2][2], const int tw, const int fw, const int r, const int hh, char* lds, const int tid) const {
;     ...
;     RL_FOLD(xc, 7, sm1, sq1);
;     ...
;     sm0 += __shfl_xor(sm0, 32, 64); sq0 += __shfl_xor(sq0, 32, 64); sm1 += __shfl_xor(sm1, 32, 64); sq1 += __shfl_xor(sq1, 32, 64);
;     if (hh == 0) {
;       float* pp = part + ((fw * 256) + tw * 64 + r) * 2; pp[0] = sm0; pp[1] = sq0;
;       pp[64] = sm1; pp[65] = sq1;
	v_pk_fma_f32 v[34:35], v[166:167], s[0:1], v[22:23] op_sel_hi:[1,0,1]
	v_pk_add_f32 v[18:19], v[20:21], v[18:19] op_sel_hi:[0,1]
	v_add_f32_e32 v20, v34, v21
	v_pk_fma_f32 v[18:19], v[34:35], v[34:35], v[18:19]
	v_add_f32_e32 v21, v35, v20
	v_mul_f32_e32 v20, v35, v35
	v_pk_fma_f32 v[40:41], v[168:169], s[0:1], v[24:25] op_sel_hi:[1,0,1]
	v_pk_add_f32 v[18:19], v[20:21], v[18:19] op_sel_hi:[0,1]
	v_add_f32_e32 v20, v40, v21
	v_pk_fma_f32 v[18:19], v[40:41], v[40:41], v[18:19]
	v_add_f32_e32 v21, v41, v20
	v_mul_f32_e32 v20, v41, v41
	v_pk_fma_f32 v[26:27], v[202:203], s[0:1], v[26:27] op_sel_hi:[1,0,1]
	v_pk_add_f32 v[18:19], v[20:21], v[18:19] op_sel_hi:[0,1]
	v_add_f32_e32 v20, v26, v21
	v_pk_fma_f32 v[18:19], v[26:27], v[26:27], v[18:19]
	v_add_f32_e32 v21, v27, v20
	v_mul_f32_e32 v20, v27, v27
	v_pk_fma_f32 v[36:37], v[204:205], s[0:1], v[28:29] op_sel_hi:[1,0,1]
	v_pk_add_f32 v[18:19], v[20:21], v[18:19] op_sel_hi:[0,1]
	v_add_f32_e32 v20, v36, v21
	v_pk_fma_f32 v[18:19], v[36:37], v[36:37], v[18:19]
	v_add_f32_e32 v21, v37, v20
	v_mul_f32_e32 v20, v37, v37
	v_pk_fma_f32 v[24:25], v[194:195], s[0:1], v[30:31] op_sel_hi:[1,0,1]
	v_pk_add_f32 v[18:19], v[20:21], v[18:19] op_sel_hi:[0,1]
	v_add_f32_e32 v20, v24, v21
	v_pk_fma_f32 v[18:19], v[24:25], v[24:25], v[18:19]
	v_add_f32_e32 v21, v25, v20
	v_mul_f32_e32 v20, v25, v25
	v_pk_fma_f32 v[28:29], v[196:197], s[0:1], v[32:33] op_sel_hi:[1,0,1]
	v_pk_add_f32 v[18:19], v[20:21], v[18:19] op_sel_hi:[0,1]
	v_add_f32_e32 v20, v28, v21
	v_pk_fma_f32 v[18:19], v[28:29], v[28:29], v[18:19]
	v_add_f32_e32 v22, v29, v20
	v_mul_f32_e32 v20, v29, v29
	v_pk_add_f32 v[20:21], v[20:21], v[18:19] op_sel_hi:[0,1]
	s_waitcnt vmcnt(1)
	v_pk_fma_f32 v[18:19], v[98:99], s[0:1], v[2:3] op_sel_hi:[1,0,1]
	s_waitcnt vmcnt(0)
	v_pk_fma_f32 v[6:7], v[186:187], s[0:1], v[6:7] op_sel_hi:[1,0,1]
	v_add_f32_e32 v22, v18, v22
	v_pk_fma_f32 v[2:3], v[18:19], v[18:19], v[20:21]
	v_add_f32_e32 v21, v19, v22
	v_pk_fma_f32 v[22:23], v[100:101], s[0:1], v[4:5] op_sel_hi:[1,0,1]
	v_mul_f32_e32 v20, v19, v19
	v_add_f32_e32 v4, v22, v21
	v_pk_add_f32 v[2:3], v[20:21], v[2:3] op_sel_hi:[0,1]
	v_add_f32_e32 v4, v23, v4
	v_pk_fma_f32 v[2:3], v[22:23], v[22:23], v[2:3]
	v_add_f32_e32 v21, v6, v4
	v_mul_f32_e32 v20, v23, v23
	v_mov_b32_e32 v4, v6
	v_mov_b32_e32 v5, v23
	v_pk_add_f32 v[2:3], v[20:21], v[2:3] op_sel_hi:[0,1]
	v_pk_fma_f32 v[2:3], v[4:5], v[4:5], v[2:3]
	v_add_f32_e32 v4, v7, v21
	v_pk_fma_f32 v[20:21], v[188:189], s[0:1], v[8:9] op_sel_hi:[1,0,1]
	v_mul_f32_e32 v8, v7, v7
	v_add_f32_e32 v9, v20, v4
	v_mov_b32_e32 v4, v20
	v_mov_b32_e32 v5, v7
	v_pk_add_f32 v[2:3], v[8:9], v[2:3] op_sel_hi:[0,1]
	v_pk_fma_f32 v[4:5], v[4:5], v[4:5], v[2:3]
	v_add_f32_e32 v8, v21, v9
	v_pk_fma_f32 v[2:3], v[76:77], s[0:1], v[10:11] op_sel_hi:[1,0,1]
	v_mul_f32_e32 v10, v21, v21
	v_add_f32_e32 v11, v2, v8
	v_mov_b32_e32 v8, v2
	v_mov_b32_e32 v9, v21
	v_pk_add_f32 v[4:5], v[10:11], v[4:5] op_sel_hi:[0,1]
	v_pk_fma_f32 v[4:5], v[8:9], v[8:9], v[4:5]
	v_add_f32_e32 v10, v3, v11
	v_pk_fma_f32 v[8:9], v[78:79], s[0:1], v[12:13] op_sel_hi:[1,0,1]
	v_mul_f32_e32 v12, v3, v3
	v_add_f32_e32 v13, v8, v10
	v_mov_b32_e32 v10, v8
	v_mov_b32_e32 v11, v3
	v_pk_add_f32 v[4:5], v[12:13], v[4:5] op_sel_hi:[0,1]
	v_pk_fma_f32 v[10:11], v[10:11], v[10:11], v[4:5]
	v_add_f32_e32 v12, v9, v13
	v_pk_fma_f32 v[4:5], v[50:51], s[0:1], v[14:15] op_sel_hi:[1,0,1]
	v_mul_f32_e32 v14, v9, v9
	v_add_f32_e32 v15, v4, v12
	v_mov_b32_e32 v12, v4
	v_mov_b32_e32 v13, v9
	v_pk_add_f32 v[10:11], v[14:15], v[10:11] op_sel_hi:[0,1]
	v_pk_fma_f32 v[12:13], v[12:13], v[12:13], v[10:11]
	v_pk_fma_f32 v[10:11], v[52:53], s[0:1], v[16:17] op_sel_hi:[1,0,1]
	v_mul_f32_e32 v30, v5, v5
	v_mov_b32_e32 v16, v10
	v_mov_b32_e32 v17, v5
	v_pk_add_f32 v[12:13], v[30:31], v[12:13] op_sel_hi:[0,1]
	v_pk_fma_f32 v[12:13], v[16:17], v[16:17], v[12:13]
	v_pk_mul_f32 v[16:17], v[10:11], v[10:11]
	v_add_f32_e32 v14, v5, v15
	v_mov_b32_e32 v15, v17
	v_and_b32_e32 v17, 64, v201
	v_xor_b32_e32 v16, 32, v201
	v_add_u32_e32 v17, 64, v17
	v_add_f32_e32 v14, v10, v14
	v_pk_mov_b32 v[12:13], v[10:11], v[12:13] op_sel:[1,0]
	v_cmp_lt_i32_e32 vcc, v16, v17
	v_pk_add_f32 v[12:13], v[12:13], v[14:15]
	v_pk_mov_b32 v[14:15], v[110:111], v[74:75] op_sel:[1,0]
	v_cndmask_b32_e32 v16, v201, v16, vcc
	v_pk_add_f32 v[14:15], v[14:15], v[114:115]
	v_lshlrev_b32_e32 v31, 2, v16
	ds_bpermute_b32 v16, v31, v14
	ds_bpermute_b32 v17, v31, v15
	ds_bpermute_b32 v30, v31, v12
	ds_bpermute_b32 v31, v31, v13
	v_cmp_eq_u32_e32 vcc, 0, v224
	s_and_saveexec_b64 s[18:19], vcc
	s_cbranch_execz .LBB0_704
	v_lshlrev_b32_e32 v32, 3, v184
	v_and_b32_e32 v32, 0xfffffef8, v32
	v_add_u32_e32 v32, 0, v32
	v_add_u32_e32 v32, 0x12000, v32
	s_waitcnt lgkmcnt(2)
	v_pk_add_f32 v[14:15], v[14:15], v[16:17]
	s_waitcnt lgkmcnt(0)
	v_pk_add_f32 v[12:13], v[12:13], v[30:31]
	ds_write2_b64 v32, v[14:15], v[12:13] offset1:32

; #define G_GLOAD(XR, WR, KT) { _Pragma("unroll") for (int i_ = 0; i_ < 4; ++i_) XR[i_] = *(const u32x4*)(Xt + ((size_t)(64 * i_) * ldx + (KT) * 64) * 2 + xoff); \
;     _Pragma("unroll") for (int i_ = 0; i_ < 4; ++i_) WR[i_] = *(const u32x4*)(Wtb + ((size_t)(64 * i_) * K + (KT) * 64) * 2 + woff); }
; #define G_LSTORE(XR, WR, STG) { char* xs_ = lds + (STG) * G_STAGE; char* ws_ = xs_ + G_XB; \
;     _Pragma("unroll") for (int i_ = 0; i_ < 4; ++i_) *(u32x4*)(xs_ + (lrow + 64 * i_) * LROW + lch * 16) = XR[i_]; \
;     _Pragma("unroll") for (int i_ = 0; i_ < 4; ++i_) *(u32x4*)(ws_ + (lrow + 64 * i_) * LROW + lch * 16) = WR[i_]; }
; template <class Epi>
; DI void gemm_phase(const bf16_t* __restrict__ X, const int ldx, const bf16_t* __restrict__ Wt, const int N, const int K, const Epi& epi, char* lds) {
;     ...
;     const int L = chunk * 32 + slot, band = L / (4 * nNt), rem = L % (4 * nNt);
;     const int mt_ = band * 4 + (rem & 3), nt_ = rem >> 2;
;     const char* Xt = (const char*)(X + (size_t)(mt_ * 256) * ldx);
;     const char* Wtb = (const char*)(Wt + (size_t)(nt_ * 256) * K);
;     const unsigned xoff = (unsigned)(lrow * ldx + lch * 8) * 2u, woff = (unsigned)(lrow * K + lch * 8) * 2u;
;     const bool has_next = !Epi::kFull && (chunk + 8 < nchunks);
;     const int Ln = (has_next ? chunk + 8 : chunk) * 32 + slot, band_n = Ln / (4 * nNt), rem_n = Ln % (4 * nNt);
;     const char* Xt_n = (const char*)(X + (size_t)((band_n * 4 + (rem_n & 3)) * 256) * ldx);
;     const char* Wtb_n = (const char*)(Wt + (size_t)((rem_n >> 2) * 256) * K);
;     f32x16 acc[2][2][2];
;     ...
;     asm volatile("" ::: "memory");
;     if (Epi::kFull || chunk == xcd) {
;       G_GLOAD(xr0, wr0, 0);
;       G_LSTORE(xr0, wr0, 0);
;       __syncthreads();
;       G_GLOAD(xr0, wr0, 1);
;     }
; #pragma unroll
;     for (int c = 0; c < 2; ++c)
; #pragma unroll
;       for (int a = 0; a < 2; ++a)
; #pragma unroll
;         for (int b = 0; b < 2; ++b)
; #pragma unroll
;           for (int i = 0; i < 16; ++i) acc[c][a][b][i] = 0.f;
.LBB0_768:
	s_lshl_b32 s2, s35, 5
	v_readlane_b32 s3, v254, 3
	s_add_i32 s2, s2, s3
	s_lshr_b32 s2, s2, 2
	s_and_b32 s2, s2, 0xffffffc
	s_or_b32 s36, s2, s90
	s_lshl_b32 s2, s36, 8
	s_mul_i32 s3, s36, 0x160000
	s_mul_hi_u32 s5, s2, 0x1600
	s_add_u32 s4, s31, s3
	s_addc_u32 s5, s34, s5
	v_lshl_add_u64 v[178:179], s[4:5], 0, v[162:163]
	v_add_co_u32_e32 v70, vcc, s93, v178
	s_mov_b64 s[18:19], 0xb0000
	s_nop 0
	v_addc_co_u32_e32 v71, vcc, 0, v179, vcc
	v_add_co_u32_e32 v72, vcc, s49, v178
	global_load_dwordx4 v[22:25], v[178:179], off
	global_load_dwordx4 v[26:29], v[70:71], off
	v_addc_co_u32_e32 v73, vcc, 0, v179, vcc
	global_load_dwordx4 v[30:33], v[72:73], off
	global_load_dwordx4 v[50:53], v[164:165], off
	global_load_dwordx4 v[54:57], v[198:199], off
	global_load_dwordx4 v[58:61], v[206:207], off
	global_load_dwordx4 v[62:65], v[170:171], off
	v_add_co_u32_e32 v74, vcc, s70, v178
	v_mov_b32_e32 v2, 0
	s_nop 0
	v_addc_co_u32_e32 v75, vcc, 0, v179, vcc
	global_load_dwordx4 v[66:69], v[74:75], off
	v_lshl_add_u64 v[180:181], v[178:179], 0, s[18:19]
	s_mov_b64 s[18:19], 0x108000
	s_mov_b32 s5, 0
	s_movk_i32 s3, 0x100
	v_mov_b32_e32 v3, v2
	v_mov_b64_e32 v[4:5], v[2:3]
	v_mov_b64_e32 v[6:7], v[2:3]
	v_mov_b64_e32 v[8:9], v[2:3]
	v_mov_b64_e32 v[10:11], v[2:3]
	v_mov_b64_e32 v[12:13], v[2:3]
	v_mov_b64_e32 v[14:15], v[2:3]
	v_mov_b64_e32 v[16:17], v[2:3]
	s_waitcnt vmcnt(13)
	v_mov_b64_e32 v[34:35], v[2:3]
	v_mov_b64_e32 v[36:37], v[2:3]
	s_waitcnt vmcnt(12)
	v_mov_b64_e32 v[38:39], v[2:3]
	v_mov_b64_e32 v[40:41], v[2:3]
	s_waitcnt vmcnt(11)
	v_mov_b64_e32 v[42:43], v[2:3]
	v_mov_b64_e32 v[44:45], v[2:3]
	s_waitcnt vmcnt(10)
	v_mov_b64_e32 v[46:47], v[2:3]
	v_mov_b64_e32 v[48:49], v[2:3]
	v_mov_b64_e32 v[18:19], v[2:3]
	v_mov_b64_e32 v[20:21], v[2:3]
	v_lshl_add_u64 v[182:183], v[178:179], 0, s[18:19]
	v_mov_b64_e32 v[82:83], v[2:3]
	v_mov_b64_e32 v[84:85], v[2:3]
	v_mov_b64_e32 v[86:87], v[2:3]
	v_mov_b64_e32 v[88:89], v[2:3]
	v_mov_b64_e32 v[90:91], v[2:3]
	v_mov_b64_e32 v[92:93], v[2:3]
	v_mov_b64_e32 v[94:95], v[2:3]
	v_mov_b64_e32 v[96:97], v[2:3]
	v_mov_b64_e32 v[98:99], v[2:3]
	v_mov_b64_e32 v[100:101], v[2:3]
	v_mov_b64_e32 v[102:103], v[2:3]
	s_waitcnt vmcnt(4)
	ds_write_b128 v224, v[50:53] offset:36864
	s_waitcnt vmcnt(3)
	ds_write_b128 v224, v[54:57] offset:46080
	s_waitcnt vmcnt(2)
	ds_write_b128 v224, v[58:61] offset:55296
	s_waitcnt vmcnt(1)
	ds_write_b128 v224, v[62:65] offset:64512
	ds_write_b128 v224, v[22:25]
	ds_write_b128 v224, v[30:33] offset:18432
	ds_write_b128 v224, v[26:29] offset:9216
	s_waitcnt vmcnt(0)
	ds_write_b128 v224, v[66:69] offset:27648
	s_waitcnt lgkmcnt(0)
	s_barrier
	global_load_dwordx4 v[130:133], v[174:175], off
	global_load_dwordx4 v[150:153], v[176:177], off
	global_load_dwordx4 v[158:161], v[172:173], off
	global_load_dwordx4 v[138:141], v[164:165], off offset:128
	global_load_dwordx4 v[146:149], v[74:75], off offset:128
	global_load_dwordx4 v[134:137], v[72:73], off offset:128
	global_load_dwordx4 v[154:157], v[70:71], off offset:128
	global_load_dwordx4 v[142:145], v[178:179], off offset:128
	v_mov_b64_e32 v[22:23], v[2:3]
	v_mov_b64_e32 v[24:25], v[2:3]
	v_mov_b64_e32 v[26:27], v[2:3]
	v_mov_b64_e32 v[28:29], v[2:3]
	v_mov_b64_e32 v[30:31], v[2:3]
	v_mov_b64_e32 v[32:33], v[2:3]
	v_mov_b64_e32 v[50:51], v[2:3]
	v_mov_b64_e32 v[52:53], v[2:3]
	v_mov_b64_e32 v[54:55], v[2:3]
	v_mov_b64_e32 v[56:57], v[2:3]
	v_mov_b64_e32 v[58:59], v[2:3]
	v_mov_b64_e32 v[60:61], v[2:3]
	v_mov_b64_e32 v[62:63], v[2:3]
	v_mov_b64_e32 v[64:65], v[2:3]
	v_mov_b64_e32 v[104:105], v[2:3]
	v_mov_b64_e32 v[106:107], v[2:3]
	v_mov_b64_e32 v[108:109], v[2:3]
	v_mov_b64_e32 v[110:111], v[2:3]
	v_mov_b64_e32 v[112:113], v[2:3]
	v_mov_b64_e32 v[66:67], v[2:3]
	v_mov_b64_e32 v[68:69], v[2:3]
	v_mov_b64_e32 v[70:71], v[2:3]
	v_mov_b64_e32 v[72:73], v[2:3]
	v_mov_b64_e32 v[74:75], v[2:3]
	v_mov_b64_e32 v[76:77], v[2:3]
	v_mov_b64_e32 v[78:79], v[2:3]
	v_mov_b64_e32 v[80:81], v[2:3]
	v_mov_b64_e32 v[114:115], v[2:3]
	v_mov_b32_e32 v116, v2
	v_mov_b32_e32 v117, v2
	v_mov_b32_e32 v118, v2
	v_mov_b32_e32 v119, v2
	v_mov_b32_e32 v120, v2
	v_mov_b32_e32 v121, v2
	v_mov_b32_e32 v122, v2
	v_mov_b32_e32 v123, v2
	v_mov_b32_e32 v124, v2
	v_mov_b32_e32 v125, v2
	v_mov_b32_e32 v126, v2
	v_mov_b32_e32 v127, v2
	v_mov_b32_e32 v128, v2
	v_mov_b32_e32 v129, v2
	v_readfirstlane_b32 vcc_lo, v162
	v_readfirstlane_b32 s98, v178
	v_readfirstlane_b32 s99, v179
	v_readfirstlane_b32 s100, v164
	v_readfirstlane_b32 s101, v165
	s_nop 4
	s_sub_u32 s98, s98, vcc_lo
	s_subb_u32 s99, s99, 0
	s_sub_u32 s100, s100, vcc_lo
	s_subb_u32 s101, s101, 0
	v_add_u32_e32 v179, s93, v162
	v_add_u32_e32 v181, s49, v162
	v_add_u32_e32 v183, s70, v162
	v_add_u32_e32 v178, v209, v210
	v_add_u32_e32 v180, v209, v211
	v_add_u32_e32 v182, v212, v208
.LBB0_769:
	ds_read_b128 v[166:169], v178
	ds_read_b128 v[184:187], v178 offset:4608
	ds_read_b128 v[188:191], v180 offset:36864
	ds_read_b128 v[194:197], v180 offset:41472
	ds_read_b128 v[202:205], v180 offset:46080
	ds_read_b128 v[226:229], v180 offset:50688
	ds_read_b128 v[230:233], v214 offset:32
	ds_read_b128 v[234:237], v214 offset:4640
	s_add_i32 s18, s5, 2
	s_cmp_lt_u32 s5, 42
	s_cselect_b32 s96, s3, 0x1580
	s_min_u32 s4, s5, 40
	s_lshl_b32 s4, s4, 7
	s_addk_i32 s3, 0x100
	s_cmp_gt_u32 s5, 41
	s_waitcnt lgkmcnt(5)
	v_mfma_f32_32x32x16_bf16 v[114:129], v[188:191], v[166:169], v[114:129]
	v_mfma_f32_32x32x16_bf16 v[66:81], v[188:191], v[184:187], v[66:81]
	s_waitcnt lgkmcnt(4)
	v_mfma_f32_32x32x16_bf16 v[98:113], v[194:197], v[166:169], v[98:113]
	v_mfma_f32_32x32x16_bf16 v[50:65], v[194:197], v[184:187], v[50:65]
	s_waitcnt lgkmcnt(3)
	v_mfma_f32_32x32x16_bf16 v[82:97], v[202:205], v[166:169], v[82:97]
	v_mfma_f32_32x32x16_bf16 v[18:33], v[202:205], v[184:187], v[18:33]
	s_waitcnt lgkmcnt(2)
	v_mfma_f32_32x32x16_bf16 v[34:49], v[226:229], v[166:169], v[34:49]
	ds_read_b128 v[166:169], v215 offset:36896
	ds_read_b128 v[188:191], v215 offset:41504
	v_mfma_f32_32x32x16_bf16 v[2:17], v[226:229], v[184:187], v[2:17]
	s_waitcnt vmcnt(1)
	ds_write_b128 v216, v[154:157] offset:9216
	s_waitcnt vmcnt(0)
	ds_write_b128 v216, v[142:145]
	s_add_u32 vcc_lo, s98, s96
	s_addc_u32 vcc_hi, s99, 0
	global_load_dwordx4 v[142:145], v162, vcc
	global_load_dwordx4 v[154:157], v179, vcc
	ds_write_b128 v216, v[134:137] offset:18432
	ds_write_b128 v216, v[146:149] offset:27648
	global_load_dwordx4 v[134:137], v181, vcc
	global_load_dwordx4 v[146:149], v183, vcc
	ds_read_b128 v[184:187], v215 offset:46112
	ds_read_b128 v[194:197], v215 offset:50720
	ds_read_b128 v[202:205], v214 offset:64
	ds_read_b128 v[226:229], v214 offset:4672
	s_waitcnt lgkmcnt(9)
	v_mfma_f32_32x32x16_bf16 v[114:129], v[166:169], v[230:233], v[114:129]
	v_mfma_f32_32x32x16_bf16 v[66:81], v[166:169], v[234:237], v[66:81]
	s_waitcnt lgkmcnt(8)
	v_mfma_f32_32x32x16_bf16 v[98:113], v[188:191], v[230:233], v[98:113]
	v_mfma_f32_32x32x16_bf16 v[50:65], v[188:191], v[234:237], v[50:65]
	s_waitcnt lgkmcnt(3)
	v_mfma_f32_32x32x16_bf16 v[82:97], v[184:187], v[230:233], v[82:97]
	v_mfma_f32_32x32x16_bf16 v[18:33], v[184:187], v[234:237], v[18:33]
	ds_read_b128 v[166:169], v215 offset:36928
	ds_read_b128 v[184:187], v215 offset:41536
	s_waitcnt lgkmcnt(4)
	v_mfma_f32_32x32x16_bf16 v[34:49], v[194:197], v[230:233], v[34:49]
	v_mfma_f32_32x32x16_bf16 v[2:17], v[194:197], v[234:237], v[2:17]
	ds_write_b128 v217, v[150:153] offset:9216
	ds_write_b128 v217, v[138:141]
	s_add_u32 vcc_lo, s100, s96
	s_addc_u32 vcc_hi, s101, 0
	global_load_dwordx4 v[138:141], v162, vcc
	global_load_dwordx4 v[150:153], v179, vcc
	ds_read_b128 v[188:191], v215 offset:46144
	ds_read_b128 v[194:197], v215 offset:50752
	ds_read_b128 v[230:233], v214 offset:96
	ds_read_b128 v[234:237], v214 offset:4704
	s_waitcnt lgkmcnt(7)
	v_mfma_f32_32x32x16_bf16 v[114:129], v[166:169], v[202:205], v[114:129]
	v_mfma_f32_32x32x16_bf16 v[66:81], v[166:169], v[226:229], v[66:81]
	s_waitcnt lgkmcnt(6)
	v_mfma_f32_32x32x16_bf16 v[98:113], v[184:187], v[202:205], v[98:113]
	v_mfma_f32_32x32x16_bf16 v[50:65], v[184:187], v[226:229], v[50:65]
	s_waitcnt lgkmcnt(3)
	v_mfma_f32_32x32x16_bf16 v[82:97], v[188:191], v[202:205], v[82:97]
	ds_read_b128 v[166:169], v215 offset:36960
	ds_read_b128 v[184:187], v215 offset:41568
	v_mfma_f32_32x32x16_bf16 v[18:33], v[188:191], v[226:229], v[18:33]
	s_waitcnt lgkmcnt(4)
	v_mfma_f32_32x32x16_bf16 v[34:49], v[194:197], v[202:205], v[34:49]
	v_mfma_f32_32x32x16_bf16 v[2:17], v[194:197], v[226:229], v[2:17]
	ds_write_b128 v217, v[130:133] offset:18432
	ds_write_b128 v217, v[158:161] offset:27648
	global_load_dwordx4 v[130:133], v181, vcc
	global_load_dwordx4 v[158:161], v183, vcc
	ds_read_b128 v[188:191], v215 offset:46176
	ds_read_b128 v[194:197], v215 offset:50784
	s_waitcnt lgkmcnt(5)
	v_mfma_f32_32x32x16_bf16 v[114:129], v[166:169], v[230:233], v[114:129]
	v_mfma_f32_32x32x16_bf16 v[66:81], v[166:169], v[234:237], v[66:81]
	s_waitcnt lgkmcnt(4)
	v_mfma_f32_32x32x16_bf16 v[98:113], v[184:187], v[230:233], v[98:113]
	v_mfma_f32_32x32x16_bf16 v[50:65], v[184:187], v[234:237], v[50:65]
	s_waitcnt lgkmcnt(1)
	v_mfma_f32_32x32x16_bf16 v[82:97], v[188:191], v[230:233], v[82:97]
	v_mfma_f32_32x32x16_bf16 v[18:33], v[188:191], v[234:237], v[18:33]
	s_waitcnt lgkmcnt(0)
	v_mfma_f32_32x32x16_bf16 v[34:49], v[194:197], v[230:233], v[34:49]
	v_mfma_f32_32x32x16_bf16 v[2:17], v[194:197], v[234:237], v[2:17]
	s_barrier
	ds_read_b128 v[166:169], v218
	ds_read_b128 v[184:187], v218 offset:4608
	ds_read_b128 v[188:191], v219
	ds_read_b128 v[194:197], v219 offset:4608
	ds_read_b128 v[202:205], v219 offset:9216
	ds_read_b128 v[226:229], v219 offset:13824
	ds_read_b128 v[230:233], v182 offset:32
	ds_read_b128 v[234:237], v220 offset:32
	s_waitcnt lgkmcnt(5)
	v_mfma_f32_32x32x16_bf16 v[114:129], v[188:191], v[166:169], v[114:129]
	v_mfma_f32_32x32x16_bf16 v[66:81], v[188:191], v[184:187], v[66:81]
	s_waitcnt lgkmcnt(4)
	v_mfma_f32_32x32x16_bf16 v[98:113], v[194:197], v[166:169], v[98:113]
	v_mfma_f32_32x32x16_bf16 v[50:65], v[194:197], v[184:187], v[50:65]
	s_waitcnt lgkmcnt(3)
	v_mfma_f32_32x32x16_bf16 v[82:97], v[202:205], v[166:169], v[82:97]
	v_add_u32_e32 v225, v213, v208
	v_mfma_f32_32x32x16_bf16 v[18:33], v[202:205], v[184:187], v[18:33]
	s_waitcnt lgkmcnt(2)
	v_mfma_f32_32x32x16_bf16 v[34:49], v[226:229], v[166:169], v[34:49]
	ds_read_b128 v[166:169], v225 offset:32
	ds_read_b128 v[188:191], v221 offset:32
	v_mfma_f32_32x32x16_bf16 v[2:17], v[226:229], v[184:187], v[2:17]
	s_mov_b32 s5, s97
	s_waitcnt vmcnt(6)
	ds_write_b128 v224, v[154:157] offset:9216
	ds_write_b128 v224, v[142:145]
	s_add_u32 vcc_lo, s98, s4
	s_addc_u32 vcc_hi, s99, 0
	global_load_dwordx4 v[142:145], v162, vcc offset:384
	global_load_dwordx4 v[154:157], v179, vcc offset:384
	s_waitcnt vmcnt(7)
	ds_write_b128 v224, v[134:137] offset:18432
	s_waitcnt vmcnt(6)
	ds_write_b128 v224, v[146:149] offset:27648
	global_load_dwordx4 v[134:137], v181, vcc offset:384
	global_load_dwordx4 v[146:149], v183, vcc offset:384
	ds_read_b128 v[184:187], v222 offset:32
	ds_read_b128 v[194:197], v223 offset:32
	ds_read_b128 v[202:205], v182 offset:64
	ds_read_b128 v[226:229], v220 offset:64
	s_waitcnt lgkmcnt(9)
	v_mfma_f32_32x32x16_bf16 v[114:129], v[166:169], v[230:233], v[114:129]
	v_mfma_f32_32x32x16_bf16 v[66:81], v[166:169], v[234:237], v[66:81]
	s_waitcnt lgkmcnt(8)
	v_mfma_f32_32x32x16_bf16 v[98:113], v[188:191], v[230:233], v[98:113]
	v_mfma_f32_32x32x16_bf16 v[50:65], v[188:191], v[234:237], v[50:65]
	s_waitcnt lgkmcnt(3)
	v_mfma_f32_32x32x16_bf16 v[82:97], v[184:187], v[230:233], v[82:97]
	v_mfma_f32_32x32x16_bf16 v[18:33], v[184:187], v[234:237], v[18:33]
	ds_read_b128 v[166:169], v225 offset:64
	ds_read_b128 v[184:187], v221 offset:64
	s_waitcnt lgkmcnt(4)
	v_mfma_f32_32x32x16_bf16 v[34:49], v[194:197], v[230:233], v[34:49]
	v_mfma_f32_32x32x16_bf16 v[2:17], v[194:197], v[234:237], v[2:17]
	s_waitcnt vmcnt(6)
	ds_write_b128 v224, v[150:153] offset:46080
	ds_write_b128 v224, v[138:141] offset:36864
	s_add_u32 vcc_lo, s100, s4
	s_addc_u32 vcc_hi, s101, 0
	global_load_dwordx4 v[138:141], v162, vcc offset:384
	global_load_dwordx4 v[150:153], v179, vcc offset:384
	ds_read_b128 v[188:191], v222 offset:64
	ds_read_b128 v[194:197], v223 offset:64
	ds_read_b128 v[230:233], v182 offset:96
	ds_read_b128 v[234:237], v220 offset:96
	s_waitcnt lgkmcnt(7)
	v_mfma_f32_32x32x16_bf16 v[114:129], v[166:169], v[202:205], v[114:129]
	v_mfma_f32_32x32x16_bf16 v[66:81], v[166:169], v[226:229], v[66:81]
	s_waitcnt lgkmcnt(6)
	v_mfma_f32_32x32x16_bf16 v[98:113], v[184:187], v[202:205], v[98:113]
	v_mfma_f32_32x32x16_bf16 v[50:65], v[184:187], v[226:229], v[50:65]
	s_waitcnt lgkmcnt(3)
	v_mfma_f32_32x32x16_bf16 v[82:97], v[188:191], v[202:205], v[82:97]
	ds_read_b128 v[166:169], v225 offset:96
	ds_read_b128 v[184:187], v221 offset:96
	v_mfma_f32_32x32x16_bf16 v[18:33], v[188:191], v[226:229], v[18:33]
	s_waitcnt lgkmcnt(4)
	v_mfma_f32_32x32x16_bf16 v[34:49], v[194:197], v[202:205], v[34:49]
	v_mfma_f32_32x32x16_bf16 v[2:17], v[194:197], v[226:229], v[2:17]
	s_waitcnt vmcnt(7)
	ds_write_b128 v224, v[130:133] offset:55296
	s_waitcnt vmcnt(6)
	ds_write_b128 v224, v[158:161] offset:64512
	global_load_dwordx4 v[130:133], v181, vcc offset:384
	global_load_dwordx4 v[158:161], v183, vcc offset:384
	ds_read_b128 v[188:191], v222 offset:96
	ds_read_b128 v[194:197], v223 offset:96
	s_waitcnt lgkmcnt(5)
	v_mfma_f32_32x32x16_bf16 v[114:129], v[166:169], v[230:233], v[114:129]
	v_mfma_f32_32x32x16_bf16 v[66:81], v[166:169], v[234:237], v[66:81]
	s_waitcnt lgkmcnt(4)
	v_mfma_f32_32x32x16_bf16 v[98:113], v[184:187], v[230:233], v[98:113]
	v_mfma_f32_32x32x16_bf16 v[50:65], v[184:187], v[234:237], v[50:65]
	s_waitcnt lgkmcnt(1)
	v_mfma_f32_32x32x16_bf16 v[82:97], v[188:191], v[230:233], v[82:97]
	v_mfma_f32_32x32x16_bf16 v[18:33], v[188:191], v[234:237], v[18:33]
	s_waitcnt lgkmcnt(0)
	v_mfma_f32_32x32x16_bf16 v[34:49], v[194:197], v[230:233], v[34:49]
	v_mfma_f32_32x32x16_bf16 v[2:17], v[194:197], v[234:237], v[2:17]
	s_mov_b32 s5, s18
	s_cmp_gt_u32 s5, 43
	s_barrier
	s_cbranch_scc0 .LBB0_769
; #define RL_LOAD(XV, G) { constexpr int mt__ = (G) >> 2, half__ = ((G) >> 1) & 1, nt__ = (G) & 1; \
;     _Pragma("unroll") for (int gq = 0; gq < 4; ++gq) XV[gq] = *(const f32x4*)(xin + rbase + (size_t)mt__ * 32 * 1024 + half__ * 64 + nt__ * 32 + 4 * gq); }
; #define RL_FOLD(XV, G, SM, SQ) { constexpr int mt__ = (G) >> 2, half__ = ((G) >> 1) & 1, nt__ = (G) & 1; \
;     _Pragma("unroll") for (int gq = 0; gq < 4; ++gq) _Pragma("unroll") for (int jj = 0; jj < 4; ++jj) { \
;       const float y = ALPHA * XV[gq][jj] + acc[half__][nt__][mt__][4 * gq + jj]; acc[half__][nt__][mt__][4 * gq + jj] = y; SM += y; SQ += y * y; } }
; #define SB __builtin_amdgcn_sched_barrier(0)
;   DI void full(const int mt_, const int nt_, f32x16 (&acc)[2][2][2], const int tw, const int fw, const int r, const int hh, char* lds, const int tid) const {
;     float* part = (float*)(lds + G_STAGE);
;     const size_t rbase = (size_t)(mt_ * 256 + tw * 64 + r) * 1024 + nt_ * 256 + fw * 128 + 16 * hh;
;     f32x4 xa[4], xc[4], xe[4];
;     ...
;     float sm0 = 0.f, sq0 = 0.f, sm1 = 0.f, sq1 = 0.f;
;     RL_LOAD(xa, 0); RL_LOAD(xc, 1); RL_LOAD(xe, 2); SB;
;     RL_FOLD(xa, 0, sm0, sq0); SB; RL_LOAD(xa, 3); SB;
;     RL_FOLD(xc, 1, sm0, sq0); SB; RL_LOAD(xc, 4); SB;
;     RL_FOLD(xe, 2, sm0, sq0); SB; RL_LOAD(xe, 5); SB;
;     RL_FOLD(xa, 3, sm0, sq0); SB; RL_LOAD(xa, 6); SB;
	v_mov_b32_e32 v186, v192
	s_waitcnt vmcnt(1)
	v_ashrrev_i32_e32 v130, 1, v186
	v_and_b32_e32 v225, 0xdf, v186
	v_and_b32_e32 v184, 0xffffff80, v130
	v_or_b32_e32 v0, s2, v225
	v_ashrrev_i32_e32 v185, 31, v184
	v_bfe_u32 v226, v186, 5, 1
	v_lshl_add_u64 v[130:131], v[184:185], 2, s[16:17]
	v_lshlrev_b64 v[132:133], 12, v[0:1]
	v_lshl_add_u64 v[130:131], v[130:131], 0, v[132:133]
	v_lshlrev_b32_e32 v132, 6, v226
	v_mov_b32_e32 v133, v1
	v_lshl_add_u64 v[188:189], v[130:131], 0, v[132:133]
	global_load_dwordx4 v[130:133], v[188:189], off offset:48
	global_load_dwordx4 v[134:137], v[188:189], off offset:32
	global_load_dwordx4 v[138:141], v[188:189], off offset:16
	global_load_dwordx4 v[142:145], v[188:189], off
	global_load_dwordx4 v[194:197], v[188:189], off offset:176
	global_load_dwordx4 v[202:205], v[188:189], off offset:160
	global_load_dwordx4 v[228:231], v[188:189], off offset:144
	global_load_dwordx4 v[146:149], v[188:189], off offset:128
	global_load_dwordx4 v[232:235], v[188:189], off offset:304
	global_load_dwordx4 v[236:239], v[188:189], off offset:288
	global_load_dwordx4 v[240:243], v[188:189], off offset:272
	global_load_dwordx4 v[244:247], v[188:189], off offset:256
	s_waitcnt vmcnt(8)
	v_pk_fma_f32 v[180:181], v[142:143], s[0:1], v[114:115] op_sel_hi:[1,0,1]
	v_pk_fma_f32 v[182:183], v[144:145], s[0:1], v[116:117] op_sel_hi:[1,0,1]
	v_add_f32_e32 v114, 0, v180
	v_add_f32_e32 v142, v181, v114
	v_mul_f32_e32 v114, v181, v181
	v_pk_fma_f32 v[114:115], v[180:181], v[180:181], v[114:115] op_sel_hi:[1,1,0]
	v_add_f32_e32 v116, v182, v142
	v_pk_fma_f32 v[114:115], v[182:183], v[182:183], v[114:115]
	v_add_f32_e32 v117, v183, v116
	v_mul_f32_e32 v116, v183, v183
	v_pk_fma_f32 v[160:161], v[138:139], s[0:1], v[118:119] op_sel_hi:[1,0,1]
	v_pk_add_f32 v[114:115], v[116:117], v[114:115] op_sel_hi:[0,1]
	v_add_f32_e32 v116, v160, v117
	v_pk_fma_f32 v[114:115], v[160:161], v[160:161], v[114:115]
	v_add_f32_e32 v117, v161, v116
	v_mul_f32_e32 v116, v161, v161
	v_pk_fma_f32 v[178:179], v[140:141], s[0:1], v[120:121] op_sel_hi:[1,0,1]
	v_pk_add_f32 v[114:115], v[116:117], v[114:115] op_sel_hi:[0,1]
	v_add_f32_e32 v116, v178, v117
	v_pk_fma_f32 v[114:115], v[178:179], v[178:179], v[114:115]
	v_add_f32_e32 v117, v179, v116
	v_mul_f32_e32 v116, v179, v179
	v_pk_fma_f32 v[156:157], v[134:135], s[0:1], v[122:123] op_sel_hi:[1,0,1]
	v_pk_add_f32 v[114:115], v[116:117], v[114:115] op_sel_hi:[0,1]
	v_add_f32_e32 v116, v156, v117
	v_pk_fma_f32 v[114:115], v[156:157], v[156:157], v[114:115]
	v_add_f32_e32 v117, v157, v116
	v_mul_f32_e32 v116, v157, v157
	v_pk_fma_f32 v[158:159], v[136:137], s[0:1], v[124:125] op_sel_hi:[1,0,1]
	v_pk_add_f32 v[114:115], v[116:117], v[114:115] op_sel_hi:[0,1]
	v_add_f32_e32 v116, v158, v117
	v_pk_fma_f32 v[114:115], v[158:159], v[158:159], v[114:115]
	v_add_f32_e32 v120, v159, v116
	v_mul_f32_e32 v116, v159, v159
	v_pk_add_f32 v[114:115], v[116:117], v[114:115] op_sel_hi:[0,1]
	v_pk_fma_f32 v[154:155], v[130:131], s[0:1], v[126:127] op_sel_hi:[1,0,1]
	v_pk_fma_f32 v[152:153], v[132:133], s[0:1], v[128:129] op_sel_hi:[1,0,1]
	v_pk_fma_f32 v[114:115], v[154:155], v[154:155], v[114:115]
	v_mul_f32_e32 v116, v155, v155
	v_pk_add_f32 v[114:115], v[116:117], v[114:115] op_sel_hi:[0,1]
	v_pk_fma_f32 v[114:115], v[152:153], v[152:153], v[114:115]
	v_mul_f32_e32 v116, v153, v153
	v_pk_add_f32 v[118:119], v[116:117], v[114:115] op_sel_hi:[0,1]
	global_load_dwordx4 v[114:117], v[188:189], off offset:432
	global_load_dwordx4 v[248:251], v[188:189], off offset:416
	global_load_dwordx4 v[166:169], v[188:189], off offset:400
	global_load_dwordx4 v[122:125], v[188:189], off offset:384
	v_add_f32_e32 v120, v154, v120
	v_add_f32_e32 v120, v155, v120
	v_add_f32_e32 v120, v152, v120
	v_add_f32_e32 v120, v153, v120
	s_waitcnt vmcnt(8)
	v_pk_fma_f32 v[146:147], v[146:147], s[0:1], v[98:99] op_sel_hi:[1,0,1]
	v_pk_fma_f32 v[150:151], v[148:149], s[0:1], v[100:101] op_sel_hi:[1,0,1]
	v_add_f32_e32 v120, v146, v120
	v_pk_fma_f32 v[98:99], v[146:147], v[146:147], v[118:119]
	v_add_f32_e32 v119, v147, v120
	v_mul_f32_e32 v118, v147, v147
	v_pk_add_f32 v[98:99], v[118:119], v[98:99] op_sel_hi:[0,1]
	v_add_f32_e32 v100, v150, v119
	v_pk_fma_f32 v[98:99], v[150:151], v[150:151], v[98:99]
	v_add_f32_e32 v101, v151, v100
	v_mul_f32_e32 v100, v151, v151
	v_pk_fma_f32 v[140:141], v[228:229], s[0:1], v[102:103] op_sel_hi:[1,0,1]
	v_pk_add_f32 v[98:99], v[100:101], v[98:99] op_sel_hi:[0,1]
	v_add_f32_e32 v100, v140, v101
	v_pk_fma_f32 v[98:99], v[140:141], v[140:141], v[98:99]
	v_add_f32_e32 v101, v141, v100
	v_mul_f32_e32 v100, v141, v141
	v_pk_fma_f32 v[148:149], v[230:231], s[0:1], v[104:105] op_sel_hi:[1,0,1]
	v_pk_add_f32 v[98:99], v[100:101], v[98:99] op_sel_hi:[0,1]
	v_add_f32_e32 v100, v148, v101
	v_pk_fma_f32 v[98:99], v[148:149], v[148:149], v[98:99]
	v_add_f32_e32 v101, v149, v100
	v_mul_f32_e32 v100, v149, v149
	v_pk_fma_f32 v[132:133], v[202:203], s[0:1], v[106:107] op_sel_hi:[1,0,1]
	v_pk_add_f32 v[98:99], v[100:101], v[98:99] op_sel_hi:[0,1]
	v_add_f32_e32 v100, v132, v101
	v_pk_fma_f32 v[98:99], v[132:133], v[132:133], v[98:99]
	v_add_f32_e32 v101, v133, v100
	v_mul_f32_e32 v100, v133, v133
	v_pk_fma_f32 v[142:143], v[204:205], s[0:1], v[108:109] op_sel_hi:[1,0,1]
	v_pk_add_f32 v[98:99], v[100:101], v[98:99] op_sel_hi:[0,1]
	v_add_f32_e32 v100, v142, v101
	v_pk_fma_f32 v[98:99], v[142:143], v[142:143], v[98:99]
	v_add_f32_e32 v106, v143, v100
	v_mul_f32_e32 v100, v143, v143
	v_pk_add_f32 v[102:103], v[100:101], v[98:99] op_sel_hi:[0,1]
	v_pk_fma_f32 v[126:127], v[194:195], s[0:1], v[110:111] op_sel_hi:[1,0,1]
	v_pk_fma_f32 v[136:137], v[196:197], s[0:1], v[112:113] op_sel_hi:[1,0,1]
	v_add_co_u32_e32 v190, vcc, s91, v188
	s_mov_b64 s[4:5], 0x20000
	s_nop 0
	v_addc_co_u32_e32 v191, vcc, 0, v189, vcc
	v_lshl_add_u64 v[104:105], v[188:189], 0, s[4:5]
	global_load_dwordx4 v[194:197], v[190:191], off
	global_load_dwordx4 v[98:101], v[104:105], off offset:48
	global_load_dwordx4 v[202:205], v[104:105], off offset:32
	global_load_dwordx4 v[228:231], v[104:105], off offset:16
	v_add_f32_e32 v104, v126, v106
	v_pk_fma_f32 v[102:103], v[126:127], v[126:127], v[102:103]
	v_add_f32_e32 v105, v127, v104
	v_mul_f32_e32 v104, v127, v127
	v_pk_add_f32 v[102:103], v[104:105], v[102:103] op_sel_hi:[0,1]
	v_add_f32_e32 v104, v136, v105
	v_pk_fma_f32 v[102:103], v[136:137], v[136:137], v[102:103]
	v_add_f32_e32 v105, v137, v104
	v_mul_f32_e32 v104, v137, v137
	v_pk_add_f32 v[102:103], v[104:105], v[102:103] op_sel_hi:[0,1]
	s_waitcnt vmcnt(8)
; #define RL_LOAD(XV, G) { constexpr int mt__ = (G) >> 2, half__ = ((G) >> 1) & 1, nt__ = (G) & 1; \
;     _Pragma("unroll") for (int gq = 0; gq < 4; ++gq) XV[gq] = *(const f32x4*)(xin + rbase + (size_t)mt__ * 32 * 1024 + half__ * 64 + nt__ * 32 + 4 * gq); }
; #define RL_FOLD(XV, G, SM, SQ) { constexpr int mt__ = (G) >> 2, half__ = ((G) >> 1) & 1, nt__ = (G) & 1; \
;     _Pragma("unroll") for (int gq = 0; gq < 4; ++gq) _Pragma("unroll") for (int jj = 0; jj < 4; ++jj) { \
;       const float y = ALPHA * XV[gq][jj] + acc[half__][nt__][mt__][4 * gq + jj]; acc[half__][nt__][mt__][4 * gq + jj] = y; SM += y; SQ += y * y; } }
; #define SB __builtin_amdgcn_sched_barrier(0)
;   DI void full(const int mt_, const int nt_, f32x16 (&acc)[2][2][2], const int tw, const int fw, const int r, const int hh, char* lds, const int tid) const {
;     ...
;     RL_LOAD(xa, 0); RL_LOAD(xc, 1); RL_LOAD(xe, 2); SB;
;     RL_FOLD(xa, 0, sm0, sq0); SB; RL_LOAD(xa, 3); SB;
;     RL_FOLD(xc, 1, sm0, sq0); SB; RL_LOAD(xc, 4); SB;
;     RL_FOLD(xe, 2, sm0, sq0); SB; RL_LOAD(xe, 5); SB;
;     RL_FOLD(xa, 3, sm0, sq0); SB; RL_LOAD(xa, 6); SB;
;     RL_FOLD(xc, 4, sm1, sq1); SB; RL_LOAD(xc, 7); SB;
;     RL_FOLD(xe, 5, sm1, sq1); SB;
;     RL_FOLD(xa, 6, sm1, sq1); SB;
;     RL_FOLD(xc, 7, sm1, sq1);
	v_pk_fma_f32 v[134:135], v[244:245], s[0:1], v[82:83] op_sel_hi:[1,0,1]
	v_pk_fma_f32 v[144:145], v[246:247], s[0:1], v[84:85] op_sel_hi:[1,0,1]
	v_add_f32_e32 v104, v134, v105
	v_pk_fma_f32 v[82:83], v[134:135], v[134:135], v[102:103]
	v_add_f32_e32 v103, v135, v104
	v_mul_f32_e32 v102, v135, v135
	v_pk_add_f32 v[82:83], v[102:103], v[82:83] op_sel_hi:[0,1]
	v_add_f32_e32 v84, v144, v103
	v_pk_fma_f32 v[82:83], v[144:145], v[144:145], v[82:83]
	v_add_f32_e32 v85, v145, v84
	v_mul_f32_e32 v84, v145, v145
	v_pk_fma_f32 v[128:129], v[240:241], s[0:1], v[86:87] op_sel_hi:[1,0,1]
	v_pk_add_f32 v[82:83], v[84:85], v[82:83] op_sel_hi:[0,1]
	v_add_f32_e32 v84, v128, v85
	v_pk_fma_f32 v[82:83], v[128:129], v[128:129], v[82:83]
	v_add_f32_e32 v85, v129, v84
	v_mul_f32_e32 v84, v129, v129
	v_pk_fma_f32 v[138:139], v[242:243], s[0:1], v[88:89] op_sel_hi:[1,0,1]
	v_pk_add_f32 v[82:83], v[84:85], v[82:83] op_sel_hi:[0,1]
	v_add_f32_e32 v84, v138, v85
	v_pk_fma_f32 v[82:83], v[138:139], v[138:139], v[82:83]
	v_add_f32_e32 v85, v139, v84
	v_mul_f32_e32 v84, v139, v139
	v_pk_fma_f32 v[118:119], v[236:237], s[0:1], v[90:91] op_sel_hi:[1,0,1]
	v_pk_add_f32 v[82:83], v[84:85], v[82:83] op_sel_hi:[0,1]
	v_add_f32_e32 v84, v118, v85
	v_pk_fma_f32 v[82:83], v[118:119], v[118:119], v[82:83]
	v_add_f32_e32 v85, v119, v84
	v_mul_f32_e32 v84, v119, v119
	v_pk_fma_f32 v[130:131], v[238:239], s[0:1], v[92:93] op_sel_hi:[1,0,1]
	v_pk_add_f32 v[82:83], v[84:85], v[82:83] op_sel_hi:[0,1]
	v_add_f32_e32 v84, v130, v85
	v_pk_fma_f32 v[82:83], v[130:131], v[130:131], v[82:83]
	v_add_f32_e32 v90, v131, v84
	v_mul_f32_e32 v84, v131, v131
	v_pk_add_f32 v[86:87], v[84:85], v[82:83] op_sel_hi:[0,1]
	v_pk_fma_f32 v[108:109], v[232:233], s[0:1], v[94:95] op_sel_hi:[1,0,1]
	v_pk_fma_f32 v[120:121], v[234:235], s[0:1], v[96:97] op_sel_hi:[1,0,1]
	s_mov_b64 s[4:5], 0x20080
	v_lshl_add_u64 v[88:89], v[188:189], 0, s[4:5]
	global_load_dwordx4 v[82:85], v[88:89], off offset:48
	global_load_dwordx4 v[232:235], v[88:89], off offset:32
	global_load_dwordx4 v[236:239], v[190:191], off offset:128
	global_load_dwordx4 v[240:243], v[88:89], off offset:16
	v_add_f32_e32 v88, v108, v90
	v_pk_fma_f32 v[86:87], v[108:109], v[108:109], v[86:87]
	v_add_f32_e32 v89, v109, v88
	v_mul_f32_e32 v88, v109, v109
	v_pk_add_f32 v[86:87], v[88:89], v[86:87] op_sel_hi:[0,1]
	v_add_f32_e32 v88, v120, v89
	v_pk_fma_f32 v[86:87], v[120:121], v[120:121], v[86:87]
	v_add_f32_e32 v89, v121, v88
	v_mul_f32_e32 v88, v121, v121
	v_pk_add_f32 v[86:87], v[88:89], v[86:87] op_sel_hi:[0,1]
	s_waitcnt vmcnt(8)
	v_pk_fma_f32 v[106:107], v[122:123], s[0:1], v[34:35] op_sel_hi:[1,0,1]
	v_pk_fma_f32 v[124:125], v[124:125], s[0:1], v[36:37] op_sel_hi:[1,0,1]
	v_add_f32_e32 v88, v106, v89
	v_pk_fma_f32 v[34:35], v[106:107], v[106:107], v[86:87]
	v_add_f32_e32 v87, v107, v88
	v_mul_f32_e32 v86, v107, v107
	v_add_f32_e32 v36, v124, v87
	v_pk_add_f32 v[34:35], v[86:87], v[34:35] op_sel_hi:[0,1]
	v_add_f32_e32 v36, v125, v36
	v_pk_fma_f32 v[104:105], v[166:167], s[0:1], v[38:39] op_sel_hi:[1,0,1]
	v_pk_fma_f32 v[34:35], v[124:125], v[124:125], v[34:35]
	v_add_f32_e32 v39, v104, v36
	v_mul_f32_e32 v38, v125, v125
	v_mov_b32_e32 v36, v104
	v_mov_b32_e32 v37, v125
	v_pk_add_f32 v[34:35], v[38:39], v[34:35] op_sel_hi:[0,1]
	v_pk_fma_f32 v[34:35], v[36:37], v[36:37], v[34:35]
	v_add_f32_e32 v36, v105, v39
	v_pk_fma_f32 v[122:123], v[168:169], s[0:1], v[40:41] op_sel_hi:[1,0,1]
	v_mul_f32_e32 v38, v105, v105
	v_add_f32_e32 v39, v122, v36
	v_mov_b32_e32 v36, v122
	v_mov_b32_e32 v37, v105
	v_pk_add_f32 v[34:35], v[38:39], v[34:35] op_sel_hi:[0,1]
	v_pk_fma_f32 v[34:35], v[36:37], v[36:37], v[34:35]
	v_add_f32_e32 v36, v123, v39
	v_pk_fma_f32 v[96:97], v[248:249], s[0:1], v[42:43] op_sel_hi:[1,0,1]
	v_mul_f32_e32 v38, v123, v123
	v_add_f32_e32 v39, v96, v36
	v_mov_b32_e32 v36, v96
	v_mov_b32_e32 v37, v123
	v_pk_add_f32 v[34:35], v[38:39], v[34:35] op_sel_hi:[0,1]
	v_pk_fma_f32 v[34:35], v[36:37], v[36:37], v[34:35]
	v_add_f32_e32 v36, v97, v39
	v_pk_fma_f32 v[110:111], v[250:251], s[0:1], v[44:45] op_sel_hi:[1,0,1]
	v_mul_f32_e32 v38, v97, v97
	v_add_f32_e32 v39, v110, v36
	v_mov_b32_e32 v36, v110
	v_mov_b32_e32 v37, v97
	v_pk_add_f32 v[34:35], v[38:39], v[34:35] op_sel_hi:[0,1]
	v_pk_fma_f32 v[102:103], v[114:115], s[0:1], v[46:47] op_sel_hi:[1,0,1]
	v_pk_fma_f32 v[112:113], v[116:117], s[0:1], v[48:49] op_sel_hi:[1,0,1]
	v_pk_fma_f32 v[34:35], v[36:37], v[36:37], v[34:35]
	v_add_f32_e32 v86, v111, v39
	v_mul_f32_e32 v38, v111, v111
	v_mov_b32_e32 v42, v112
	v_mov_b32_e32 v43, v103
	v_mov_b32_e32 v36, v102
	v_mov_b32_e32 v37, v111
	v_pk_add_f32 v[34:35], v[38:39], v[34:35] op_sel_hi:[0,1]
	v_pk_mul_f32 v[114:115], v[112:113], v[112:113]
	s_mov_b64 s[4:5], 0x20100
	v_lshl_add_u64 v[44:45], v[188:189], 0, s[4:5]
	global_load_dwordx4 v[166:169], v[44:45], off offset:48
	global_load_dwordx4 v[244:247], v[44:45], off offset:32
	global_load_dwordx4 v[38:41], v[190:191], off offset:256
	global_load_dwordx4 v[248:251], v[44:45], off offset:16
	v_add_f32_e32 v44, v102, v86
	v_add_f32_e32 v44, v103, v44
	v_add_f32_e32 v114, v112, v44
	s_waitcnt vmcnt(11)
	v_pk_fma_f32 v[92:93], v[194:195], s[0:1], v[66:67] op_sel_hi:[1,0,1]
	v_pk_fma_f32 v[94:95], v[196:197], s[0:1], v[68:69] op_sel_hi:[1,0,1]
	v_add_f32_e32 v44, 0, v92
	v_add_f32_e32 v46, v93, v44
	v_mul_f32_e32 v44, v93, v93
	v_pk_fma_f32 v[44:45], v[92:93], v[92:93], v[44:45] op_sel_hi:[1,1,0]
	v_add_f32_e32 v46, v94, v46
	v_pk_fma_f32 v[44:45], v[94:95], v[94:95], v[44:45]
	v_add_f32_e32 v47, v95, v46
	v_mul_f32_e32 v46, v95, v95
	s_waitcnt vmcnt(8)
; #define RL_LOAD(XV, G) { constexpr int mt__ = (G) >> 2, half__ = ((G) >> 1) & 1, nt__ = (G) & 1; \
;     _Pragma("unroll") for (int gq = 0; gq < 4; ++gq) XV[gq] = *(const f32x4*)(xin + rbase + (size_t)mt__ * 32 * 1024 + half__ * 64 + nt__ * 32 + 4 * gq); }
; #define RL_FOLD(XV, G, SM, SQ) { constexpr int mt__ = (G) >> 2, half__ = ((G) >> 1) & 1, nt__ = (G) & 1; \
;     _Pragma("unroll") for (int gq = 0; gq < 4; ++gq) _Pragma("unroll") for (int jj = 0; jj < 4; ++jj) { \
;       const float y = ALPHA * XV[gq][jj] + acc[half__][nt__][mt__][4 * gq + jj]; acc[half__][nt__][mt__][4 * gq + jj] = y; SM += y; SQ += y * y; } }
; #define SB __builtin_amdgcn_sched_barrier(0)
;   DI void full(const int mt_, const int nt_, f32x16 (&acc)[2][2][2], const int tw, const int fw, const int r, const int hh, char* lds, const int tid) const {
;     ...
;     RL_FOLD(xc, 1, sm0, sq0); SB; RL_LOAD(xc, 4); SB;
;     RL_FOLD(xe, 2, sm0, sq0); SB; RL_LOAD(xe, 5); SB;
;     RL_FOLD(xa, 3, sm0, sq0); SB; RL_LOAD(xa, 6); SB;
;     RL_FOLD(xc, 4, sm1, sq1); SB; RL_LOAD(xc, 7); SB;
;     RL_FOLD(xe, 5, sm1, sq1); SB;
;     RL_FOLD(xa, 6, sm1, sq1); SB;
;     RL_FOLD(xc, 7, sm1, sq1);
	v_pk_fma_f32 v[88:89], v[228:229], s[0:1], v[70:71] op_sel_hi:[1,0,1]
	v_pk_add_f32 v[44:45], v[46:47], v[44:45] op_sel_hi:[0,1]
	v_add_f32_e32 v46, v88, v47
	v_pk_fma_f32 v[44:45], v[88:89], v[88:89], v[44:45]
	v_add_f32_e32 v47, v89, v46
	v_mul_f32_e32 v46, v89, v89
	v_pk_fma_f32 v[90:91], v[230:231], s[0:1], v[72:73] op_sel_hi:[1,0,1]
	v_pk_add_f32 v[44:45], v[46:47], v[44:45] op_sel_hi:[0,1]
	v_add_f32_e32 v46, v90, v47
	v_pk_fma_f32 v[44:45], v[90:91], v[90:91], v[44:45]
	v_add_f32_e32 v47, v91, v46
	v_mul_f32_e32 v46, v91, v91
	v_pk_fma_f32 v[86:87], v[202:203], s[0:1], v[74:75] op_sel_hi:[1,0,1]
	v_pk_add_f32 v[44:45], v[46:47], v[44:45] op_sel_hi:[0,1]
	v_add_f32_e32 v46, v86, v47
	v_pk_fma_f32 v[44:45], v[86:87], v[86:87], v[44:45]
	v_add_f32_e32 v47, v87, v46
	v_mul_f32_e32 v46, v87, v87
	v_pk_fma_f32 v[76:77], v[204:205], s[0:1], v[76:77] op_sel_hi:[1,0,1]
	v_pk_add_f32 v[44:45], v[46:47], v[44:45] op_sel_hi:[0,1]
	v_add_f32_e32 v46, v76, v47
	v_pk_fma_f32 v[44:45], v[76:77], v[76:77], v[44:45]
	v_add_f32_e32 v47, v77, v46
	v_mul_f32_e32 v46, v77, v77
	v_pk_fma_f32 v[34:35], v[36:37], v[36:37], v[34:35]
	v_mul_f32_e32 v36, v103, v103
	v_pk_add_f32 v[44:45], v[46:47], v[44:45] op_sel_hi:[0,1]
	v_pk_fma_f32 v[74:75], v[98:99], s[0:1], v[78:79] op_sel_hi:[1,0,1]
	v_pk_fma_f32 v[72:73], v[100:101], s[0:1], v[80:81] op_sel_hi:[1,0,1]
	v_pk_add_f32 v[34:35], v[36:37], v[34:35] op_sel_hi:[0,1]
	v_pk_fma_f32 v[78:79], v[42:43], v[42:43], v[34:35]
	s_mov_b64 s[4:5], 0x20180
	v_lshl_add_u64 v[42:43], v[188:189], 0, s[4:5]
	global_load_dwordx4 v[34:37], v[42:43], off offset:48
	global_load_dwordx4 v[98:101], v[42:43], off offset:32
	s_nop 0
	global_load_dwordx4 v[188:191], v[190:191], off offset:384
	s_nop 0
	global_load_dwordx4 v[194:197], v[42:43], off offset:16
	v_add_f32_e32 v46, v74, v47
	v_pk_fma_f32 v[42:43], v[74:75], v[74:75], v[44:45]
	v_add_f32_e32 v45, v75, v46
	v_mul_f32_e32 v44, v75, v75
	v_pk_add_f32 v[42:43], v[44:45], v[42:43] op_sel_hi:[0,1]
	v_add_f32_e32 v44, v72, v45
	v_pk_fma_f32 v[42:43], v[72:73], v[72:73], v[42:43]
	v_add_f32_e32 v45, v73, v44
	v_mul_f32_e32 v44, v73, v73
	v_pk_add_f32 v[42:43], v[44:45], v[42:43] op_sel_hi:[0,1]
	s_waitcnt vmcnt(9)
	v_pk_fma_f32 v[66:67], v[236:237], s[0:1], v[50:51] op_sel_hi:[1,0,1]
	v_pk_fma_f32 v[70:71], v[238:239], s[0:1], v[52:53] op_sel_hi:[1,0,1]
	v_add_f32_e32 v44, v66, v45
	v_pk_fma_f32 v[42:43], v[66:67], v[66:67], v[42:43]
	v_add_f32_e32 v45, v67, v44
	v_mul_f32_e32 v44, v67, v67
	v_pk_add_f32 v[42:43], v[44:45], v[42:43] op_sel_hi:[0,1]
	v_add_f32_e32 v44, v70, v45
	v_pk_fma_f32 v[42:43], v[70:71], v[70:71], v[42:43]
	v_add_f32_e32 v45, v71, v44
	v_mul_f32_e32 v44, v71, v71
	s_waitcnt vmcnt(8)
	v_pk_fma_f32 v[54:55], v[240:241], s[0:1], v[54:55] op_sel_hi:[1,0,1]
	v_pk_add_f32 v[42:43], v[44:45], v[42:43] op_sel_hi:[0,1]
	v_add_f32_e32 v44, v54, v45
	v_pk_fma_f32 v[42:43], v[54:55], v[54:55], v[42:43]
	v_add_f32_e32 v45, v55, v44
	v_mul_f32_e32 v44, v55, v55
	v_pk_fma_f32 v[68:69], v[242:243], s[0:1], v[56:57] op_sel_hi:[1,0,1]
	v_pk_add_f32 v[42:43], v[44:45], v[42:43] op_sel_hi:[0,1]
	v_add_f32_e32 v44, v68, v45
	v_pk_fma_f32 v[42:43], v[68:69], v[68:69], v[42:43]
	v_add_f32_e32 v45, v69, v44
	v_mul_f32_e32 v44, v69, v69
	v_pk_fma_f32 v[50:51], v[232:233], s[0:1], v[58:59] op_sel_hi:[1,0,1]
	v_pk_add_f32 v[42:43], v[44:45], v[42:43] op_sel_hi:[0,1]
	v_add_f32_e32 v44, v50, v45
	v_pk_fma_f32 v[42:43], v[50:51], v[50:51], v[42:43]
	v_add_f32_e32 v45, v51, v44
	v_mul_f32_e32 v44, v51, v51
	v_pk_fma_f32 v[56:57], v[234:235], s[0:1], v[60:61] op_sel_hi:[1,0,1]
	v_pk_add_f32 v[42:43], v[44:45], v[42:43] op_sel_hi:[0,1]
	v_add_f32_e32 v44, v56, v45
	v_pk_fma_f32 v[42:43], v[56:57], v[56:57], v[42:43]
	v_add_f32_e32 v45, v57, v44
	v_mul_f32_e32 v44, v57, v57
	v_pk_fma_f32 v[48:49], v[82:83], s[0:1], v[62:63] op_sel_hi:[1,0,1]
	v_pk_add_f32 v[42:43], v[44:45], v[42:43] op_sel_hi:[0,1]
	v_add_f32_e32 v44, v48, v45
	v_pk_fma_f32 v[42:43], v[48:49], v[48:49], v[42:43]
	v_add_f32_e32 v45, v49, v44
	v_mul_f32_e32 v44, v49, v49
	v_pk_fma_f32 v[52:53], v[84:85], s[0:1], v[64:65] op_sel_hi:[1,0,1]
	v_pk_add_f32 v[42:43], v[44:45], v[42:43] op_sel_hi:[0,1]
	v_add_f32_e32 v44, v52, v45
	v_pk_fma_f32 v[42:43], v[52:53], v[52:53], v[42:43]
	v_add_f32_e32 v46, v53, v44
	v_mul_f32_e32 v44, v53, v53
	v_pk_add_f32 v[44:45], v[44:45], v[42:43] op_sel_hi:[0,1]
	s_waitcnt vmcnt(5)
	v_pk_fma_f32 v[42:43], v[38:39], s[0:1], v[18:19] op_sel_hi:[1,0,1]
	v_pk_fma_f32 v[26:27], v[244:245], s[0:1], v[26:27] op_sel_hi:[1,0,1]
	v_add_f32_e32 v38, v42, v46
	v_pk_fma_f32 v[18:19], v[42:43], v[42:43], v[44:45]
	v_add_f32_e32 v39, v43, v38
	v_mul_f32_e32 v38, v43, v43
	v_pk_fma_f32 v[46:47], v[40:41], s[0:1], v[20:21] op_sel_hi:[1,0,1]
	v_pk_add_f32 v[18:19], v[38:39], v[18:19] op_sel_hi:[0,1]
	v_add_f32_e32 v20, v46, v39
	v_pk_fma_f32 v[18:19], v[46:47], v[46:47], v[18:19]
	v_add_f32_e32 v21, v47, v20
	v_mul_f32_e32 v20, v47, v47
	s_waitcnt vmcnt(4)
; #define RL_FOLD(XV, G, SM, SQ) { constexpr int mt__ = (G) >> 2, half__ = ((G) >> 1) & 1, nt__ = (G) & 1; \
;     _Pragma("unroll") for (int gq = 0; gq < 4; ++gq) _Pragma("unroll") for (int jj = 0; jj < 4; ++jj) { \
;       const float y = ALPHA * XV[gq][jj] + acc[half__][nt__][mt__][4 * gq + jj]; acc[half__][nt__][mt__][4 * gq + jj] = y; SM += y; SQ += y * y; } }
;   DI void full(const int mt_, const int nt_, f32x16 (&acc)[2][2][2], const int tw, const int fw, const int r, const int hh, char* lds, const int tid) const {
;     ...
;     RL_FOLD(xc, 7, sm1, sq1);
;     ...
;     sm0 += __shfl_xor(sm0, 32, 64); sq0 += __shfl_xor(sq0, 32, 64); sm1 += __shfl_xor(sm1, 32, 64); sq1 += __shfl_xor(sq1, 32, 64);
;     if (hh == 0) {
;       float* pp = part + ((fw * 256) + tw * 64 + r) * 2; pp[0] = sm0; pp[1] = sq0;
;       pp[64] = sm1; pp[65] = sq1;
	v_pk_fma_f32 v[38:39], v[248:249], s[0:1], v[22:23] op_sel_hi:[1,0,1]
	v_pk_add_f32 v[18:19], v[20:21], v[18:19] op_sel_hi:[0,1]
	v_add_f32_e32 v20, v38, v21
	v_pk_fma_f32 v[18:19], v[38:39], v[38:39], v[18:19]
	v_add_f32_e32 v21, v39, v20
	v_mul_f32_e32 v20, v39, v39
	v_pk_fma_f32 v[44:45], v[250:251], s[0:1], v[24:25] op_sel_hi:[1,0,1]
	v_pk_add_f32 v[18:19], v[20:21], v[18:19] op_sel_hi:[0,1]
	v_add_f32_e32 v20, v44, v21
	v_pk_fma_f32 v[18:19], v[44:45], v[44:45], v[18:19]
	v_add_f32_e32 v21, v45, v20
	v_mul_f32_e32 v20, v45, v45
	v_pk_add_f32 v[18:19], v[20:21], v[18:19] op_sel_hi:[0,1]
	v_add_f32_e32 v20, v26, v21
	v_pk_fma_f32 v[18:19], v[26:27], v[26:27], v[18:19]
	v_add_f32_e32 v21, v27, v20
	v_mul_f32_e32 v20, v27, v27
	v_pk_fma_f32 v[40:41], v[246:247], s[0:1], v[28:29] op_sel_hi:[1,0,1]
	v_pk_add_f32 v[18:19], v[20:21], v[18:19] op_sel_hi:[0,1]
	v_add_f32_e32 v20, v40, v21
	v_pk_fma_f32 v[18:19], v[40:41], v[40:41], v[18:19]
	v_add_f32_e32 v21, v41, v20
	v_mul_f32_e32 v20, v41, v41
	v_pk_fma_f32 v[24:25], v[166:167], s[0:1], v[30:31] op_sel_hi:[1,0,1]
	v_pk_add_f32 v[18:19], v[20:21], v[18:19] op_sel_hi:[0,1]
	v_add_f32_e32 v20, v24, v21
	v_pk_fma_f32 v[18:19], v[24:25], v[24:25], v[18:19]
	v_add_f32_e32 v21, v25, v20
	v_mul_f32_e32 v20, v25, v25
	v_pk_fma_f32 v[28:29], v[168:169], s[0:1], v[32:33] op_sel_hi:[1,0,1]
	v_pk_add_f32 v[18:19], v[20:21], v[18:19] op_sel_hi:[0,1]
	v_add_f32_e32 v20, v28, v21
	v_pk_fma_f32 v[18:19], v[28:29], v[28:29], v[18:19]
	v_add_f32_e32 v22, v29, v20
	v_mul_f32_e32 v20, v29, v29
	v_pk_add_f32 v[20:21], v[20:21], v[18:19] op_sel_hi:[0,1]
	s_waitcnt vmcnt(1)
	v_pk_fma_f32 v[18:19], v[188:189], s[0:1], v[2:3] op_sel_hi:[1,0,1]
	s_waitcnt vmcnt(0)
	v_pk_fma_f32 v[6:7], v[194:195], s[0:1], v[6:7] op_sel_hi:[1,0,1]
	v_add_f32_e32 v22, v18, v22
	v_pk_fma_f32 v[2:3], v[18:19], v[18:19], v[20:21]
	v_add_f32_e32 v21, v19, v22
	v_pk_fma_f32 v[22:23], v[190:191], s[0:1], v[4:5] op_sel_hi:[1,0,1]
	v_mul_f32_e32 v20, v19, v19
	v_add_f32_e32 v4, v22, v21
	v_pk_add_f32 v[2:3], v[20:21], v[2:3] op_sel_hi:[0,1]
	v_add_f32_e32 v4, v23, v4
	v_pk_fma_f32 v[2:3], v[22:23], v[22:23], v[2:3]
	v_add_f32_e32 v21, v6, v4
	v_mul_f32_e32 v20, v23, v23
	v_mov_b32_e32 v4, v6
	v_mov_b32_e32 v5, v23
	v_pk_add_f32 v[2:3], v[20:21], v[2:3] op_sel_hi:[0,1]
	v_pk_fma_f32 v[2:3], v[4:5], v[4:5], v[2:3]
	v_add_f32_e32 v4, v7, v21
	v_pk_fma_f32 v[20:21], v[196:197], s[0:1], v[8:9] op_sel_hi:[1,0,1]
	v_mul_f32_e32 v8, v7, v7
	v_add_f32_e32 v9, v20, v4
	v_mov_b32_e32 v4, v20
	v_mov_b32_e32 v5, v7
	v_pk_add_f32 v[2:3], v[8:9], v[2:3] op_sel_hi:[0,1]
	v_pk_fma_f32 v[4:5], v[4:5], v[4:5], v[2:3]
	v_add_f32_e32 v8, v21, v9
	v_pk_fma_f32 v[2:3], v[98:99], s[0:1], v[10:11] op_sel_hi:[1,0,1]
	v_mul_f32_e32 v10, v21, v21
	v_add_f32_e32 v11, v2, v8
	v_mov_b32_e32 v8, v2
	v_mov_b32_e32 v9, v21
	v_pk_add_f32 v[4:5], v[10:11], v[4:5] op_sel_hi:[0,1]
	v_pk_fma_f32 v[4:5], v[8:9], v[8:9], v[4:5]
	v_add_f32_e32 v10, v3, v11
	v_pk_fma_f32 v[8:9], v[100:101], s[0:1], v[12:13] op_sel_hi:[1,0,1]
	v_mul_f32_e32 v12, v3, v3
	v_add_f32_e32 v13, v8, v10
	v_mov_b32_e32 v10, v8
	v_mov_b32_e32 v11, v3
	v_pk_add_f32 v[4:5], v[12:13], v[4:5] op_sel_hi:[0,1]
	v_pk_fma_f32 v[10:11], v[10:11], v[10:11], v[4:5]
	v_add_f32_e32 v12, v9, v13
	v_pk_fma_f32 v[4:5], v[34:35], s[0:1], v[14:15] op_sel_hi:[1,0,1]
	v_mul_f32_e32 v14, v9, v9
	v_add_f32_e32 v15, v4, v12
	v_mov_b32_e32 v12, v4
	v_mov_b32_e32 v13, v9
	v_pk_add_f32 v[10:11], v[14:15], v[10:11] op_sel_hi:[0,1]
	v_pk_fma_f32 v[12:13], v[12:13], v[12:13], v[10:11]
	v_pk_fma_f32 v[10:11], v[36:37], s[0:1], v[16:17] op_sel_hi:[1,0,1]
	v_mul_f32_e32 v30, v5, v5
	v_mov_b32_e32 v16, v10
	v_mov_b32_e32 v17, v5
	v_pk_add_f32 v[12:13], v[30:31], v[12:13] op_sel_hi:[0,1]
	v_pk_fma_f32 v[12:13], v[16:17], v[16:17], v[12:13]
	v_pk_mul_f32 v[16:17], v[10:11], v[10:11]
	v_add_f32_e32 v14, v5, v15
	v_mov_b32_e32 v15, v17
	v_and_b32_e32 v17, 64, v201
	v_xor_b32_e32 v16, 32, v201
	v_add_u32_e32 v17, 64, v17
	v_add_f32_e32 v14, v10, v14
	v_pk_mov_b32 v[12:13], v[10:11], v[12:13] op_sel:[1,0]
	v_cmp_lt_i32_e32 vcc, v16, v17
	v_pk_add_f32 v[12:13], v[12:13], v[14:15]
	v_pk_mov_b32 v[14:15], v[112:113], v[78:79] op_sel:[1,0]
	v_cndmask_b32_e32 v16, v201, v16, vcc
	v_pk_add_f32 v[14:15], v[14:15], v[114:115]
	v_lshlrev_b32_e32 v31, 2, v16
	ds_bpermute_b32 v16, v31, v14
	ds_bpermute_b32 v17, v31, v15
	ds_bpermute_b32 v30, v31, v12
	ds_bpermute_b32 v31, v31, v13
	v_cmp_eq_u32_e32 vcc, 0, v226
	s_and_saveexec_b64 s[4:5], vcc
	s_cbranch_execz .LBB0_772
	v_lshlrev_b32_e32 v32, 3, v186
	v_and_b32_e32 v32, 0xfffffef8, v32
	v_add_u32_e32 v32, 0, v32
	v_add_u32_e32 v32, 0x12000, v32
	s_waitcnt lgkmcnt(2)
	v_pk_add_f32 v[14:15], v[14:15], v[16:17]
	s_waitcnt lgkmcnt(0)
	v_pk_add_f32 v[12:13], v[12:13], v[30:31]
	ds_write2_b64 v32, v[14:15], v[12:13] offset1:32
